# speedup vs baseline: 1.1086x; 1.0063x over previous
; template <bool FINAL>
; __device__ void phase_lru(const Params& p, int l, unsigned char* smem) {
;   u16* xs = (u16*)smem;
;   float* u32 = (float*)(smem + 8704);
;   u16* ub = (u16*)(smem + 25088);
;   float* sa = (float*)(smem + 34304);
;   float* sb = (float*)(smem + 50688);
;   float* part = (float*)(smem + 67072);
;   const int tid = TIDX(), lane = tid & 63, w = tid >> 6, l15 = lane & 15, g = lane >> 4;
;   const int e_ = tid & 63, qd = tid >> 6;
;   const int NIT = NCHUNK * 8;
;   const int step = gridDim.x;
;   int it = BIDX();
;   uint4 x0 = make_uint4(0, 0, 0, 0), x1 = x0, x2 = x0;
;   auto load_x = [&](int item, uint4& a0, uint4& a1, uint4& a2) {
;     const int ci = item >> 3, nb = item & 7;
;     const int tb = ci * 64, pos0 = tok_pos(tb), S = tok_len(tb);
;     const u16* zb = p.Z + (long)(tb - 2) * DIN + C_LX + nb * 64;
;     { int idx = tid, r = idx >> 3, ch = idx & 7, pp = pos0 - 2 + r;
;       a0 = (pp >= 0 && pp < S) ? *(const uint4*)(zb + (long)r * DIN + ch * 8) : make_uint4(0, 0, 0, 0); }
;     { int idx = tid + 256, r = idx >> 3, ch = idx & 7, pp = pos0 - 2 + r;
;       a1 = (pp >= 0 && pp < S) ? *(const uint4*)(zb + (long)r * DIN + ch * 8) : make_uint4(0, 0, 0, 0); }
;     { int idx = tid + 512, r = idx >> 3, ch = idx & 7, pp = pos0 - 2 + r;
;       a2 = (idx < 67 * 8 && pp >= 0 && pp < S) ? *(const uint4*)(zb + (long)r * DIN + ch * 8) : make_uint4(0, 0, 0, 0); }
;   };
;   if (it < NIT) load_x(it, x0, x1, x2);
;   for (; it < NIT; it += step) {
;     const int ci = it >> 3, nb = it & 7;
;     const int tb = ci * 64;
;     __syncthreads();
;     *(uint4*)(xs + (tid >> 3) * 64 + (tid & 7) * 8) = x0;
;     *(uint4*)(xs + ((tid + 256) >> 3) * 64 + (tid & 7) * 8) = x1;
;     if (tid + 512 < 67 * 8) *(uint4*)(xs + ((tid + 512) >> 3) * 64 + (tid & 7) * 8) = x2;
;     uint4 gz0 = make_uint4(0, 0, 0, 0), gz1 = gz0;
;     float cin0 = 0.f, cin1 = 0.f;
;     if (FINAL) {
;       const u16* gb = p.Z + (size_t)tb * DIN + C_LG + nb * 64 + (tid & 7) * 8;
;       typedef unsigned u4v __attribute__((ext_vector_type(4)));
;       const u4v g0_ = __builtin_nontemporal_load((const u4v*)(gb + (size_t)(tid >> 3) * DIN));
;       const u4v g1_ = __builtin_nontemporal_load((const u4v*)(gb + (size_t)((tid >> 3) + 32) * DIN));
;       gz0 = make_uint4(g0_[0], g0_[1], g0_[2], g0_[3]);
;       gz1 = make_uint4(g1_[0], g1_[1], g1_[2], g1_[3]);
.LBB0_196:
	s_mov_b32 s4, s22
	s_andn2_b64 vcc, exec, s[30:31]
	v_writelane_b32 v248, s4, 38
	s_nop 1
	v_writelane_b32 v248, s5, 39
	s_cbranch_vccnz .LBB0_226
	v_and_b32_e32 v38, 63, v12
	v_ashrrev_i32_e32 v13, 6, v12
	v_lshlrev_b32_e32 v17, 1, v38
	v_and_b32_e32 v39, 15, v12
	v_add_u32_e32 v18, 0, v17
	v_lshlrev_b32_e32 v21, 4, v13
	v_bfe_u32 v16, v12, 4, 2
	v_add_u32_e32 v20, 0x100, v12
	v_add_u32_e32 v96, v18, v17
	v_or_b32_e32 v17, v21, v39
	v_ashrrev_i32_e32 v51, 3, v20
	v_add_u32_e32 v20, 0x200, v12
	v_mul_lo_u32 v22, v17, s28
	v_lshlrev_b32_e32 v50, 3, v16
	v_and_b32_e32 v23, 48, v12
	v_lshlrev_b32_e32 v97, 2, v16
	v_readlane_b32 s4, v248, 16
	v_lshlrev_b32_e32 v16, 2, v38
	v_lshlrev_b32_e32 v14, 3, v12
	v_ashrrev_i32_e32 v53, 3, v20
	v_add3_u32 v52, 0, v22, v23
	v_lshl_add_u32 v98, v12, 2, s4
	v_add_u32_e32 v99, s4, v16
	s_movk_i32 s4, 0x70
	v_and_b32_e32 v40, 56, v14
	v_add_u32_e32 v14, 32, v36
	v_mad_u64_u32 v[58:59], s[42:43], v17, s4, v[52:53]
	v_readlane_b32 s4, v248, 17
	v_mad_i64_i32 v[42:43], s[30:31], v36, s26, 0
	v_mad_i64_i32 v[44:45], s[30:31], v14, s26, 0
	v_mad_i64_i32 v[46:47], s[30:31], v51, s26, 0
	v_mad_i64_i32 v[48:49], s[30:31], v53, s26, 0
	v_add_u32_e32 v133, s4, v16
	v_readlane_b32 s4, v248, 18
	v_lshlrev_b32_e32 v15, 4, v12
	s_lshl_b32 s30, s22, 1
	v_add_u32_e32 v134, s4, v16
	v_readlane_b32 s4, v248, 19
	v_and_b32_e32 v15, 0xffffff80, v15
	v_lshlrev_b32_e32 v19, 1, v40
	s_or_b32 s56, s30, 1
	v_add_u32_e32 v135, s4, v16
	v_readlane_b32 s4, v248, 20
	v_add3_u32 v41, 0, v15, v19
	v_cmp_gt_i32_e64 s[38:39], 24, v12
	v_ashrrev_i32_e32 v15, 31, v14
	v_and_b32_e32 v12, 0x3fffffc0, v12
	s_ashr_i32 s31, s30, 31
	s_lshl_b32 s40, s22, 10
	s_lshl_b32 s66, s56, 9
	v_add_u32_e32 v136, s4, v16
	v_readlane_b32 s4, v250, 5
	s_lshl_b32 s58, s22, 11
	s_lshl_b32 s59, s22, 9
	v_lshl_add_u32 v100, v12, 2, v99
	v_mul_lo_u32 v12, v36, s28
	v_lshlrev_b64 v[56:57], 11, v[14:15]
	v_lshlrev_b32_e32 v102, 12, v13
	v_or_b32_e32 v14, 1, v21
	s_ashr_i32 s41, s40, 31
	s_ashr_i32 s57, s56, 31
	s_ashr_i32 s67, s66, 31
	s_lshl_b64 s[30:31], s[30:31], 17
	v_readlane_b32 s10, v250, 11
	v_ashrrev_i32_e32 v37, 31, v36
	v_add3_u32 v12, 0, v12, v19
	v_lshlrev_b32_e32 v103, 8, v14
	v_or_b32_e32 v19, 2, v21
	v_or_b32_e32 v17, v102, v16
	v_readlane_b32 s11, v250, 12
	v_readlane_b32 s16, v250, 17
	v_readlane_b32 s17, v250, 18
	v_readlane_b32 s18, v250, 19
	v_readlane_b32 s19, v250, 20
	s_add_u32 s42, s10, s30
	v_add_u32_e32 v101, 0x6200, v12
	v_lshlrev_b64 v[54:55], 11, v[36:37]
	v_add_u32_e32 v37, 0x7400, v12
	v_mul_lo_u32 v12, v13, s27
	v_mul_lo_u32 v15, v14, s28
	v_lshlrev_b32_e32 v104, 8, v19
	v_or_b32_e32 v22, 3, v21
	v_add_u32_e32 v59, 0, v17
	v_or_b32_e32 v17, v103, v16
	s_addc_u32 s43, s11, s31
	v_readlane_b32 s16, v250, 37
	v_lshlrev_b32_e32 v105, 8, v22
	v_or_b32_e32 v23, 4, v21
	v_add_u32_e32 v118, 0, v17
	v_or_b32_e32 v17, v104, v16
	s_lshl_b64 s[40:41], s[40:41], 2
	v_readlane_b32 s20, v250, 41
	v_readlane_b32 s24, v250, 45
	v_lshlrev_b32_e32 v106, 8, v23
	v_or_b32_e32 v24, 5, v21
	v_add_u32_e32 v119, 0, v17
	v_or_b32_e32 v17, v105, v16
	v_readlane_b32 s21, v250, 42
	v_readlane_b32 s25, v250, 46
	s_mov_b32 s20, s58
	s_add_u32 s58, s24, s40
	v_lshlrev_b32_e32 v107, 8, v24
	v_or_b32_e32 v25, 6, v21
	v_add_u32_e32 v120, 0, v17
	v_or_b32_e32 v17, v106, v16
	v_cmp_lt_i32_e64 s[60:61], 0, v13
	v_readlane_b32 s22, v250, 43
	v_readlane_b32 s23, v250, 44
	v_readlane_b32 s28, v250, 49
	s_mov_b32 s21, s59
	s_addc_u32 s59, s25, s41
	v_lshlrev_b32_e32 v108, 8, v25
	v_or_b32_e32 v26, 7, v21
	v_add_u32_e32 v121, 0, v17
	v_or_b32_e32 v17, v107, v16
	v_readlane_b32 s29, v250, 50
	s_mov_b64 s[22:23], s[60:61]
	s_add_u32 s60, s28, s40
	v_lshlrev_b32_e32 v109, 8, v26
	v_or_b32_e32 v27, 8, v21
	v_add_u32_e32 v122, 0, v17
	v_or_b32_e32 v17, v108, v16
	v_readlane_b32 s14, v250, 15
	s_addc_u32 s61, s29, s41
	v_lshlrev_b32_e32 v110, 8, v27
	v_or_b32_e32 v28, 9, v21
	v_add_u32_e32 v123, 0, v17
	v_or_b32_e32 v17, v109, v16
	v_readlane_b32 s15, v250, 16
	s_add_u32 s62, s14, s40
	v_lshlrev_b32_e32 v111, 8, v28
	v_or_b32_e32 v29, 10, v21
	v_add_u32_e32 v124, 0, v17
	v_or_b32_e32 v17, v110, v16
	s_addc_u32 s63, s15, s41
	s_lshl_b64 s[40:41], s[56:57], 17
	v_lshlrev_b32_e32 v112, 8, v29
	v_or_b32_e32 v30, 11, v21
	v_add_u32_e32 v125, 0, v17
	v_or_b32_e32 v17, v111, v16
	s_add_u32 s64, s10, s40
	v_lshlrev_b32_e32 v113, 8, v30
	v_or_b32_e32 v31, 12, v21
	v_add_u32_e32 v126, 0, v17
	v_or_b32_e32 v17, v112, v16
	s_addc_u32 s65, s11, s41
	s_lshl_b64 s[40:41], s[66:67], 2
	v_lshlrev_b32_e32 v114, 8, v31
; template <bool FINAL>
; __device__ void phase_lru(const Params& p, int l, unsigned char* smem) {
;     ...
;     float hsum[16];
; #pragma unroll
;     for (int tt = 0; tt < 16; ++tt) hsum[tt] = 0.f;
; #pragma unroll
;     for (int d = 0; d < 2; ++d) {
;       {
;         bf16x8 uf[2];
;         uf[0] = *(const bf16x8*)(ub + (16 * w + l15) * 72 + g * 8);
;         uf[1] = *(const bf16x8*)(ub + (16 * w + l15) * 72 + 32 + g * 8);
;         const int t = 16 * w + l15;
; #pragma unroll
;         for (int et = 0; et < 4; ++et) {
;           f32x4 ar = {0.f, 0.f, 0.f, 0.f}, ai = {0.f, 0.f, 0.f, 0.f};
;           const u16* wr = p.WLRU + ((((size_t)(l * 2 + d) * 2 + 0) * 8 + nb) * 64 + et * 16 + l15) * 64 + g * 8;
;           const u16* wi = p.WLRU + ((((size_t)(l * 2 + d) * 2 + 1) * 8 + nb) * 64 + et * 16 + l15) * 64 + g * 8;
; #pragma unroll
;           for (int ks = 0; ks < 2; ++ks) {
;             ar = mfma16(*(const bf16x8*)(wr + ks * 32), uf[ks], ar);
;             ai = mfma16(*(const bf16x8*)(wi + ks * 32), uf[ks], ai);
;           }
;           const int e0 = et * 16 + 4 * g, ch0 = nb * 64 + e0;
;           const float4 ba4 = *(const float4*)(p.ba + (l * 2 + d) * 512 + ch0);
;           const float4 bx4 = *(const float4*)(p.bx + (l * 2 + d) * 512 + ch0);
;           const float4 sp4 = *(const float4*)(p.SP8 + (l * 2 + d) * 512 + ch0);
	v_or_b32_e32 v32, 13, v21
	v_add_u32_e32 v127, 0, v17
	v_or_b32_e32 v17, v113, v16
	s_add_u32 s66, s24, s40
	v_lshlrev_b32_e32 v115, 8, v32
	v_or_b32_e32 v33, 14, v21
	v_add_u32_e32 v128, 0, v17
	v_or_b32_e32 v17, v114, v16
	v_cmp_lt_i32_e64 s[68:69], 1, v13
	s_addc_u32 s67, s25, s41
	v_lshlrev_b32_e32 v116, 8, v33
	v_or_b32_e32 v21, 15, v21
	v_add_u32_e32 v129, 0, v17
	v_or_b32_e32 v17, v115, v16
	s_mov_b64 s[24:25], s[68:69]
	s_add_u32 s68, s28, s40
	v_lshlrev_b32_e32 v117, 8, v21
	v_add_u32_e32 v130, 0, v17
	v_or_b32_e32 v17, v116, v16
	v_readlane_b32 s5, v250, 6
	s_addc_u32 s69, s29, s41
	v_add_u32_e32 v131, 0, v17
	v_or_b32_e32 v17, v117, v16
	s_add_u32 s72, s14, s40
	v_readlane_b32 s4, v250, 1
	v_lshlrev_b32_e32 v20, 11, v13
	v_add_u32_e32 v132, 0, v17
	v_cmp_lt_i32_e64 s[44:45], 2, v13
	v_cmp_lt_i32_e64 s[46:47], 3, v13
	v_cmp_gt_i32_e64 s[48:49], 3, v13
	v_cmp_gt_i32_e64 s[50:51], 2, v13
	v_cmp_gt_i32_e64 s[52:53], 1, v13
	v_cmp_gt_i32_e64 s[54:55], 0, v13
	v_lshlrev_b32_e32 v13, 7, v14
	v_lshlrev_b32_e32 v14, 7, v19
	v_lshlrev_b32_e32 v16, 7, v22
	v_lshlrev_b32_e32 v17, 7, v23
	v_lshlrev_b32_e32 v19, 7, v24
	v_lshlrev_b32_e32 v22, 7, v25
	v_lshlrev_b32_e32 v23, 7, v26
	v_lshlrev_b32_e32 v24, 7, v27
	v_lshlrev_b32_e32 v25, 7, v28
	v_lshlrev_b32_e32 v26, 7, v29
	v_lshlrev_b32_e32 v27, 7, v30
	v_lshlrev_b32_e32 v28, 7, v31
	v_lshlrev_b32_e32 v29, 7, v32
	v_lshlrev_b32_e32 v30, 7, v33
	v_lshlrev_b32_e32 v21, 7, v21
	s_addc_u32 s73, s15, s41
	s_add_i32 s40, s4, s36
	s_lshl_b32 s99, s40, 3
	s_lshl_b32 s97, s36, 6
	v_lshlrev_b32_e32 v137, 2, v38
	v_add_u32_e32 v138, v18, v13
	v_add_u32_e32 v139, v18, v14
	v_add_u32_e32 v140, v18, v16
	v_add_u32_e32 v141, v18, v17
	v_add_u32_e32 v142, v18, v19
	v_add_u32_e32 v143, v18, v22
	v_add_u32_e32 v149, v18, v23
	v_add_u32_e32 v150, v18, v24
	v_add_u32_e32 v151, v18, v25
	v_add_u32_e32 v152, v18, v26
	v_add_u32_e32 v153, v18, v27
	v_add_u32_e32 v154, v18, v28
	v_add_u32_e32 v155, v18, v29
	v_add_u32_e32 v156, v18, v30
	v_add_u32_e32 v157, v18, v21
	v_add_u32_e32 v158, v18, v20
	v_add_u32_e32 v159, v18, v12
	v_add_u32_e32 v160, v18, v15
	v_readlane_b32 s6, v250, 7
	v_readlane_b32 s7, v250, 8
	v_readlane_b32 s8, v250, 9
	v_readlane_b32 s9, v250, 10
	v_readlane_b32 s12, v250, 13
	v_readlane_b32 s13, v250, 14
	v_readlane_b32 s17, v250, 38
	v_readlane_b32 s18, v250, 39
	v_readlane_b32 s19, v250, 40
	v_readlane_b32 s26, v250, 47
	v_readlane_b32 s27, v250, 48
	v_readlane_b32 s30, v250, 51
	v_readlane_b32 s31, v250, 52
	v_readlane_b32 s5, v250, 2
	s_lshl_b32 s32, s36, 6
	s_and_b32 s32, s32, 0x1c0
	v_lshrrev_b32_e32 v12, 6, v147
	v_and_b32_e32 v22, 15, v147
	v_lshlrev_b32_e32 v13, 4, v12
	v_or_b32_e32 v13, v13, v22
	v_or_b32_e32 v13, s32, v13
	v_lshlrev_b32_e32 v14, 7, v13
	v_mov_b32_e32 v15, v145
	v_bfe_u32 v16, v147, 4, 2
	v_lshlrev_b32_e32 v17, 4, v16
	v_add_u32_e32 v14, v14, v17
	v_lshl_add_u64 v[18:19], s[42:43], 0, v[14:15]
	global_load_dwordx4 v[180:183], v[18:19], off
	global_load_dwordx4 v[184:187], v[18:19], off offset:64
	v_add_co_u32_e32 v20, vcc, 0x10000, v18
	s_nop 0
	v_addc_co_u32_e32 v21, vcc, 0, v19, vcc
	global_load_dwordx4 v[188:191], v[20:21], off
	global_load_dwordx4 v[192:195], v[20:21], off offset:64
	v_lshl_add_u64 v[18:19], s[64:65], 0, v[14:15]
	global_load_dwordx4 v[232:235], v[18:19], off
	global_load_dwordx4 v[236:239], v[18:19], off offset:64
	v_add_co_u32_e32 v20, vcc, 0x10000, v18
	s_nop 0
	v_addc_co_u32_e32 v21, vcc, 0, v19, vcc
	global_load_dwordx4 v[240:243], v[20:21], off
	global_load_dwordx4 v[244:247], v[20:21], off offset:64
	v_mul_u32_u24_e32 v229, 0x90, v22
	v_add_u32_e32 v229, v229, v17
	v_lshlrev_b32_e32 v230, 8, v22
	v_add_u32_e32 v230, v230, v17
	v_lshl_add_u32 v230, v12, 6, v230
	v_lshlrev_b32_e32 v231, 4, v12
	v_lshl_add_u32 v231, v16, 2, v231
	v_or_b32_e32 v231, s32, v231
	v_lshlrev_b32_e32 v231, 2, v231
	v_mov_b32_e32 v205, 0x3c088889
	v_lshl_add_u32 v204, v12, 2, v16
	v_xor_b32_e32 v204, v204, v22
	v_lshlrev_b32_e32 v204, 4, v204
	v_lshl_add_u32 v204, v22, 8, v204
	v_xor_b32_e32 v118, 0x10, v118
	v_xor_b32_e32 v119, 0x20, v119
	v_xor_b32_e32 v120, 0x30, v120
	v_xor_b32_e32 v121, 0x40, v121
	v_xor_b32_e32 v122, 0x50, v122
	v_xor_b32_e32 v123, 0x60, v123
	v_xor_b32_e32 v124, 0x70, v124
	v_xor_b32_e32 v125, 0x80, v125
	v_xor_b32_e32 v126, 0x90, v126
	v_xor_b32_e32 v127, 0xa0, v127
	v_xor_b32_e32 v128, 0xb0, v128
	v_xor_b32_e32 v129, 0xc0, v129
	v_xor_b32_e32 v130, 0xd0, v130
	v_xor_b32_e32 v131, 0xe0, v131
	v_xor_b32_e32 v132, 0xf0, v132
	s_branch .LBB0_199

; __device__ __forceinline__ float bf2f(unsigned h) { return __uint_as_float(h << 16); }
; template <bool FINAL>
; __device__ void phase_lru(const Params& p, int l, unsigned char* smem) {
;     ...
;     {
;       const int ch = nb * 64 + e_;
;       const float cw0 = p.conv_w[(l * 4 + 0) * 512 + ch], cw1 = p.conv_w[(l * 4 + 1) * 512 + ch],
;                   cw2 = p.conv_w[(l * 4 + 2) * 512 + ch], cw3 = p.conv_w[(l * 4 + 3) * 512 + ch];
;       const float cb = p.conv_b[l * 512 + ch];
;       float xv[19];
; #pragma unroll
;       for (int k = 0; k < 19; ++k) xv[k] = bf2f(xs[(qd * 16 + k) * 64 + e_]);
; #pragma unroll
;       for (int tt = 0; tt < 16; ++tt) {
;         const int t = qd * 16 + tt;
;         const float u = cb + xv[tt] * cw0 + xv[tt + 1] * cw1 + xv[tt + 2] * cw2 + xv[tt + 3] * cw3;
;         u32[t * 64 + e_] = u;
;         ub[t * 72 + e_] = (u16)f2bf(u);
;       }
;     }
.LBB0_209:
	v_or_b32_e32 v26, s40, v38
	v_or_b32_e32 v20, s20, v26
	v_readlane_b32 s4, v250, 37
	v_ashrrev_i32_e32 v21, 31, v20
	v_readlane_b32 s6, v250, 39
	v_readlane_b32 s7, v250, 40
	v_readlane_b32 s8, v250, 41
	v_readlane_b32 s9, v250, 42
	v_lshl_add_u64 v[22:23], v[20:21], 2, s[6:7]
	v_add_co_u32_e32 v24, vcc, 0x1000, v22
	global_load_dword v21, v[22:23], off
	global_load_dword v20, v[22:23], off offset:2048
	v_addc_co_u32_e32 v25, vcc, 0, v23, vcc
	global_load_dword v23, v[24:25], off
	global_load_dword v22, v[24:25], off offset:2048
	v_or_b32_e32 v24, s21, v26
	v_ashrrev_i32_e32 v25, 31, v24
	v_lshl_add_u64 v[24:25], v[24:25], 2, s[8:9]
	global_load_dword v24, v[24:25], off
	ds_read_u16 v25, v158
	ds_read_u16 v26, v158 offset:128
	ds_read_u16 v27, v158 offset:256
	ds_read_u16 v28, v158 offset:384
	ds_read_u16 v29, v158 offset:512
	s_waitcnt lgkmcnt(4)
	v_lshlrev_b32_e32 v25, 16, v25
	s_waitcnt lgkmcnt(3)
	v_lshlrev_b32_e32 v26, 16, v26
	s_waitcnt lgkmcnt(2)
	v_lshlrev_b32_e32 v27, 16, v27
	s_waitcnt lgkmcnt(1)
	v_lshlrev_b32_e32 v28, 16, v28
	v_add_u32_e32 v69, v96, v102
	ds_read_u16 v30, v158 offset:640
	ds_read_u16 v31, v158 offset:768
	ds_read_u16 v32, v158 offset:896
	ds_read_u16 v33, v158 offset:1024
	ds_read_u16 v34, v158 offset:1152
	ds_read_u16 v35, v158 offset:1280
	ds_read_u16 v61, v158 offset:1408
	ds_read_u16 v62, v158 offset:1536
	ds_read_u16 v63, v158 offset:1664
	ds_read_u16 v64, v158 offset:1792
	ds_read_u16 v65, v158 offset:1920
	ds_read_u16 v66, v158 offset:2048
	ds_read_u16 v67, v158 offset:2176
	ds_read_u16 v68, v158 offset:2304
	s_waitcnt lgkmcnt(14)
	v_lshlrev_b32_e32 v29, 16, v29
	s_waitcnt lgkmcnt(13)
	v_lshlrev_b32_e32 v30, 16, v30
	s_waitcnt lgkmcnt(12)
	v_lshlrev_b32_e32 v31, 16, v31
	s_waitcnt lgkmcnt(11)
	v_lshlrev_b32_e32 v32, 16, v32
	s_waitcnt lgkmcnt(10)
	v_lshlrev_b32_e32 v33, 16, v33
	s_waitcnt lgkmcnt(9)
	v_lshlrev_b32_e32 v34, 16, v34
	s_waitcnt lgkmcnt(8)
	v_lshlrev_b32_e32 v35, 16, v35
	s_waitcnt lgkmcnt(7)
	v_lshlrev_b32_e32 v61, 16, v61
	s_waitcnt lgkmcnt(6)
	v_lshlrev_b32_e32 v62, 16, v62
	s_waitcnt lgkmcnt(5)
	v_lshlrev_b32_e32 v63, 16, v63
	s_waitcnt lgkmcnt(4)
	v_lshlrev_b32_e32 v64, 16, v64
	s_waitcnt lgkmcnt(3)
	v_lshlrev_b32_e32 v65, 16, v65
	s_waitcnt lgkmcnt(2)
	v_lshlrev_b32_e32 v66, 16, v66
	s_waitcnt lgkmcnt(1)
	v_lshlrev_b32_e32 v67, 16, v67
	s_waitcnt lgkmcnt(0)
	v_lshlrev_b32_e32 v68, 16, v68
	v_readlane_b32 s5, v250, 38
	s_mov_b64 s[4:5], 0x10000
	s_mov_b32 s6, 0xbe800000
	s_mov_b64 s[8:9], 0x10800
	s_ashr_i32 s93, s92, 31
	v_readlane_b32 s10, v250, 43
	v_readlane_b32 s11, v250, 44
	v_readlane_b32 s12, v250, 45
	v_readlane_b32 s13, v250, 46
	v_readlane_b32 s14, v250, 47
	v_readlane_b32 s15, v250, 48
	v_readlane_b32 s16, v250, 49
	v_readlane_b32 s17, v250, 50
	v_readlane_b32 s18, v250, 51
	v_readlane_b32 s19, v250, 52
	s_waitcnt vmcnt(0)
	v_fma_f32 v25, v21, v25, v24
	v_fmac_f32_e32 v25, v20, v26
	v_fmac_f32_e32 v25, v23, v27
	v_fmac_f32_e32 v25, v22, v28
	ds_write_b32 v69, v25 offset:8704
	v_cvt_pk_bf16_f32 v25, v25, s0
	ds_write_b16 v159, v25 offset:25088
	v_fma_f32 v25, v21, v26, v24
	v_fmac_f32_e32 v25, v20, v27
	v_fmac_f32_e32 v25, v23, v28
	v_fmac_f32_e32 v25, v22, v29
	v_add_u32_e32 v26, v96, v103
	ds_write_b32 v26, v25 offset:8704
	v_cvt_pk_bf16_f32 v25, v25, s0
	ds_write_b16 v160, v25 offset:25088
	v_fma_f32 v25, v21, v27, v24
	v_fmac_f32_e32 v25, v20, v28
	v_fmac_f32_e32 v25, v23, v29
	v_fmac_f32_e32 v25, v22, v30
	v_add_u32_e32 v26, v96, v104
	ds_write_b32 v26, v25 offset:8704
	v_cvt_pk_bf16_f32 v25, v25, s0
	ds_write_b16 v160, v25 offset:25232
	v_fma_f32 v25, v21, v28, v24
	v_fmac_f32_e32 v25, v20, v29
	v_fmac_f32_e32 v25, v23, v30
	v_fmac_f32_e32 v25, v22, v31
	v_add_u32_e32 v26, v96, v105
	ds_write_b32 v26, v25 offset:8704
	v_cvt_pk_bf16_f32 v25, v25, s0
	ds_write_b16 v160, v25 offset:25376
	v_fma_f32 v25, v21, v29, v24
	v_fmac_f32_e32 v25, v20, v30
	v_fmac_f32_e32 v25, v23, v31
	v_fmac_f32_e32 v25, v22, v32
	v_add_u32_e32 v26, v96, v106
	ds_write_b32 v26, v25 offset:8704
	v_cvt_pk_bf16_f32 v25, v25, s0
	ds_write_b16 v160, v25 offset:25520
	v_fma_f32 v25, v21, v30, v24
	v_fmac_f32_e32 v25, v20, v31
	v_fmac_f32_e32 v25, v23, v32
	v_fmac_f32_e32 v25, v22, v33
	v_add_u32_e32 v26, v96, v107
	ds_write_b32 v26, v25 offset:8704
	v_cvt_pk_bf16_f32 v25, v25, s0
	ds_write_b16 v160, v25 offset:25664
	v_fma_f32 v25, v21, v31, v24
	v_fmac_f32_e32 v25, v20, v32
	v_fmac_f32_e32 v25, v23, v33
	v_fmac_f32_e32 v25, v22, v34
	v_add_u32_e32 v26, v96, v108
	ds_write_b32 v26, v25 offset:8704
	v_cvt_pk_bf16_f32 v25, v25, s0
	ds_write_b16 v160, v25 offset:25808
	v_fma_f32 v25, v21, v32, v24
	v_fmac_f32_e32 v25, v20, v33
	v_fmac_f32_e32 v25, v23, v34
	v_fmac_f32_e32 v25, v22, v35
	v_add_u32_e32 v26, v96, v109
	ds_write_b32 v26, v25 offset:8704
	v_cvt_pk_bf16_f32 v25, v25, s0
	ds_write_b16 v160, v25 offset:25952
	v_fma_f32 v25, v21, v33, v24
	v_fmac_f32_e32 v25, v20, v34
	v_fmac_f32_e32 v25, v23, v35
	v_fmac_f32_e32 v25, v22, v61
	v_add_u32_e32 v26, v96, v110
	ds_write_b32 v26, v25 offset:8704
	v_cvt_pk_bf16_f32 v25, v25, s0
	ds_write_b16 v160, v25 offset:26096
	v_fma_f32 v25, v21, v34, v24
	v_fmac_f32_e32 v25, v20, v35
	v_fmac_f32_e32 v25, v23, v61
	v_fmac_f32_e32 v25, v22, v62
	v_add_u32_e32 v26, v96, v111
	ds_write_b32 v26, v25 offset:8704
	v_cvt_pk_bf16_f32 v25, v25, s0
	ds_write_b16 v160, v25 offset:26240
	v_fma_f32 v25, v21, v35, v24
	v_fmac_f32_e32 v25, v20, v61
	v_fmac_f32_e32 v25, v23, v62
	v_fmac_f32_e32 v25, v22, v63
	v_add_u32_e32 v26, v96, v112
	ds_write_b32 v26, v25 offset:8704
	v_cvt_pk_bf16_f32 v25, v25, s0
	ds_write_b16 v160, v25 offset:26384
	v_fma_f32 v25, v21, v61, v24
; template <bool FINAL>
; __device__ void phase_lru(const Params& p, int l, unsigned char* smem) {
;     ...
;       for (int tt = 0; tt < 16; ++tt) {
;         const int t = qd * 16 + tt;
;         const float u = cb + xv[tt] * cw0 + xv[tt + 1] * cw1 + xv[tt + 2] * cw2 + xv[tt + 3] * cw3;
;         u32[t * 64 + e_] = u;
;         ub[t * 72 + e_] = (u16)f2bf(u);
;       }
;     }
;     __syncthreads();
;     if (FINAL) {
;       *(uint4*)(xs + (tid >> 3) * 64 + (tid & 7) * 8) = gz0;
;       *(uint4*)(xs + ((tid >> 3) + 32) * 64 + (tid & 7) * 8) = gz1;
;     }
;     float hsum[16];
; #pragma unroll
;     for (int tt = 0; tt < 16; ++tt) hsum[tt] = 0.f;
; #pragma unroll
;     for (int d = 0; d < 2; ++d) {
;       {
;         bf16x8 uf[2];
;         uf[0] = *(const bf16x8*)(ub + (16 * w + l15) * 72 + g * 8);
;         uf[1] = *(const bf16x8*)(ub + (16 * w + l15) * 72 + 32 + g * 8);
;         const int t = 16 * w + l15;
; #pragma unroll
;         for (int et = 0; et < 4; ++et) {
;           f32x4 ar = {0.f, 0.f, 0.f, 0.f}, ai = {0.f, 0.f, 0.f, 0.f};
;           const u16* wr = p.WLRU + ((((size_t)(l * 2 + d) * 2 + 0) * 8 + nb) * 64 + et * 16 + l15) * 64 + g * 8;
;           const u16* wi = p.WLRU + ((((size_t)(l * 2 + d) * 2 + 1) * 8 + nb) * 64 + et * 16 + l15) * 64 + g * 8;
; #pragma unroll
;           for (int ks = 0; ks < 2; ++ks) {
;             ar = mfma16(*(const bf16x8*)(wr + ks * 32), uf[ks], ar);
;             ai = mfma16(*(const bf16x8*)(wi + ks * 32), uf[ks], ai);
;           }
;           const int e0 = et * 16 + 4 * g, ch0 = nb * 64 + e0;
;           const float4 ba4 = *(const float4*)(p.ba + (l * 2 + d) * 512 + ch0);
;           const float4 bx4 = *(const float4*)(p.bx + (l * 2 + d) * 512 + ch0);
;           const float4 sp4 = *(const float4*)(p.SP8 + (l * 2 + d) * 512 + ch0);
;           const float4 uu = *(const float4*)(u32 + t * 64 + e0);
;           const float* bap = (const float*)&ba4; const float* bxp = (const float*)&bx4;
;           const float* spp = (const float*)&sp4; const float* uup = (const float*)&uu;
;           f32x4 av, bv;
; #pragma unroll
;           for (int j = 0; j < 4; ++j) {
;             float r = sigmoidf_(ar[j] + bap[j]);
;             float ig = sigmoidf_(ai[j] + bxp[j]);
;             float la = spp[j] * r;
;             float av_ = __expf(la);
;             float t2 = 2.0f * la;
	v_fmac_f32_e32 v25, v20, v62
	v_fmac_f32_e32 v25, v23, v63
	v_fmac_f32_e32 v25, v22, v64
	v_add_u32_e32 v26, v96, v113
	ds_write_b32 v26, v25 offset:8704
	v_cvt_pk_bf16_f32 v25, v25, s0
	ds_write_b16 v160, v25 offset:26528
	v_fma_f32 v25, v21, v62, v24
	v_fmac_f32_e32 v25, v20, v63
	v_fmac_f32_e32 v25, v23, v64
	v_fmac_f32_e32 v25, v22, v65
	v_add_u32_e32 v26, v96, v114
	ds_write_b32 v26, v25 offset:8704
	v_cvt_pk_bf16_f32 v25, v25, s0
	ds_write_b16 v160, v25 offset:26672
	v_fma_f32 v25, v21, v63, v24
	v_fmac_f32_e32 v25, v20, v64
	v_fmac_f32_e32 v25, v23, v65
	v_fmac_f32_e32 v25, v22, v66
	v_add_u32_e32 v26, v96, v115
	ds_write_b32 v26, v25 offset:8704
	v_cvt_pk_bf16_f32 v25, v25, s0
	ds_write_b16 v160, v25 offset:26816
	v_fma_f32 v25, v21, v64, v24
	v_fmac_f32_e32 v24, v21, v65
	v_fmac_f32_e32 v24, v20, v66
	v_fmac_f32_e32 v24, v23, v67
	v_fmac_f32_e32 v25, v20, v65
	v_fmac_f32_e32 v24, v22, v68
	v_add_u32_e32 v20, v96, v117
	ds_write_b32 v20, v24 offset:8704
	v_cvt_pk_bf16_f32 v20, v24, s0
	v_fmac_f32_e32 v25, v23, v66
	ds_write_b16 v160, v20 offset:27104
	v_or_b32_e32 v20, s40, v39
	v_fmac_f32_e32 v25, v22, v67
	v_add_u32_e32 v26, v96, v116
	v_lshlrev_b32_e32 v144, 7, v20
	ds_write_b32 v26, v25 offset:8704
	v_cvt_pk_bf16_f32 v25, v25, s0
	v_lshl_add_u64 v[20:21], s[42:43], 0, v[144:145]
	v_lshlrev_b32_e32 v62, 1, v50
	v_mov_b32_e32 v63, v145
	ds_write_b16 v160, v25 offset:26960
	s_waitcnt lgkmcnt(0)
	s_barrier
	ds_write_b128 v41, v[12:15]
	ds_write_b128 v41, v[16:19] offset:4096
	s_mov_b32 s5, 0x3e4ccccd
	global_load_dwordx4 v[196:199], v231, s[58:59]
	global_load_dwordx4 v[200:203], v231, s[60:61]
	global_load_dwordx4 v[32:35], v231, s[62:63]
	ds_read_b128 v[12:15], v229 offset:25088
	ds_read_b128 v[16:19], v229 offset:25152
	ds_read_b128 v[28:31], v230 offset:8704
	s_waitcnt lgkmcnt(1)
	v_mfma_f32_16x16x32_bf16 v[20:23], v[180:183], v[12:15], 0
	v_mfma_f32_16x16x32_bf16 v[24:27], v[188:191], v[12:15], 0
	v_mfma_f32_16x16x32_bf16 v[20:23], v[184:187], v[16:19], v[20:23]
	v_mfma_f32_16x16x32_bf16 v[24:27], v[192:195], v[16:19], v[24:27]
	s_waitcnt vmcnt(0)
	v_mul_f32_e32 v196, 0xbfb8aa3b, v196
	v_mul_f32_e32 v197, 0xbfb8aa3b, v197
	v_mul_f32_e32 v198, 0xbfb8aa3b, v198
	v_mul_f32_e32 v199, 0xbfb8aa3b, v199
	v_mul_f32_e32 v200, 0xbfb8aa3b, v200
	v_mul_f32_e32 v201, 0xbfb8aa3b, v201
	v_mul_f32_e32 v202, 0xbfb8aa3b, v202
	v_mul_f32_e32 v203, 0xbfb8aa3b, v203
	s_nop 7
	s_nop 3
	s_waitcnt lgkmcnt(0)
	v_fmamk_f32 v20, v20, 0xbfb8aa3b, v196
	v_fmamk_f32 v21, v21, 0xbfb8aa3b, v197
	v_fmamk_f32 v24, v24, 0xbfb8aa3b, v200
	v_fmamk_f32 v25, v25, 0xbfb8aa3b, v201
	v_exp_f32_e32 v20, v20
	v_exp_f32_e32 v21, v21
	v_exp_f32_e32 v24, v24
	v_exp_f32_e32 v25, v25
	v_add_f32_e32 v20, 1.0, v20
	v_add_f32_e32 v21, 1.0, v21
	v_add_f32_e32 v24, 1.0, v24
	v_add_f32_e32 v25, 1.0, v25
	v_rcp_f32_e32 v20, v20
	v_rcp_f32_e32 v21, v21
	v_rcp_f32_e32 v24, v24
	v_rcp_f32_e32 v25, v25
	v_pk_mul_f32 v[12:13], v[20:21], v[32:33]
	s_nop 0
	v_pk_add_f32 v[14:15], v[12:13], v[12:13]
	v_mul_f32_e32 v20, 0x3fb8aa3b, v12
	v_mul_f32_e32 v21, 0x3fb8aa3b, v13
	v_exp_f32_e32 v20, v20
	v_exp_f32_e32 v21, v21
	v_fmaak_f32 v16, v14, v205, 0x3d2aaaab
	v_fmaak_f32 v19, v15, v205, 0x3d2aaaab
	v_fmaak_f32 v16, v16, v14, 0x3e2aaaab
	v_fmaak_f32 v19, v19, v15, 0x3e2aaaab
	v_fma_f32 v16, v16, v14, 0.5
	v_fma_f32 v19, v19, v15, 0.5
	v_fma_f32 v16, v16, v14, 1.0
	v_fma_f32 v19, v19, v15, 1.0
	v_mul_f32_e64 v17, v16, -v14
	v_mul_f32_e64 v12, v19, -v15
	v_fma_f32 v16, -v20, v20, 1.0
	v_cmp_lt_f32_e32 vcc, s6, v14
	v_fma_f32 v13, -v21, v21, 1.0
	s_nop 0
	v_cndmask_b32_e32 v16, v16, v17, vcc
	v_cmp_lt_f32_e32 vcc, s6, v15
	v_sqrt_f32_e32 v16, v16
	s_nop 1
	v_cndmask_b32_e32 v17, v13, v12, vcc
	v_sqrt_f32_e32 v17, v17
	s_nop 0
	v_pk_mul_f32 v[24:25], v[24:25], v[16:17]
	s_nop 0
	v_pk_mul_f32 v[24:25], v[28:29], v[24:25]
	v_fmamk_f32 v22, v22, 0xbfb8aa3b, v198
	v_fmamk_f32 v23, v23, 0xbfb8aa3b, v199
	v_fmamk_f32 v26, v26, 0xbfb8aa3b, v202
	v_fmamk_f32 v27, v27, 0xbfb8aa3b, v203
	v_exp_f32_e32 v22, v22
	v_exp_f32_e32 v23, v23
	v_exp_f32_e32 v26, v26
	v_exp_f32_e32 v27, v27
	v_add_f32_e32 v22, 1.0, v22
	v_add_f32_e32 v23, 1.0, v23
	v_add_f32_e32 v26, 1.0, v26
	v_add_f32_e32 v27, 1.0, v27
	v_rcp_f32_e32 v22, v22
	v_rcp_f32_e32 v23, v23
	v_rcp_f32_e32 v26, v26
	v_rcp_f32_e32 v27, v27
	v_pk_mul_f32 v[12:13], v[22:23], v[34:35]
	s_nop 0
	v_pk_add_f32 v[14:15], v[12:13], v[12:13]
	v_mul_f32_e32 v22, 0x3fb8aa3b, v12
	v_mul_f32_e32 v23, 0x3fb8aa3b, v13
	v_exp_f32_e32 v22, v22
	v_exp_f32_e32 v23, v23
	v_fmaak_f32 v16, v14, v205, 0x3d2aaaab
	v_fmaak_f32 v19, v15, v205, 0x3d2aaaab
	v_fmaak_f32 v16, v16, v14, 0x3e2aaaab
	v_fmaak_f32 v19, v19, v15, 0x3e2aaaab
	v_fma_f32 v16, v16, v14, 0.5
	v_fma_f32 v19, v19, v15, 0.5
	v_fma_f32 v16, v16, v14, 1.0
	v_fma_f32 v19, v19, v15, 1.0
	v_mul_f32_e64 v17, v16, -v14
	v_mul_f32_e64 v12, v19, -v15
	v_fma_f32 v16, -v22, v22, 1.0
	v_cmp_lt_f32_e32 vcc, s6, v14
	v_fma_f32 v13, -v23, v23, 1.0
	s_nop 0
	v_cndmask_b32_e32 v16, v16, v17, vcc
	v_cmp_lt_f32_e32 vcc, s6, v15
	v_sqrt_f32_e32 v16, v16
	s_nop 1
	v_cndmask_b32_e32 v17, v13, v12, vcc
	v_sqrt_f32_e32 v17, v17
	s_nop 0
	v_pk_mul_f32 v[26:27], v[26:27], v[16:17]
	s_nop 0
	v_pk_mul_f32 v[26:27], v[30:31], v[26:27]
	ds_write_b128 v204, v[20:23] offset:34304
	ds_write_b128 v204, v[24:27] offset:50688
	ds_read_b128 v[12:15], v229 offset:27392
	ds_read_b128 v[16:19], v229 offset:27456
	ds_read_b128 v[28:31], v230 offset:12800
	s_waitcnt lgkmcnt(1)
	v_mfma_f32_16x16x32_bf16 v[20:23], v[180:183], v[12:15], 0
	v_mfma_f32_16x16x32_bf16 v[24:27], v[188:191], v[12:15], 0
	v_mfma_f32_16x16x32_bf16 v[20:23], v[184:187], v[16:19], v[20:23]
	v_mfma_f32_16x16x32_bf16 v[24:27], v[192:195], v[16:19], v[24:27]
	s_nop 7
	s_nop 3
	s_waitcnt lgkmcnt(0)
; __device__ __forceinline__ float sigmoidf_(float x) { return __builtin_amdgcn_rcpf(1.0f + __expf(-x)); }
; template <bool FINAL>
; __device__ void phase_lru(const Params& p, int l, unsigned char* smem) {
;     ...
; #pragma unroll
;         for (int et = 0; et < 4; ++et) {
;           f32x4 ar = {0.f, 0.f, 0.f, 0.f}, ai = {0.f, 0.f, 0.f, 0.f};
;           const u16* wr = p.WLRU + ((((size_t)(l * 2 + d) * 2 + 0) * 8 + nb) * 64 + et * 16 + l15) * 64 + g * 8;
;           const u16* wi = p.WLRU + ((((size_t)(l * 2 + d) * 2 + 1) * 8 + nb) * 64 + et * 16 + l15) * 64 + g * 8;
; #pragma unroll
;           for (int ks = 0; ks < 2; ++ks) {
;             ar = mfma16(*(const bf16x8*)(wr + ks * 32), uf[ks], ar);
;             ai = mfma16(*(const bf16x8*)(wi + ks * 32), uf[ks], ai);
;           }
;           const int e0 = et * 16 + 4 * g, ch0 = nb * 64 + e0;
;           const float4 ba4 = *(const float4*)(p.ba + (l * 2 + d) * 512 + ch0);
;           const float4 bx4 = *(const float4*)(p.bx + (l * 2 + d) * 512 + ch0);
;           const float4 sp4 = *(const float4*)(p.SP8 + (l * 2 + d) * 512 + ch0);
;           const float4 uu = *(const float4*)(u32 + t * 64 + e0);
;           const float* bap = (const float*)&ba4; const float* bxp = (const float*)&bx4;
;           const float* spp = (const float*)&sp4; const float* uup = (const float*)&uu;
;           f32x4 av, bv;
; #pragma unroll
;           for (int j = 0; j < 4; ++j) {
;             float r = sigmoidf_(ar[j] + bap[j]);
;             float ig = sigmoidf_(ai[j] + bxp[j]);
;             float la = spp[j] * r;
;             float av_ = __expf(la);
;             float t2 = 2.0f * la;
;             float ser = -t2 * (1.f + t2 * 0.5f * (1.f + t2 * (1.f / 3.f) * (1.f + t2 * 0.25f * (1.f + t2 * 0.2f))));
;             float om = (t2 > -0.25f) ? ser : (1.0f - av_ * av_);
;             av[j] = av_;
;             bv[j] = __builtin_amdgcn_sqrtf(om) * ig * uup[j];
;           }
;           *(f32x4*)(sa + t * 64 + e0) = av;
;           *(f32x4*)(sb + t * 64 + e0) = bv;
;         }
	v_fmamk_f32 v20, v20, 0xbfb8aa3b, v196
	v_fmamk_f32 v21, v21, 0xbfb8aa3b, v197
	v_fmamk_f32 v24, v24, 0xbfb8aa3b, v200
	v_fmamk_f32 v25, v25, 0xbfb8aa3b, v201
	v_exp_f32_e32 v20, v20
	v_exp_f32_e32 v21, v21
	v_exp_f32_e32 v24, v24
	v_exp_f32_e32 v25, v25
	v_add_f32_e32 v20, 1.0, v20
	v_add_f32_e32 v21, 1.0, v21
	v_add_f32_e32 v24, 1.0, v24
	v_add_f32_e32 v25, 1.0, v25
	v_rcp_f32_e32 v20, v20
	v_rcp_f32_e32 v21, v21
	v_rcp_f32_e32 v24, v24
	v_rcp_f32_e32 v25, v25
	v_pk_mul_f32 v[12:13], v[20:21], v[32:33]
	s_nop 0
	v_pk_add_f32 v[14:15], v[12:13], v[12:13]
	v_mul_f32_e32 v20, 0x3fb8aa3b, v12
	v_mul_f32_e32 v21, 0x3fb8aa3b, v13
	v_exp_f32_e32 v20, v20
	v_exp_f32_e32 v21, v21
	v_fmaak_f32 v16, v14, v205, 0x3d2aaaab
	v_fmaak_f32 v19, v15, v205, 0x3d2aaaab
	v_fmaak_f32 v16, v16, v14, 0x3e2aaaab
	v_fmaak_f32 v19, v19, v15, 0x3e2aaaab
	v_fma_f32 v16, v16, v14, 0.5
	v_fma_f32 v19, v19, v15, 0.5
	v_fma_f32 v16, v16, v14, 1.0
	v_fma_f32 v19, v19, v15, 1.0
	v_mul_f32_e64 v17, v16, -v14
	v_mul_f32_e64 v12, v19, -v15
	v_fma_f32 v16, -v20, v20, 1.0
	v_cmp_lt_f32_e32 vcc, s6, v14
	v_fma_f32 v13, -v21, v21, 1.0
	s_nop 0
	v_cndmask_b32_e32 v16, v16, v17, vcc
	v_cmp_lt_f32_e32 vcc, s6, v15
	v_sqrt_f32_e32 v16, v16
	s_nop 1
	v_cndmask_b32_e32 v17, v13, v12, vcc
	v_sqrt_f32_e32 v17, v17
	s_nop 0
	v_pk_mul_f32 v[24:25], v[24:25], v[16:17]
	s_nop 0
	v_pk_mul_f32 v[24:25], v[28:29], v[24:25]
	v_fmamk_f32 v22, v22, 0xbfb8aa3b, v198
	v_fmamk_f32 v23, v23, 0xbfb8aa3b, v199
	v_fmamk_f32 v26, v26, 0xbfb8aa3b, v202
	v_fmamk_f32 v27, v27, 0xbfb8aa3b, v203
	v_exp_f32_e32 v22, v22
	v_exp_f32_e32 v23, v23
	v_exp_f32_e32 v26, v26
	v_exp_f32_e32 v27, v27
	v_add_f32_e32 v22, 1.0, v22
	v_add_f32_e32 v23, 1.0, v23
	v_add_f32_e32 v26, 1.0, v26
	v_add_f32_e32 v27, 1.0, v27
	v_rcp_f32_e32 v22, v22
	v_rcp_f32_e32 v23, v23
	v_rcp_f32_e32 v26, v26
	v_rcp_f32_e32 v27, v27
	v_pk_mul_f32 v[12:13], v[22:23], v[34:35]
	s_nop 0
	v_pk_add_f32 v[14:15], v[12:13], v[12:13]
	v_mul_f32_e32 v22, 0x3fb8aa3b, v12
	v_mul_f32_e32 v23, 0x3fb8aa3b, v13
	v_exp_f32_e32 v22, v22
	v_exp_f32_e32 v23, v23
	v_fmaak_f32 v16, v14, v205, 0x3d2aaaab
	v_fmaak_f32 v19, v15, v205, 0x3d2aaaab
	v_fmaak_f32 v16, v16, v14, 0x3e2aaaab
	v_fmaak_f32 v19, v19, v15, 0x3e2aaaab
	v_fma_f32 v16, v16, v14, 0.5
	v_fma_f32 v19, v19, v15, 0.5
	v_fma_f32 v16, v16, v14, 1.0
	v_fma_f32 v19, v19, v15, 1.0
	v_mul_f32_e64 v17, v16, -v14
	v_mul_f32_e64 v12, v19, -v15
	v_fma_f32 v16, -v22, v22, 1.0
	v_cmp_lt_f32_e32 vcc, s6, v14
	v_fma_f32 v13, -v23, v23, 1.0
	s_nop 0
	v_cndmask_b32_e32 v16, v16, v17, vcc
	v_cmp_lt_f32_e32 vcc, s6, v15
	v_sqrt_f32_e32 v16, v16
	s_nop 1
	v_cndmask_b32_e32 v17, v13, v12, vcc
	v_sqrt_f32_e32 v17, v17
	s_nop 0
	v_pk_mul_f32 v[26:27], v[26:27], v[16:17]
	s_nop 0
	v_pk_mul_f32 v[26:27], v[30:31], v[26:27]
	ds_write_b128 v204, v[20:23] offset:38400
	ds_write_b128 v204, v[24:27] offset:54784
	ds_read_b128 v[12:15], v229 offset:29696
	ds_read_b128 v[16:19], v229 offset:29760
	ds_read_b128 v[28:31], v230 offset:16896
	s_waitcnt lgkmcnt(1)
	v_mfma_f32_16x16x32_bf16 v[20:23], v[180:183], v[12:15], 0
	v_mfma_f32_16x16x32_bf16 v[24:27], v[188:191], v[12:15], 0
	v_mfma_f32_16x16x32_bf16 v[20:23], v[184:187], v[16:19], v[20:23]
	v_mfma_f32_16x16x32_bf16 v[24:27], v[192:195], v[16:19], v[24:27]
	s_nop 7
	s_nop 3
	s_waitcnt lgkmcnt(0)
	v_fmamk_f32 v20, v20, 0xbfb8aa3b, v196
	v_fmamk_f32 v21, v21, 0xbfb8aa3b, v197
	v_fmamk_f32 v24, v24, 0xbfb8aa3b, v200
	v_fmamk_f32 v25, v25, 0xbfb8aa3b, v201
	v_exp_f32_e32 v20, v20
	v_exp_f32_e32 v21, v21
	v_exp_f32_e32 v24, v24
	v_exp_f32_e32 v25, v25
	v_add_f32_e32 v20, 1.0, v20
	v_add_f32_e32 v21, 1.0, v21
	v_add_f32_e32 v24, 1.0, v24
	v_add_f32_e32 v25, 1.0, v25
	v_rcp_f32_e32 v20, v20
	v_rcp_f32_e32 v21, v21
	v_rcp_f32_e32 v24, v24
	v_rcp_f32_e32 v25, v25
	v_pk_mul_f32 v[12:13], v[20:21], v[32:33]
	s_nop 0
	v_pk_add_f32 v[14:15], v[12:13], v[12:13]
	v_mul_f32_e32 v20, 0x3fb8aa3b, v12
	v_mul_f32_e32 v21, 0x3fb8aa3b, v13
	v_exp_f32_e32 v20, v20
	v_exp_f32_e32 v21, v21
	v_fmaak_f32 v16, v14, v205, 0x3d2aaaab
	v_fmaak_f32 v19, v15, v205, 0x3d2aaaab
	v_fmaak_f32 v16, v16, v14, 0x3e2aaaab
	v_fmaak_f32 v19, v19, v15, 0x3e2aaaab
	v_fma_f32 v16, v16, v14, 0.5
	v_fma_f32 v19, v19, v15, 0.5
	v_fma_f32 v16, v16, v14, 1.0
	v_fma_f32 v19, v19, v15, 1.0
	v_mul_f32_e64 v17, v16, -v14
	v_mul_f32_e64 v12, v19, -v15
	v_fma_f32 v16, -v20, v20, 1.0
	v_cmp_lt_f32_e32 vcc, s6, v14
	v_fma_f32 v13, -v21, v21, 1.0
	s_nop 0
	v_cndmask_b32_e32 v16, v16, v17, vcc
	v_cmp_lt_f32_e32 vcc, s6, v15
	v_sqrt_f32_e32 v16, v16
	s_nop 1
	v_cndmask_b32_e32 v17, v13, v12, vcc
	v_sqrt_f32_e32 v17, v17
	s_nop 0
	v_pk_mul_f32 v[24:25], v[24:25], v[16:17]
	s_nop 0
	v_pk_mul_f32 v[24:25], v[28:29], v[24:25]
	v_fmamk_f32 v22, v22, 0xbfb8aa3b, v198
	v_fmamk_f32 v23, v23, 0xbfb8aa3b, v199
	v_fmamk_f32 v26, v26, 0xbfb8aa3b, v202
	v_fmamk_f32 v27, v27, 0xbfb8aa3b, v203
	v_exp_f32_e32 v22, v22
	v_exp_f32_e32 v23, v23
	v_exp_f32_e32 v26, v26
	v_exp_f32_e32 v27, v27
	v_add_f32_e32 v22, 1.0, v22
	v_add_f32_e32 v23, 1.0, v23
	v_add_f32_e32 v26, 1.0, v26
	v_add_f32_e32 v27, 1.0, v27
	v_rcp_f32_e32 v22, v22
	v_rcp_f32_e32 v23, v23
	v_rcp_f32_e32 v26, v26
	v_rcp_f32_e32 v27, v27
	v_pk_mul_f32 v[12:13], v[22:23], v[34:35]
	s_nop 0
	v_pk_add_f32 v[14:15], v[12:13], v[12:13]
	v_mul_f32_e32 v22, 0x3fb8aa3b, v12
	v_mul_f32_e32 v23, 0x3fb8aa3b, v13
	v_exp_f32_e32 v22, v22
	v_exp_f32_e32 v23, v23
	v_fmaak_f32 v16, v14, v205, 0x3d2aaaab
	v_fmaak_f32 v19, v15, v205, 0x3d2aaaab
	v_fmaak_f32 v16, v16, v14, 0x3e2aaaab
	v_fmaak_f32 v19, v19, v15, 0x3e2aaaab
	v_fma_f32 v16, v16, v14, 0.5
	v_fma_f32 v19, v19, v15, 0.5
	v_fma_f32 v16, v16, v14, 1.0
	v_fma_f32 v19, v19, v15, 1.0
	v_mul_f32_e64 v17, v16, -v14
	v_mul_f32_e64 v12, v19, -v15
	v_fma_f32 v16, -v22, v22, 1.0
	v_cmp_lt_f32_e32 vcc, s6, v14
	v_fma_f32 v13, -v23, v23, 1.0
	s_nop 0
	v_cndmask_b32_e32 v16, v16, v17, vcc
	v_cmp_lt_f32_e32 vcc, s6, v15
	v_sqrt_f32_e32 v16, v16
	s_nop 1
	v_cndmask_b32_e32 v17, v13, v12, vcc
	v_sqrt_f32_e32 v17, v17
	s_nop 0
	v_pk_mul_f32 v[26:27], v[26:27], v[16:17]
	s_nop 0
	v_pk_mul_f32 v[26:27], v[30:31], v[26:27]
	ds_write_b128 v204, v[20:23] offset:42496
	ds_write_b128 v204, v[24:27] offset:58880
	ds_read_b128 v[12:15], v229 offset:32000
	ds_read_b128 v[16:19], v229 offset:32064
	ds_read_b128 v[28:31], v230 offset:20992
	s_waitcnt lgkmcnt(1)
; __device__ __forceinline__ float sigmoidf_(float x) { return __builtin_amdgcn_rcpf(1.0f + __expf(-x)); }
; template <bool FINAL>
; __device__ void phase_lru(const Params& p, int l, unsigned char* smem) {
;     ...
;             ar = mfma16(*(const bf16x8*)(wr + ks * 32), uf[ks], ar);
;             ai = mfma16(*(const bf16x8*)(wi + ks * 32), uf[ks], ai);
;           }
;           const int e0 = et * 16 + 4 * g, ch0 = nb * 64 + e0;
;           const float4 ba4 = *(const float4*)(p.ba + (l * 2 + d) * 512 + ch0);
;           const float4 bx4 = *(const float4*)(p.bx + (l * 2 + d) * 512 + ch0);
;           const float4 sp4 = *(const float4*)(p.SP8 + (l * 2 + d) * 512 + ch0);
;           const float4 uu = *(const float4*)(u32 + t * 64 + e0);
;           const float* bap = (const float*)&ba4; const float* bxp = (const float*)&bx4;
;           const float* spp = (const float*)&sp4; const float* uup = (const float*)&uu;
;           f32x4 av, bv;
; #pragma unroll
;           for (int j = 0; j < 4; ++j) {
;             float r = sigmoidf_(ar[j] + bap[j]);
;             float ig = sigmoidf_(ai[j] + bxp[j]);
;             float la = spp[j] * r;
;             float av_ = __expf(la);
;             float t2 = 2.0f * la;
;             float ser = -t2 * (1.f + t2 * 0.5f * (1.f + t2 * (1.f / 3.f) * (1.f + t2 * 0.25f * (1.f + t2 * 0.2f))));
;             float om = (t2 > -0.25f) ? ser : (1.0f - av_ * av_);
;             av[j] = av_;
;             bv[j] = __builtin_amdgcn_sqrtf(om) * ig * uup[j];
;           }
;           *(f32x4*)(sa + t * 64 + e0) = av;
;           *(f32x4*)(sb + t * 64 + e0) = bv;
;         }
;       }
;       __syncthreads();
;       {
;         float A = 1.f, B = 0.f;
;         if (d == 0) {
; #pragma unroll
;           for (int tt = 0; tt < 16; ++tt) { int t = qd * 16 + tt; float a = sa[t * 64 + e_], b = sb[t * 64 + e_]; B = a * B + b; A *= a; }
;         } else {
; #pragma unroll
;     ...
;         }
;         part[(0 * 4 + qd) * 64 + e_] = A;
;         part[(1 * 4 + qd) * 64 + e_] = B;
;       }
	v_mfma_f32_16x16x32_bf16 v[20:23], v[180:183], v[12:15], 0
	v_mfma_f32_16x16x32_bf16 v[24:27], v[188:191], v[12:15], 0
	v_mfma_f32_16x16x32_bf16 v[20:23], v[184:187], v[16:19], v[20:23]
	v_mfma_f32_16x16x32_bf16 v[24:27], v[192:195], v[16:19], v[24:27]
	s_nop 7
	s_nop 3
	s_waitcnt lgkmcnt(0)
	v_fmamk_f32 v20, v20, 0xbfb8aa3b, v196
	v_fmamk_f32 v21, v21, 0xbfb8aa3b, v197
	v_fmamk_f32 v24, v24, 0xbfb8aa3b, v200
	v_fmamk_f32 v25, v25, 0xbfb8aa3b, v201
	v_exp_f32_e32 v20, v20
	v_exp_f32_e32 v21, v21
	v_exp_f32_e32 v24, v24
	v_exp_f32_e32 v25, v25
	v_add_f32_e32 v20, 1.0, v20
	v_add_f32_e32 v21, 1.0, v21
	v_add_f32_e32 v24, 1.0, v24
	v_add_f32_e32 v25, 1.0, v25
	v_rcp_f32_e32 v20, v20
	v_rcp_f32_e32 v21, v21
	v_rcp_f32_e32 v24, v24
	v_rcp_f32_e32 v25, v25
	v_pk_mul_f32 v[12:13], v[20:21], v[32:33]
	s_nop 0
	v_pk_add_f32 v[14:15], v[12:13], v[12:13]
	v_mul_f32_e32 v20, 0x3fb8aa3b, v12
	v_mul_f32_e32 v21, 0x3fb8aa3b, v13
	v_exp_f32_e32 v20, v20
	v_exp_f32_e32 v21, v21
	v_fmaak_f32 v16, v14, v205, 0x3d2aaaab
	v_fmaak_f32 v19, v15, v205, 0x3d2aaaab
	v_fmaak_f32 v16, v16, v14, 0x3e2aaaab
	v_fmaak_f32 v19, v19, v15, 0x3e2aaaab
	v_fma_f32 v16, v16, v14, 0.5
	v_fma_f32 v19, v19, v15, 0.5
	v_fma_f32 v16, v16, v14, 1.0
	v_fma_f32 v19, v19, v15, 1.0
	v_mul_f32_e64 v17, v16, -v14
	v_mul_f32_e64 v12, v19, -v15
	v_fma_f32 v16, -v20, v20, 1.0
	v_cmp_lt_f32_e32 vcc, s6, v14
	v_fma_f32 v13, -v21, v21, 1.0
	s_nop 0
	v_cndmask_b32_e32 v16, v16, v17, vcc
	v_cmp_lt_f32_e32 vcc, s6, v15
	v_sqrt_f32_e32 v16, v16
	s_nop 1
	v_cndmask_b32_e32 v17, v13, v12, vcc
	v_sqrt_f32_e32 v17, v17
	s_nop 0
	v_pk_mul_f32 v[24:25], v[24:25], v[16:17]
	s_nop 0
	v_pk_mul_f32 v[24:25], v[28:29], v[24:25]
	v_fmamk_f32 v22, v22, 0xbfb8aa3b, v198
	v_fmamk_f32 v23, v23, 0xbfb8aa3b, v199
	v_fmamk_f32 v26, v26, 0xbfb8aa3b, v202
	v_fmamk_f32 v27, v27, 0xbfb8aa3b, v203
	v_exp_f32_e32 v22, v22
	v_exp_f32_e32 v23, v23
	v_exp_f32_e32 v26, v26
	v_exp_f32_e32 v27, v27
	v_add_f32_e32 v22, 1.0, v22
	v_add_f32_e32 v23, 1.0, v23
	v_add_f32_e32 v26, 1.0, v26
	v_add_f32_e32 v27, 1.0, v27
	v_rcp_f32_e32 v22, v22
	v_rcp_f32_e32 v23, v23
	v_rcp_f32_e32 v26, v26
	v_rcp_f32_e32 v27, v27
	v_pk_mul_f32 v[12:13], v[22:23], v[34:35]
	s_nop 0
	v_pk_add_f32 v[14:15], v[12:13], v[12:13]
	v_mul_f32_e32 v22, 0x3fb8aa3b, v12
	v_mul_f32_e32 v23, 0x3fb8aa3b, v13
	v_exp_f32_e32 v22, v22
	v_exp_f32_e32 v23, v23
	v_fmaak_f32 v16, v14, v205, 0x3d2aaaab
	v_fmaak_f32 v19, v15, v205, 0x3d2aaaab
	v_fmaak_f32 v16, v16, v14, 0x3e2aaaab
	v_fmaak_f32 v19, v19, v15, 0x3e2aaaab
	v_fma_f32 v16, v16, v14, 0.5
	v_fma_f32 v19, v19, v15, 0.5
	v_fma_f32 v16, v16, v14, 1.0
	v_fma_f32 v19, v19, v15, 1.0
	v_mul_f32_e64 v17, v16, -v14
	v_mul_f32_e64 v12, v19, -v15
	v_fma_f32 v16, -v22, v22, 1.0
	v_cmp_lt_f32_e32 vcc, s6, v14
	v_fma_f32 v13, -v23, v23, 1.0
	s_nop 0
	v_cndmask_b32_e32 v16, v16, v17, vcc
	v_cmp_lt_f32_e32 vcc, s6, v15
	v_sqrt_f32_e32 v16, v16
	s_nop 1
	v_cndmask_b32_e32 v17, v13, v12, vcc
	v_sqrt_f32_e32 v17, v17
	s_nop 0
	v_pk_mul_f32 v[26:27], v[26:27], v[16:17]
	s_nop 0
	v_pk_mul_f32 v[26:27], v[30:31], v[26:27]
	ds_write_b128 v204, v[20:23] offset:46592
	ds_write_b128 v204, v[24:27] offset:62976
	s_waitcnt lgkmcnt(0)
	s_barrier
	ds_read2st64_b32 v[12:13], v59 offset0:134 offset1:198
	ds_read2st64_b32 v[14:15], v118 offset0:134 offset1:198
	ds_read2st64_b32 v[16:17], v119 offset0:134 offset1:198
	ds_read2st64_b32 v[64:65], v129 offset0:134 offset1:198
	ds_read2st64_b32 v[66:67], v130 offset0:134 offset1:198
	s_waitcnt lgkmcnt(4)
	v_fmac_f32_e32 v13, 0, v12
	s_waitcnt lgkmcnt(3)
	v_mul_f32_e32 v18, v12, v14
	s_waitcnt lgkmcnt(2)
	v_mul_f32_e32 v20, v18, v16
	ds_read2st64_b32 v[18:19], v120 offset0:134 offset1:198
	v_fmac_f32_e32 v15, v14, v13
	v_fmac_f32_e32 v17, v16, v15
	ds_read2st64_b32 v[68:69], v131 offset0:134 offset1:198
	ds_read2st64_b32 v[70:71], v132 offset0:134 offset1:198
	s_waitcnt lgkmcnt(2)
	v_mul_f32_e32 v22, v20, v18
	ds_read2st64_b32 v[20:21], v121 offset0:134 offset1:198
	v_fmac_f32_e32 v19, v18, v17
	s_waitcnt lgkmcnt(0)
	v_mul_f32_e32 v24, v22, v20
	ds_read2st64_b32 v[22:23], v122 offset0:134 offset1:198
	v_fmac_f32_e32 v21, v20, v19
	s_waitcnt lgkmcnt(0)
	v_mul_f32_e32 v26, v24, v22
	ds_read2st64_b32 v[24:25], v123 offset0:134 offset1:198
	v_fmac_f32_e32 v23, v22, v21
	s_waitcnt lgkmcnt(0)
	v_mul_f32_e32 v28, v26, v24
	ds_read2st64_b32 v[26:27], v124 offset0:134 offset1:198
	v_fmac_f32_e32 v25, v24, v23
	s_waitcnt lgkmcnt(0)
	v_mul_f32_e32 v30, v28, v26
	ds_read2st64_b32 v[28:29], v125 offset0:134 offset1:198
	v_fmac_f32_e32 v27, v26, v25
	s_waitcnt lgkmcnt(0)
	v_mul_f32_e32 v32, v30, v28
	ds_read2st64_b32 v[30:31], v126 offset0:134 offset1:198
	v_fmac_f32_e32 v29, v28, v27
	s_waitcnt lgkmcnt(0)
	v_mul_f32_e32 v34, v32, v30
	ds_read2st64_b32 v[32:33], v127 offset0:134 offset1:198
	v_fmac_f32_e32 v31, v30, v29
	s_waitcnt lgkmcnt(0)
	v_mul_f32_e32 v63, v34, v32
	ds_read2st64_b32 v[34:35], v128 offset0:134 offset1:198
	v_fmac_f32_e32 v33, v32, v31
	s_waitcnt lgkmcnt(0)
	v_mul_f32_e32 v63, v63, v34
	v_mul_f32_e32 v63, v63, v64
	v_fmac_f32_e32 v35, v34, v33
	v_mul_f32_e32 v63, v63, v66
	v_fmac_f32_e32 v65, v64, v35
	v_mul_f32_e32 v63, v63, v68
	v_fmac_f32_e32 v67, v66, v65
	v_mul_f32_e32 v63, v63, v70
	v_fmac_f32_e32 v69, v68, v67
	v_fmac_f32_e32 v71, v70, v69
	ds_write_b32 v98, v63
	ds_write_b32 v100, v71 offset:1024
	s_waitcnt lgkmcnt(0)
	s_barrier
	s_and_saveexec_b64 s[56:57], s[22:23]
	s_cbranch_execnz .LBB0_218
	s_or_b64 exec, exec, s[56:57]
	s_and_saveexec_b64 s[56:57], s[24:25]
	s_cbranch_execnz .LBB0_219

; __device__ __forceinline__ float sigmoidf_(float x) { return __builtin_amdgcn_rcpf(1.0f + __expf(-x)); }
; template <bool FINAL>
; __device__ void phase_lru(const Params& p, int l, unsigned char* smem) {
;     ...
; #pragma unroll
;         for (int et = 0; et < 4; ++et) {
;           f32x4 ar = {0.f, 0.f, 0.f, 0.f}, ai = {0.f, 0.f, 0.f, 0.f};
;           const u16* wr = p.WLRU + ((((size_t)(l * 2 + d) * 2 + 0) * 8 + nb) * 64 + et * 16 + l15) * 64 + g * 8;
;           const u16* wi = p.WLRU + ((((size_t)(l * 2 + d) * 2 + 1) * 8 + nb) * 64 + et * 16 + l15) * 64 + g * 8;
; #pragma unroll
;           for (int ks = 0; ks < 2; ++ks) {
;             ar = mfma16(*(const bf16x8*)(wr + ks * 32), uf[ks], ar);
;             ai = mfma16(*(const bf16x8*)(wi + ks * 32), uf[ks], ai);
;           }
;           const int e0 = et * 16 + 4 * g, ch0 = nb * 64 + e0;
;           const float4 ba4 = *(const float4*)(p.ba + (l * 2 + d) * 512 + ch0);
;           const float4 bx4 = *(const float4*)(p.bx + (l * 2 + d) * 512 + ch0);
;           const float4 sp4 = *(const float4*)(p.SP8 + (l * 2 + d) * 512 + ch0);
;           const float4 uu = *(const float4*)(u32 + t * 64 + e0);
;           const float* bap = (const float*)&ba4; const float* bxp = (const float*)&bx4;
;           const float* spp = (const float*)&sp4; const float* uup = (const float*)&uu;
;           f32x4 av, bv;
; #pragma unroll
;           for (int j = 0; j < 4; ++j) {
;             float r = sigmoidf_(ar[j] + bap[j]);
;             float ig = sigmoidf_(ai[j] + bxp[j]);
;             float la = spp[j] * r;
;             float av_ = __expf(la);
;             float t2 = 2.0f * la;
;             float ser = -t2 * (1.f + t2 * 0.5f * (1.f + t2 * (1.f / 3.f) * (1.f + t2 * 0.25f * (1.f + t2 * 0.2f))));
;             float om = (t2 > -0.25f) ? ser : (1.0f - av_ * av_);
;             av[j] = av_;
;             bv[j] = __builtin_amdgcn_sqrtf(om) * ig * uup[j];
;           }
;           *(f32x4*)(sa + t * 64 + e0) = av;
;           *(f32x4*)(sb + t * 64 + e0) = bv;
;         }
;     ...
;           for (int q = 0; q < 4; ++q) if (q < qd) h = part[q * 64 + e_] * h + part[(4 + q) * 64 + e_];
; #pragma unroll
;           for (int tt = 0; tt < 16; ++tt) { int t = qd * 16 + tt; h = sa[t * 64 + e_] * h + sb[t * 64 + e_]; hsum[tt] += h; }
.LBB0_214:
	s_or_b64 exec, exec, s[56:57]
	v_lshl_add_u64 v[20:21], s[64:65], 0, v[144:145]
	v_mov_b32_e32 v63, v145
	v_lshl_add_u64 v[28:29], v[20:21], 0, v[62:63]
	ds_read2st64_b32 v[94:95], v59 offset0:134 offset1:198
	ds_read2st64_b32 v[92:93], v118 offset0:134 offset1:198
	ds_read2st64_b32 v[90:91], v119 offset0:134 offset1:198
	ds_read2st64_b32 v[88:89], v120 offset0:134 offset1:198
	ds_read2st64_b32 v[86:87], v121 offset0:134 offset1:198
	ds_read2st64_b32 v[84:85], v122 offset0:134 offset1:198
	ds_read2st64_b32 v[82:83], v123 offset0:134 offset1:198
	ds_read2st64_b32 v[80:81], v124 offset0:134 offset1:198
	ds_read2st64_b32 v[78:79], v125 offset0:134 offset1:198
	ds_read2st64_b32 v[76:77], v126 offset0:134 offset1:198
	ds_read2st64_b32 v[74:75], v127 offset0:134 offset1:198
	ds_read2st64_b32 v[72:73], v128 offset0:134 offset1:198
	ds_read2st64_b32 v[70:71], v129 offset0:134 offset1:198
	ds_read2st64_b32 v[68:69], v130 offset0:134 offset1:198
	ds_read2st64_b32 v[64:65], v131 offset0:134 offset1:198
	ds_read2st64_b32 v[66:67], v132 offset0:134 offset1:198
	s_waitcnt lgkmcnt(0)
	s_barrier
	s_mov_b32 s5, 0x3e4ccccd
	global_load_dwordx4 v[196:199], v231, s[66:67]
	global_load_dwordx4 v[200:203], v231, s[68:69]
	global_load_dwordx4 v[32:35], v231, s[72:73]
	ds_read_b128 v[12:15], v229 offset:25088
	ds_read_b128 v[16:19], v229 offset:25152
	ds_read_b128 v[28:31], v230 offset:8704
	s_waitcnt lgkmcnt(1)
	v_mfma_f32_16x16x32_bf16 v[20:23], v[232:235], v[12:15], 0
	v_mfma_f32_16x16x32_bf16 v[24:27], v[240:243], v[12:15], 0
	v_mfma_f32_16x16x32_bf16 v[20:23], v[236:239], v[16:19], v[20:23]
	v_mfma_f32_16x16x32_bf16 v[24:27], v[244:247], v[16:19], v[24:27]
	s_waitcnt vmcnt(0)
	v_mul_f32_e32 v196, 0xbfb8aa3b, v196
	v_mul_f32_e32 v197, 0xbfb8aa3b, v197
	v_mul_f32_e32 v198, 0xbfb8aa3b, v198
	v_mul_f32_e32 v199, 0xbfb8aa3b, v199
	v_mul_f32_e32 v200, 0xbfb8aa3b, v200
	v_mul_f32_e32 v201, 0xbfb8aa3b, v201
	v_mul_f32_e32 v202, 0xbfb8aa3b, v202
	v_mul_f32_e32 v203, 0xbfb8aa3b, v203
	s_nop 7
	s_nop 3
	s_waitcnt lgkmcnt(0)
	v_fmamk_f32 v20, v20, 0xbfb8aa3b, v196
	v_fmamk_f32 v21, v21, 0xbfb8aa3b, v197
	v_fmamk_f32 v24, v24, 0xbfb8aa3b, v200
	v_fmamk_f32 v25, v25, 0xbfb8aa3b, v201
	v_exp_f32_e32 v20, v20
	v_exp_f32_e32 v21, v21
	v_exp_f32_e32 v24, v24
	v_exp_f32_e32 v25, v25
	v_add_f32_e32 v20, 1.0, v20
	v_add_f32_e32 v21, 1.0, v21
	v_add_f32_e32 v24, 1.0, v24
	v_add_f32_e32 v25, 1.0, v25
	v_rcp_f32_e32 v20, v20
	v_rcp_f32_e32 v21, v21
	v_rcp_f32_e32 v24, v24
	v_rcp_f32_e32 v25, v25
	v_pk_mul_f32 v[12:13], v[20:21], v[32:33]
	s_nop 0
	v_pk_add_f32 v[14:15], v[12:13], v[12:13]
	v_mul_f32_e32 v20, 0x3fb8aa3b, v12
	v_mul_f32_e32 v21, 0x3fb8aa3b, v13
	v_exp_f32_e32 v20, v20
	v_exp_f32_e32 v21, v21
	v_fmaak_f32 v16, v14, v205, 0x3d2aaaab
	v_fmaak_f32 v19, v15, v205, 0x3d2aaaab
	v_fmaak_f32 v16, v16, v14, 0x3e2aaaab
	v_fmaak_f32 v19, v19, v15, 0x3e2aaaab
	v_fma_f32 v16, v16, v14, 0.5
	v_fma_f32 v19, v19, v15, 0.5
	v_fma_f32 v16, v16, v14, 1.0
	v_fma_f32 v19, v19, v15, 1.0
	v_mul_f32_e64 v17, v16, -v14
	v_mul_f32_e64 v12, v19, -v15
	v_fma_f32 v16, -v20, v20, 1.0
	v_cmp_lt_f32_e32 vcc, s6, v14
	v_fma_f32 v13, -v21, v21, 1.0
	s_nop 0
	v_cndmask_b32_e32 v16, v16, v17, vcc
	v_cmp_lt_f32_e32 vcc, s6, v15
	v_sqrt_f32_e32 v16, v16
	s_nop 1
	v_cndmask_b32_e32 v17, v13, v12, vcc
	v_sqrt_f32_e32 v17, v17
	s_nop 0
	v_pk_mul_f32 v[24:25], v[24:25], v[16:17]
	s_nop 0
	v_pk_mul_f32 v[24:25], v[28:29], v[24:25]
	v_fmamk_f32 v22, v22, 0xbfb8aa3b, v198
	v_fmamk_f32 v23, v23, 0xbfb8aa3b, v199
	v_fmamk_f32 v26, v26, 0xbfb8aa3b, v202
	v_fmamk_f32 v27, v27, 0xbfb8aa3b, v203
	v_exp_f32_e32 v22, v22
	v_exp_f32_e32 v23, v23
	v_exp_f32_e32 v26, v26
	v_exp_f32_e32 v27, v27
	v_add_f32_e32 v22, 1.0, v22
	v_add_f32_e32 v23, 1.0, v23
	v_add_f32_e32 v26, 1.0, v26
	v_add_f32_e32 v27, 1.0, v27
	v_rcp_f32_e32 v22, v22
	v_rcp_f32_e32 v23, v23
	v_rcp_f32_e32 v26, v26
	v_rcp_f32_e32 v27, v27
	v_pk_mul_f32 v[12:13], v[22:23], v[34:35]
	s_nop 0
	v_pk_add_f32 v[14:15], v[12:13], v[12:13]
	v_mul_f32_e32 v22, 0x3fb8aa3b, v12
	v_mul_f32_e32 v23, 0x3fb8aa3b, v13
	v_exp_f32_e32 v22, v22
	v_exp_f32_e32 v23, v23
	v_fmaak_f32 v16, v14, v205, 0x3d2aaaab
	v_fmaak_f32 v19, v15, v205, 0x3d2aaaab
	v_fmaak_f32 v16, v16, v14, 0x3e2aaaab
	v_fmaak_f32 v19, v19, v15, 0x3e2aaaab
	v_fma_f32 v16, v16, v14, 0.5
	v_fma_f32 v19, v19, v15, 0.5
	v_fma_f32 v16, v16, v14, 1.0
	v_fma_f32 v19, v19, v15, 1.0
	v_mul_f32_e64 v17, v16, -v14
	v_mul_f32_e64 v12, v19, -v15
	v_fma_f32 v16, -v22, v22, 1.0
	v_cmp_lt_f32_e32 vcc, s6, v14
	v_fma_f32 v13, -v23, v23, 1.0
	s_nop 0
	v_cndmask_b32_e32 v16, v16, v17, vcc
	v_cmp_lt_f32_e32 vcc, s6, v15
	v_sqrt_f32_e32 v16, v16
	s_nop 1
	v_cndmask_b32_e32 v17, v13, v12, vcc
	v_sqrt_f32_e32 v17, v17
	s_nop 0
	v_pk_mul_f32 v[26:27], v[26:27], v[16:17]
	s_nop 0
	v_pk_mul_f32 v[26:27], v[30:31], v[26:27]
	ds_write_b128 v204, v[20:23] offset:34304
	ds_write_b128 v204, v[24:27] offset:50688
	ds_read_b128 v[12:15], v229 offset:27392
	ds_read_b128 v[16:19], v229 offset:27456
	ds_read_b128 v[28:31], v230 offset:12800
	s_waitcnt lgkmcnt(1)
	v_mfma_f32_16x16x32_bf16 v[20:23], v[232:235], v[12:15], 0
	v_mfma_f32_16x16x32_bf16 v[24:27], v[240:243], v[12:15], 0
	v_mfma_f32_16x16x32_bf16 v[20:23], v[236:239], v[16:19], v[20:23]
	v_mfma_f32_16x16x32_bf16 v[24:27], v[244:247], v[16:19], v[24:27]
	s_nop 7
	s_nop 3
	s_waitcnt lgkmcnt(0)
; __device__ __forceinline__ float sigmoidf_(float x) { return __builtin_amdgcn_rcpf(1.0f + __expf(-x)); }
; template <bool FINAL>
; __device__ void phase_lru(const Params& p, int l, unsigned char* smem) {
;     ...
; #pragma unroll
;         for (int et = 0; et < 4; ++et) {
;           f32x4 ar = {0.f, 0.f, 0.f, 0.f}, ai = {0.f, 0.f, 0.f, 0.f};
;           const u16* wr = p.WLRU + ((((size_t)(l * 2 + d) * 2 + 0) * 8 + nb) * 64 + et * 16 + l15) * 64 + g * 8;
;           const u16* wi = p.WLRU + ((((size_t)(l * 2 + d) * 2 + 1) * 8 + nb) * 64 + et * 16 + l15) * 64 + g * 8;
; #pragma unroll
;           for (int ks = 0; ks < 2; ++ks) {
;             ar = mfma16(*(const bf16x8*)(wr + ks * 32), uf[ks], ar);
;             ai = mfma16(*(const bf16x8*)(wi + ks * 32), uf[ks], ai);
;           }
;           const int e0 = et * 16 + 4 * g, ch0 = nb * 64 + e0;
;           const float4 ba4 = *(const float4*)(p.ba + (l * 2 + d) * 512 + ch0);
;           const float4 bx4 = *(const float4*)(p.bx + (l * 2 + d) * 512 + ch0);
;           const float4 sp4 = *(const float4*)(p.SP8 + (l * 2 + d) * 512 + ch0);
;           const float4 uu = *(const float4*)(u32 + t * 64 + e0);
;           const float* bap = (const float*)&ba4; const float* bxp = (const float*)&bx4;
;           const float* spp = (const float*)&sp4; const float* uup = (const float*)&uu;
;           f32x4 av, bv;
; #pragma unroll
;           for (int j = 0; j < 4; ++j) {
;             float r = sigmoidf_(ar[j] + bap[j]);
;             float ig = sigmoidf_(ai[j] + bxp[j]);
;             float la = spp[j] * r;
;             float av_ = __expf(la);
;             float t2 = 2.0f * la;
;             float ser = -t2 * (1.f + t2 * 0.5f * (1.f + t2 * (1.f / 3.f) * (1.f + t2 * 0.25f * (1.f + t2 * 0.2f))));
;             float om = (t2 > -0.25f) ? ser : (1.0f - av_ * av_);
;             av[j] = av_;
;             bv[j] = __builtin_amdgcn_sqrtf(om) * ig * uup[j];
;           }
;           *(f32x4*)(sa + t * 64 + e0) = av;
;           *(f32x4*)(sb + t * 64 + e0) = bv;
;         }
	v_fmamk_f32 v20, v20, 0xbfb8aa3b, v196
	v_fmamk_f32 v21, v21, 0xbfb8aa3b, v197
	v_fmamk_f32 v24, v24, 0xbfb8aa3b, v200
	v_fmamk_f32 v25, v25, 0xbfb8aa3b, v201
	v_exp_f32_e32 v20, v20
	v_exp_f32_e32 v21, v21
	v_exp_f32_e32 v24, v24
	v_exp_f32_e32 v25, v25
	v_add_f32_e32 v20, 1.0, v20
	v_add_f32_e32 v21, 1.0, v21
	v_add_f32_e32 v24, 1.0, v24
	v_add_f32_e32 v25, 1.0, v25
	v_rcp_f32_e32 v20, v20
	v_rcp_f32_e32 v21, v21
	v_rcp_f32_e32 v24, v24
	v_rcp_f32_e32 v25, v25
	v_pk_mul_f32 v[12:13], v[20:21], v[32:33]
	s_nop 0
	v_pk_add_f32 v[14:15], v[12:13], v[12:13]
	v_mul_f32_e32 v20, 0x3fb8aa3b, v12
	v_mul_f32_e32 v21, 0x3fb8aa3b, v13
	v_exp_f32_e32 v20, v20
	v_exp_f32_e32 v21, v21
	v_fmaak_f32 v16, v14, v205, 0x3d2aaaab
	v_fmaak_f32 v19, v15, v205, 0x3d2aaaab
	v_fmaak_f32 v16, v16, v14, 0x3e2aaaab
	v_fmaak_f32 v19, v19, v15, 0x3e2aaaab
	v_fma_f32 v16, v16, v14, 0.5
	v_fma_f32 v19, v19, v15, 0.5
	v_fma_f32 v16, v16, v14, 1.0
	v_fma_f32 v19, v19, v15, 1.0
	v_mul_f32_e64 v17, v16, -v14
	v_mul_f32_e64 v12, v19, -v15
	v_fma_f32 v16, -v20, v20, 1.0
	v_cmp_lt_f32_e32 vcc, s6, v14
	v_fma_f32 v13, -v21, v21, 1.0
	s_nop 0
	v_cndmask_b32_e32 v16, v16, v17, vcc
	v_cmp_lt_f32_e32 vcc, s6, v15
	v_sqrt_f32_e32 v16, v16
	s_nop 1
	v_cndmask_b32_e32 v17, v13, v12, vcc
	v_sqrt_f32_e32 v17, v17
	s_nop 0
	v_pk_mul_f32 v[24:25], v[24:25], v[16:17]
	s_nop 0
	v_pk_mul_f32 v[24:25], v[28:29], v[24:25]
	v_fmamk_f32 v22, v22, 0xbfb8aa3b, v198
	v_fmamk_f32 v23, v23, 0xbfb8aa3b, v199
	v_fmamk_f32 v26, v26, 0xbfb8aa3b, v202
	v_fmamk_f32 v27, v27, 0xbfb8aa3b, v203
	v_exp_f32_e32 v22, v22
	v_exp_f32_e32 v23, v23
	v_exp_f32_e32 v26, v26
	v_exp_f32_e32 v27, v27
	v_add_f32_e32 v22, 1.0, v22
	v_add_f32_e32 v23, 1.0, v23
	v_add_f32_e32 v26, 1.0, v26
	v_add_f32_e32 v27, 1.0, v27
	v_rcp_f32_e32 v22, v22
	v_rcp_f32_e32 v23, v23
	v_rcp_f32_e32 v26, v26
	v_rcp_f32_e32 v27, v27
	v_pk_mul_f32 v[12:13], v[22:23], v[34:35]
	s_nop 0
	v_pk_add_f32 v[14:15], v[12:13], v[12:13]
	v_mul_f32_e32 v22, 0x3fb8aa3b, v12
	v_mul_f32_e32 v23, 0x3fb8aa3b, v13
	v_exp_f32_e32 v22, v22
	v_exp_f32_e32 v23, v23
	v_fmaak_f32 v16, v14, v205, 0x3d2aaaab
	v_fmaak_f32 v19, v15, v205, 0x3d2aaaab
	v_fmaak_f32 v16, v16, v14, 0x3e2aaaab
	v_fmaak_f32 v19, v19, v15, 0x3e2aaaab
	v_fma_f32 v16, v16, v14, 0.5
	v_fma_f32 v19, v19, v15, 0.5
	v_fma_f32 v16, v16, v14, 1.0
	v_fma_f32 v19, v19, v15, 1.0
	v_mul_f32_e64 v17, v16, -v14
	v_mul_f32_e64 v12, v19, -v15
	v_fma_f32 v16, -v22, v22, 1.0
	v_cmp_lt_f32_e32 vcc, s6, v14
	v_fma_f32 v13, -v23, v23, 1.0
	s_nop 0
	v_cndmask_b32_e32 v16, v16, v17, vcc
	v_cmp_lt_f32_e32 vcc, s6, v15
	v_sqrt_f32_e32 v16, v16
	s_nop 1
	v_cndmask_b32_e32 v17, v13, v12, vcc
	v_sqrt_f32_e32 v17, v17
	s_nop 0
	v_pk_mul_f32 v[26:27], v[26:27], v[16:17]
	s_nop 0
	v_pk_mul_f32 v[26:27], v[30:31], v[26:27]
	ds_write_b128 v204, v[20:23] offset:38400
	ds_write_b128 v204, v[24:27] offset:54784
	ds_read_b128 v[12:15], v229 offset:29696
	ds_read_b128 v[16:19], v229 offset:29760
	ds_read_b128 v[28:31], v230 offset:16896
	s_waitcnt lgkmcnt(1)
	v_mfma_f32_16x16x32_bf16 v[20:23], v[232:235], v[12:15], 0
	v_mfma_f32_16x16x32_bf16 v[24:27], v[240:243], v[12:15], 0
	v_mfma_f32_16x16x32_bf16 v[20:23], v[236:239], v[16:19], v[20:23]
	v_mfma_f32_16x16x32_bf16 v[24:27], v[244:247], v[16:19], v[24:27]
	s_nop 7
	s_nop 3
	s_waitcnt lgkmcnt(0)
	v_fmamk_f32 v20, v20, 0xbfb8aa3b, v196
	v_fmamk_f32 v21, v21, 0xbfb8aa3b, v197
	v_fmamk_f32 v24, v24, 0xbfb8aa3b, v200
	v_fmamk_f32 v25, v25, 0xbfb8aa3b, v201
	v_exp_f32_e32 v20, v20
	v_exp_f32_e32 v21, v21
	v_exp_f32_e32 v24, v24
	v_exp_f32_e32 v25, v25
	v_add_f32_e32 v20, 1.0, v20
	v_add_f32_e32 v21, 1.0, v21
	v_add_f32_e32 v24, 1.0, v24
	v_add_f32_e32 v25, 1.0, v25
	v_rcp_f32_e32 v20, v20
	v_rcp_f32_e32 v21, v21
	v_rcp_f32_e32 v24, v24
	v_rcp_f32_e32 v25, v25
	v_pk_mul_f32 v[12:13], v[20:21], v[32:33]
	s_nop 0
	v_pk_add_f32 v[14:15], v[12:13], v[12:13]
	v_mul_f32_e32 v20, 0x3fb8aa3b, v12
	v_mul_f32_e32 v21, 0x3fb8aa3b, v13
	v_exp_f32_e32 v20, v20
	v_exp_f32_e32 v21, v21
	v_fmaak_f32 v16, v14, v205, 0x3d2aaaab
	v_fmaak_f32 v19, v15, v205, 0x3d2aaaab
	v_fmaak_f32 v16, v16, v14, 0x3e2aaaab
	v_fmaak_f32 v19, v19, v15, 0x3e2aaaab
	v_fma_f32 v16, v16, v14, 0.5
	v_fma_f32 v19, v19, v15, 0.5
	v_fma_f32 v16, v16, v14, 1.0
	v_fma_f32 v19, v19, v15, 1.0
	v_mul_f32_e64 v17, v16, -v14
	v_mul_f32_e64 v12, v19, -v15
	v_fma_f32 v16, -v20, v20, 1.0
	v_cmp_lt_f32_e32 vcc, s6, v14
	v_fma_f32 v13, -v21, v21, 1.0
	s_nop 0
	v_cndmask_b32_e32 v16, v16, v17, vcc
	v_cmp_lt_f32_e32 vcc, s6, v15
	v_sqrt_f32_e32 v16, v16
	s_nop 1
	v_cndmask_b32_e32 v17, v13, v12, vcc
	v_sqrt_f32_e32 v17, v17
	s_nop 0
	v_pk_mul_f32 v[24:25], v[24:25], v[16:17]
	s_nop 0
	v_pk_mul_f32 v[24:25], v[28:29], v[24:25]
	v_fmamk_f32 v22, v22, 0xbfb8aa3b, v198
	v_fmamk_f32 v23, v23, 0xbfb8aa3b, v199
	v_fmamk_f32 v26, v26, 0xbfb8aa3b, v202
	v_fmamk_f32 v27, v27, 0xbfb8aa3b, v203
	v_exp_f32_e32 v22, v22
	v_exp_f32_e32 v23, v23
	v_exp_f32_e32 v26, v26
	v_exp_f32_e32 v27, v27
	v_add_f32_e32 v22, 1.0, v22
	v_add_f32_e32 v23, 1.0, v23
	v_add_f32_e32 v26, 1.0, v26
	v_add_f32_e32 v27, 1.0, v27
	v_rcp_f32_e32 v22, v22
	v_rcp_f32_e32 v23, v23
	v_rcp_f32_e32 v26, v26
	v_rcp_f32_e32 v27, v27
	v_pk_mul_f32 v[12:13], v[22:23], v[34:35]
	s_nop 0
	v_pk_add_f32 v[14:15], v[12:13], v[12:13]
	v_mul_f32_e32 v22, 0x3fb8aa3b, v12
	v_mul_f32_e32 v23, 0x3fb8aa3b, v13
	v_exp_f32_e32 v22, v22
	v_exp_f32_e32 v23, v23
	v_fmaak_f32 v16, v14, v205, 0x3d2aaaab
	v_fmaak_f32 v19, v15, v205, 0x3d2aaaab
	v_fmaak_f32 v16, v16, v14, 0x3e2aaaab
	v_fmaak_f32 v19, v19, v15, 0x3e2aaaab
	v_fma_f32 v16, v16, v14, 0.5
	v_fma_f32 v19, v19, v15, 0.5
	v_fma_f32 v16, v16, v14, 1.0
	v_fma_f32 v19, v19, v15, 1.0
	v_mul_f32_e64 v17, v16, -v14
	v_mul_f32_e64 v12, v19, -v15
	v_fma_f32 v16, -v22, v22, 1.0
	v_cmp_lt_f32_e32 vcc, s6, v14
	v_fma_f32 v13, -v23, v23, 1.0
	s_nop 0
	v_cndmask_b32_e32 v16, v16, v17, vcc
	v_cmp_lt_f32_e32 vcc, s6, v15
	v_sqrt_f32_e32 v16, v16
	s_nop 1
	v_cndmask_b32_e32 v17, v13, v12, vcc
	v_sqrt_f32_e32 v17, v17
	s_nop 0
	v_pk_mul_f32 v[26:27], v[26:27], v[16:17]
	s_nop 0
	v_pk_mul_f32 v[26:27], v[30:31], v[26:27]
	ds_write_b128 v204, v[20:23] offset:42496
	ds_write_b128 v204, v[24:27] offset:58880
	ds_read_b128 v[12:15], v229 offset:32000
	ds_read_b128 v[16:19], v229 offset:32064
	ds_read_b128 v[28:31], v230 offset:20992
	s_waitcnt lgkmcnt(1)
; __device__ __forceinline__ float sigmoidf_(float x) { return __builtin_amdgcn_rcpf(1.0f + __expf(-x)); }
; template <bool FINAL>
; __device__ void phase_lru(const Params& p, int l, unsigned char* smem) {
;     ...
;             ar = mfma16(*(const bf16x8*)(wr + ks * 32), uf[ks], ar);
;             ai = mfma16(*(const bf16x8*)(wi + ks * 32), uf[ks], ai);
;           }
;           const int e0 = et * 16 + 4 * g, ch0 = nb * 64 + e0;
;           const float4 ba4 = *(const float4*)(p.ba + (l * 2 + d) * 512 + ch0);
;           const float4 bx4 = *(const float4*)(p.bx + (l * 2 + d) * 512 + ch0);
;           const float4 sp4 = *(const float4*)(p.SP8 + (l * 2 + d) * 512 + ch0);
;           const float4 uu = *(const float4*)(u32 + t * 64 + e0);
;           const float* bap = (const float*)&ba4; const float* bxp = (const float*)&bx4;
;           const float* spp = (const float*)&sp4; const float* uup = (const float*)&uu;
;           f32x4 av, bv;
; #pragma unroll
;           for (int j = 0; j < 4; ++j) {
;             float r = sigmoidf_(ar[j] + bap[j]);
;             float ig = sigmoidf_(ai[j] + bxp[j]);
;             float la = spp[j] * r;
;             float av_ = __expf(la);
;             float t2 = 2.0f * la;
;             float ser = -t2 * (1.f + t2 * 0.5f * (1.f + t2 * (1.f / 3.f) * (1.f + t2 * 0.25f * (1.f + t2 * 0.2f))));
;             float om = (t2 > -0.25f) ? ser : (1.0f - av_ * av_);
;             av[j] = av_;
;             bv[j] = __builtin_amdgcn_sqrtf(om) * ig * uup[j];
;           }
;           *(f32x4*)(sa + t * 64 + e0) = av;
;           *(f32x4*)(sb + t * 64 + e0) = bv;
;         }
;       }
;       __syncthreads();
;       {
;         float A = 1.f, B = 0.f;
;         if (d == 0) {
; #pragma unroll
;           for (int tt = 0; tt < 16; ++tt) { int t = qd * 16 + tt; float a = sa[t * 64 + e_], b = sb[t * 64 + e_]; B = a * B + b; A *= a; }
;         } else {
; #pragma unroll
;     ...
;         }
;         part[(0 * 4 + qd) * 64 + e_] = A;
;         part[(1 * 4 + qd) * 64 + e_] = B;
;       }
	v_mfma_f32_16x16x32_bf16 v[20:23], v[232:235], v[12:15], 0
	v_mfma_f32_16x16x32_bf16 v[24:27], v[240:243], v[12:15], 0
	v_mfma_f32_16x16x32_bf16 v[20:23], v[236:239], v[16:19], v[20:23]
	v_mfma_f32_16x16x32_bf16 v[24:27], v[244:247], v[16:19], v[24:27]
	s_nop 7
	s_nop 3
	s_waitcnt lgkmcnt(0)
	v_fmamk_f32 v20, v20, 0xbfb8aa3b, v196
	v_fmamk_f32 v21, v21, 0xbfb8aa3b, v197
	v_fmamk_f32 v24, v24, 0xbfb8aa3b, v200
	v_fmamk_f32 v25, v25, 0xbfb8aa3b, v201
	v_exp_f32_e32 v20, v20
	v_exp_f32_e32 v21, v21
	v_exp_f32_e32 v24, v24
	v_exp_f32_e32 v25, v25
	v_add_f32_e32 v20, 1.0, v20
	v_add_f32_e32 v21, 1.0, v21
	v_add_f32_e32 v24, 1.0, v24
	v_add_f32_e32 v25, 1.0, v25
	v_rcp_f32_e32 v20, v20
	v_rcp_f32_e32 v21, v21
	v_rcp_f32_e32 v24, v24
	v_rcp_f32_e32 v25, v25
	v_pk_mul_f32 v[12:13], v[20:21], v[32:33]
	s_nop 0
	v_pk_add_f32 v[14:15], v[12:13], v[12:13]
	v_mul_f32_e32 v20, 0x3fb8aa3b, v12
	v_mul_f32_e32 v21, 0x3fb8aa3b, v13
	v_exp_f32_e32 v20, v20
	v_exp_f32_e32 v21, v21
	v_fmaak_f32 v16, v14, v205, 0x3d2aaaab
	v_fmaak_f32 v19, v15, v205, 0x3d2aaaab
	v_fmaak_f32 v16, v16, v14, 0x3e2aaaab
	v_fmaak_f32 v19, v19, v15, 0x3e2aaaab
	v_fma_f32 v16, v16, v14, 0.5
	v_fma_f32 v19, v19, v15, 0.5
	v_fma_f32 v16, v16, v14, 1.0
	v_fma_f32 v19, v19, v15, 1.0
	v_mul_f32_e64 v17, v16, -v14
	v_mul_f32_e64 v12, v19, -v15
	v_fma_f32 v16, -v20, v20, 1.0
	v_cmp_lt_f32_e32 vcc, s6, v14
	v_fma_f32 v13, -v21, v21, 1.0
	s_nop 0
	v_cndmask_b32_e32 v16, v16, v17, vcc
	v_cmp_lt_f32_e32 vcc, s6, v15
	v_sqrt_f32_e32 v16, v16
	s_nop 1
	v_cndmask_b32_e32 v17, v13, v12, vcc
	v_sqrt_f32_e32 v17, v17
	s_nop 0
	v_pk_mul_f32 v[24:25], v[24:25], v[16:17]
	s_nop 0
	v_pk_mul_f32 v[24:25], v[28:29], v[24:25]
	v_fmamk_f32 v22, v22, 0xbfb8aa3b, v198
	v_fmamk_f32 v23, v23, 0xbfb8aa3b, v199
	v_fmamk_f32 v26, v26, 0xbfb8aa3b, v202
	v_fmamk_f32 v27, v27, 0xbfb8aa3b, v203
	v_exp_f32_e32 v22, v22
	v_exp_f32_e32 v23, v23
	v_exp_f32_e32 v26, v26
	v_exp_f32_e32 v27, v27
	v_add_f32_e32 v22, 1.0, v22
	v_add_f32_e32 v23, 1.0, v23
	v_add_f32_e32 v26, 1.0, v26
	v_add_f32_e32 v27, 1.0, v27
	v_rcp_f32_e32 v22, v22
	v_rcp_f32_e32 v23, v23
	v_rcp_f32_e32 v26, v26
	v_rcp_f32_e32 v27, v27
	v_pk_mul_f32 v[12:13], v[22:23], v[34:35]
	s_nop 0
	v_pk_add_f32 v[14:15], v[12:13], v[12:13]
	v_mul_f32_e32 v22, 0x3fb8aa3b, v12
	v_mul_f32_e32 v23, 0x3fb8aa3b, v13
	v_exp_f32_e32 v22, v22
	v_exp_f32_e32 v23, v23
	v_fmaak_f32 v16, v14, v205, 0x3d2aaaab
	v_fmaak_f32 v19, v15, v205, 0x3d2aaaab
	v_fmaak_f32 v16, v16, v14, 0x3e2aaaab
	v_fmaak_f32 v19, v19, v15, 0x3e2aaaab
	v_fma_f32 v16, v16, v14, 0.5
	v_fma_f32 v19, v19, v15, 0.5
	v_fma_f32 v16, v16, v14, 1.0
	v_fma_f32 v19, v19, v15, 1.0
	v_mul_f32_e64 v17, v16, -v14
	v_mul_f32_e64 v12, v19, -v15
	v_fma_f32 v16, -v22, v22, 1.0
	v_cmp_lt_f32_e32 vcc, s6, v14
	v_fma_f32 v13, -v23, v23, 1.0
	s_nop 0
	v_cndmask_b32_e32 v16, v16, v17, vcc
	v_cmp_lt_f32_e32 vcc, s6, v15
	v_sqrt_f32_e32 v16, v16
	s_nop 1
	v_cndmask_b32_e32 v17, v13, v12, vcc
	v_sqrt_f32_e32 v17, v17
	s_nop 0
	v_pk_mul_f32 v[26:27], v[26:27], v[16:17]
	s_nop 0
	v_pk_mul_f32 v[26:27], v[30:31], v[26:27]
	ds_write_b128 v204, v[20:23] offset:46592
	ds_write_b128 v204, v[24:27] offset:62976
	s_waitcnt lgkmcnt(0)
	s_barrier
	ds_read2st64_b32 v[12:13], v132 offset0:134 offset1:198
	ds_read2st64_b32 v[14:15], v131 offset0:134 offset1:198
	ds_read2st64_b32 v[16:17], v130 offset0:134 offset1:198
	ds_read2st64_b32 v[62:63], v120 offset0:134 offset1:198
	ds_read2st64_b32 v[164:165], v119 offset0:134 offset1:198
	s_waitcnt lgkmcnt(4)
	v_fmac_f32_e32 v13, 0, v12
	s_waitcnt lgkmcnt(3)
	v_mul_f32_e32 v18, v12, v14
	s_waitcnt lgkmcnt(2)
	v_mul_f32_e32 v20, v18, v16
	ds_read2st64_b32 v[18:19], v129 offset0:134 offset1:198
	v_fmac_f32_e32 v15, v14, v13
	v_fmac_f32_e32 v17, v16, v15
	ds_read2st64_b32 v[166:167], v118 offset0:134 offset1:198
	ds_read2st64_b32 v[168:169], v59 offset0:134 offset1:198
	s_waitcnt lgkmcnt(2)
	v_mul_f32_e32 v22, v20, v18
	ds_read2st64_b32 v[20:21], v128 offset0:134 offset1:198
	v_fmac_f32_e32 v19, v18, v17
	s_waitcnt lgkmcnt(0)
	v_mul_f32_e32 v24, v22, v20
	ds_read2st64_b32 v[22:23], v127 offset0:134 offset1:198
	v_fmac_f32_e32 v21, v20, v19
	s_waitcnt lgkmcnt(0)
	v_mul_f32_e32 v26, v24, v22
	ds_read2st64_b32 v[24:25], v126 offset0:134 offset1:198
	v_fmac_f32_e32 v23, v22, v21
	s_waitcnt lgkmcnt(0)
	v_mul_f32_e32 v28, v26, v24
	ds_read2st64_b32 v[26:27], v125 offset0:134 offset1:198
	v_fmac_f32_e32 v25, v24, v23
	s_waitcnt lgkmcnt(0)
	v_mul_f32_e32 v30, v28, v26
	ds_read2st64_b32 v[28:29], v124 offset0:134 offset1:198
	v_fmac_f32_e32 v27, v26, v25
	s_waitcnt lgkmcnt(0)
	v_mul_f32_e32 v32, v30, v28
	ds_read2st64_b32 v[30:31], v123 offset0:134 offset1:198
	v_fmac_f32_e32 v29, v28, v27
	s_waitcnt lgkmcnt(0)
	v_mul_f32_e32 v34, v32, v30
	ds_read2st64_b32 v[32:33], v122 offset0:134 offset1:198
	v_fmac_f32_e32 v31, v30, v29
	s_waitcnt lgkmcnt(0)
	v_mul_f32_e32 v61, v34, v32
	ds_read2st64_b32 v[34:35], v121 offset0:134 offset1:198
	v_fmac_f32_e32 v33, v32, v31
	s_waitcnt lgkmcnt(0)
	v_mul_f32_e32 v61, v61, v34
	v_mul_f32_e32 v61, v61, v62
	v_fmac_f32_e32 v35, v34, v33
	v_mul_f32_e32 v61, v61, v164
	v_fmac_f32_e32 v63, v62, v35
	v_mul_f32_e32 v61, v61, v166
	v_fmac_f32_e32 v165, v164, v63
	v_mul_f32_e32 v61, v61, v168
	v_fmac_f32_e32 v167, v166, v165
	v_fmac_f32_e32 v169, v168, v167
	ds_write_b32 v98, v61
	ds_write_b32 v100, v169 offset:1024
	s_waitcnt lgkmcnt(0)
	s_barrier
	s_and_saveexec_b64 s[56:57], s[48:49]
	s_cbranch_execnz .LBB0_221
	s_or_b64 exec, exec, s[56:57]
	s_and_saveexec_b64 s[56:57], s[50:51]
	s_cbranch_execnz .LBB0_222

; template <bool FINAL>
; __device__ void phase_lru(const Params& p, int l, unsigned char* smem) {
;   u16* xs = (u16*)smem;
;   float* u32 = (float*)(smem + 8704);
;   u16* ub = (u16*)(smem + 25088);
;   float* sa = (float*)(smem + 34304);
;   float* sb = (float*)(smem + 50688);
;   float* part = (float*)(smem + 67072);
;   const int tid = TIDX(), lane = tid & 63, w = tid >> 6, l15 = lane & 15, g = lane >> 4;
;   const int e_ = tid & 63, qd = tid >> 6;
;   const int NIT = NCHUNK * 8;
;   const int step = gridDim.x;
;   int it = BIDX();
;   uint4 x0 = make_uint4(0, 0, 0, 0), x1 = x0, x2 = x0;
;   auto load_x = [&](int item, uint4& a0, uint4& a1, uint4& a2) {
;     const int ci = item >> 3, nb = item & 7;
;     const int tb = ci * 64, pos0 = tok_pos(tb), S = tok_len(tb);
;     const u16* zb = p.Z + (long)(tb - 2) * DIN + C_LX + nb * 64;
;     { int idx = tid, r = idx >> 3, ch = idx & 7, pp = pos0 - 2 + r;
;       a0 = (pp >= 0 && pp < S) ? *(const uint4*)(zb + (long)r * DIN + ch * 8) : make_uint4(0, 0, 0, 0); }
;     { int idx = tid + 256, r = idx >> 3, ch = idx & 7, pp = pos0 - 2 + r;
;       a1 = (pp >= 0 && pp < S) ? *(const uint4*)(zb + (long)r * DIN + ch * 8) : make_uint4(0, 0, 0, 0); }
;     { int idx = tid + 512, r = idx >> 3, ch = idx & 7, pp = pos0 - 2 + r;
;       a2 = (idx < 67 * 8 && pp >= 0 && pp < S) ? *(const uint4*)(zb + (long)r * DIN + ch * 8) : make_uint4(0, 0, 0, 0); }
;   };
;   if (it < NIT) load_x(it, x0, x1, x2);
;   for (; it < NIT; it += step) {
;     const int ci = it >> 3, nb = it & 7;
;     const int tb = ci * 64;
;     __syncthreads();
;     *(uint4*)(xs + (tid >> 3) * 64 + (tid & 7) * 8) = x0;
;     *(uint4*)(xs + ((tid + 256) >> 3) * 64 + (tid & 7) * 8) = x1;
;     if (tid + 512 < 67 * 8) *(uint4*)(xs + ((tid + 512) >> 3) * 64 + (tid & 7) * 8) = x2;
;     uint4 gz0 = make_uint4(0, 0, 0, 0), gz1 = gz0;
;     float cin0 = 0.f, cin1 = 0.f;
;     if (FINAL) {
;       const u16* gb = p.Z + (size_t)tb * DIN + C_LG + nb * 64 + (tid & 7) * 8;
;       typedef unsigned u4v __attribute__((ext_vector_type(4)));
;       const u4v g0_ = __builtin_nontemporal_load((const u4v*)(gb + (size_t)(tid >> 3) * DIN));
;       const u4v g1_ = __builtin_nontemporal_load((const u4v*)(gb + (size_t)((tid >> 3) + 32) * DIN));
;       gz0 = make_uint4(g0_[0], g0_[1], g0_[2], g0_[3]);
;       gz1 = make_uint4(g1_[0], g1_[1], g1_[2], g1_[3]);
.LBB0_373:
	s_or_b64 exec, exec, s[40:41]
	v_and_b32_e32 v59, 63, v45
	v_and_b32_e32 v12, 0x7fffffc0, v12
	v_ashrrev_i32_e32 v13, 6, v45
	v_lshlrev_b32_e32 v16, 1, v59
	v_lshlrev_b32_e32 v12, 1, v12
	v_lshlrev_b32_e32 v18, 1, v144
	v_and_b32_e32 v60, 15, v45
	v_add_u32_e32 v17, 0, v16
	v_add3_u32 v61, 0, v12, v18
	v_lshlrev_b32_e32 v18, 4, v13
	v_add_u32_e32 v62, v17, v16
	v_or_b32_e32 v16, v18, v60
	v_mul_lo_u32 v19, v16, s28
	v_and_b32_e32 v20, 48, v45
	v_bfe_u32 v14, v45, 4, 2
	v_add3_u32 v46, 0, v19, v20
	v_and_b32_e32 v19, 0x3fffffc0, v45
	s_lshl_b32 s36, s72, 6
	s_and_b32 s30, 0xffff, s42
	v_lshlrev_b32_e32 v44, 3, v14
	v_lshlrev_b32_e32 v63, 2, v14
	v_lshlrev_b32_e32 v14, 2, v45
	v_readlane_b32 s4, v248, 16
	v_lshlrev_b32_e32 v19, 2, v19
	v_lshlrev_b32_e32 v20, 2, v59
	s_cmp_lg_u32 s30, 0
	v_add_u32_e32 v64, s4, v14
	v_add3_u32 v65, s4, v19, v20
	s_movk_i32 s4, 0x70
	s_cselect_b64 s[42:43], -1, 0
	v_mad_u64_u32 v[48:49], s[46:47], v16, s4, v[46:47]
	v_readlane_b32 s4, v248, 17
	s_cmp_lg_u64 s[42:43], 0
	v_mad_i64_i32 v[40:41], s[30:31], v47, s26, 0
	v_mad_i64_i32 v[42:43], s[30:31], v57, s26, 0
	v_add_u32_e32 v97, s4, v14
	v_readlane_b32 s4, v248, 18
	s_addc_u32 s62, s58, 0
	s_lshl_b32 s30, s22, 1
	v_add_u32_e32 v98, s4, v14
	v_readlane_b32 s4, v248, 19
	s_or_b32 s50, s30, 1
	s_ashr_i32 s31, s30, 31
	v_add_u32_e32 v99, s4, v14
	v_readlane_b32 s4, v248, 20
	s_lshl_b32 s44, s22, 10
	s_lshl_b32 s52, s50, 9
	v_add_u32_e32 v100, s4, v14
	v_readlane_b32 s4, v250, 5
	s_lshl_b32 s63, s22, 11
	s_lshl_b32 s64, s22, 9
	s_ashr_i32 s45, s44, 31
	s_ashr_i32 s51, s50, 31
	s_ashr_i32 s53, s52, 31
	s_lshl_b64 s[30:31], s[30:31], 17
	v_readlane_b32 s10, v250, 11
	v_or_b32_e32 v18, 1, v18
	v_readlane_b32 s11, v250, 12
	v_readlane_b32 s16, v250, 17
	v_readlane_b32 s17, v250, 18
	v_readlane_b32 s18, v250, 19
	v_readlane_b32 s19, v250, 20
	s_add_u32 s94, s10, s30
	v_lshlrev_b32_e32 v12, 11, v13
	v_lshlrev_b32_e32 v66, 12, v13
	v_mul_lo_u32 v13, v13, s27
	v_lshlrev_b32_e32 v67, 8, v18
	v_mul_lo_u32 v18, v18, s28
	s_mov_b32 s98, s22
	s_addc_u32 s95, s11, s31
	v_readlane_b32 s16, v250, 37
	s_lshl_b64 s[48:49], s[44:45], 2
	v_readlane_b32 s24, v250, 45
	v_readlane_b32 s25, v250, 46
	s_add_u32 s44, s24, s48
	v_readlane_b32 s28, v250, 49
	s_addc_u32 s45, s25, s49
	v_or_b32_e32 v16, v66, v20
	v_readlane_b32 s29, v250, 50
	s_add_u32 s46, s28, s48
	v_or_b32_e32 v68, 0x200, v66
	v_add_u32_e32 v49, 0, v16
	v_or_b32_e32 v16, v67, v20
	v_readlane_b32 s14, v250, 15
	s_addc_u32 s47, s29, s49
	v_or_b32_e32 v69, 0x300, v66
	v_add_u32_e32 v82, 0, v16
	v_or_b32_e32 v16, v68, v20
	v_readlane_b32 s15, v250, 16
	s_add_u32 s48, s14, s48
	v_or_b32_e32 v70, 0x400, v66
	v_add_u32_e32 v83, 0, v16
	v_or_b32_e32 v16, v69, v20
	s_addc_u32 s49, s15, s49
	s_lshl_b64 s[50:51], s[50:51], 17
	v_or_b32_e32 v71, 0x500, v66
	v_add_u32_e32 v84, 0, v16
	v_or_b32_e32 v16, v70, v20
	s_add_u32 s50, s10, s50
	v_or_b32_e32 v72, 0x600, v66
	v_add_u32_e32 v85, 0, v16
	v_or_b32_e32 v16, v71, v20
	s_addc_u32 s51, s11, s51
	s_lshl_b64 s[56:57], s[52:53], 2
	v_or_b32_e32 v73, 0x700, v66
	v_add_u32_e32 v86, 0, v16
	v_or_b32_e32 v16, v72, v20
	s_add_u32 s52, s24, s56
	v_or_b32_e32 v74, 0x800, v66
	v_add_u32_e32 v87, 0, v16
	v_or_b32_e32 v16, v73, v20
	s_addc_u32 s53, s25, s57
	v_or_b32_e32 v75, 0x900, v66
	v_add_u32_e32 v88, 0, v16
	v_or_b32_e32 v16, v74, v20
	s_add_u32 s54, s28, s56
	v_or_b32_e32 v76, 0xa00, v66
	v_add_u32_e32 v89, 0, v16
	v_or_b32_e32 v16, v75, v20
	s_addc_u32 s55, s29, s57
	v_or_b32_e32 v77, 0xb00, v66
	v_add_u32_e32 v90, 0, v16
	v_or_b32_e32 v16, v76, v20
	s_add_u32 s56, s14, s56
	v_or_b32_e32 v78, 0xc00, v66
	v_add_u32_e32 v91, 0, v16
	v_or_b32_e32 v16, v77, v20
	s_addc_u32 s57, s15, s57
	s_lshl_b32 s65, s62, 6
	v_or_b32_e32 v79, 0xd00, v66
	v_add_u32_e32 v92, 0, v16
	v_or_b32_e32 v16, v78, v20
	s_cmp_lg_u64 s[42:43], 0
	v_cndmask_b32_e64 v15, 0, 1, s[42:43]
	v_or_b32_e32 v80, 0xe00, v66
; template <bool FINAL>
; __device__ void phase_lru(const Params& p, int l, unsigned char* smem) {
;     ...
;           const u16* wr = p.WLRU + ((((size_t)(l * 2 + d) * 2 + 0) * 8 + nb) * 64 + et * 16 + l15) * 64 + g * 8;
;           const u16* wi = p.WLRU + ((((size_t)(l * 2 + d) * 2 + 1) * 8 + nb) * 64 + et * 16 + l15) * 64 + g * 8;
; #pragma unroll
;           for (int ks = 0; ks < 2; ++ks) {
;             ar = mfma16(*(const bf16x8*)(wr + ks * 32), uf[ks], ar);
;             ai = mfma16(*(const bf16x8*)(wi + ks * 32), uf[ks], ai);
;           }
;           const int e0 = et * 16 + 4 * g, ch0 = nb * 64 + e0;
;           const float4 ba4 = *(const float4*)(p.ba + (l * 2 + d) * 512 + ch0);
;           const float4 bx4 = *(const float4*)(p.bx + (l * 2 + d) * 512 + ch0);
;           const float4 sp4 = *(const float4*)(p.SP8 + (l * 2 + d) * 512 + ch0);
	v_add_u32_e32 v93, 0, v16
	v_or_b32_e32 v16, v79, v20
	s_addc_u32 s42, s72, s58
	v_or_b32_e32 v81, 0xf00, v66
	v_add_u32_e32 v94, 0, v16
	v_or_b32_e32 v16, v80, v20
	s_lshl_b32 s66, s42, 3
	v_readfirstlane_b32 s42, v15
	v_add_u32_e32 v95, 0, v16
	v_or_b32_e32 v16, v81, v20
	s_lshl_b32 s68, s58, 6
	s_lshl_b32 s42, s42, 6
	v_cmp_gt_u32_e64 s[40:41], 64, v45
	v_add_u32_e32 v96, 0, v16
	s_lshl_b32 s67, s62, 3
	s_add_i32 s68, s68, s42
	v_add_u32_e32 v101, v17, v12
	v_add_u32_e32 v102, v17, v13
	v_add_u32_e32 v103, v17, v18
	v_readlane_b32 s5, v250, 6
	v_readlane_b32 s6, v250, 7
	v_readlane_b32 s7, v250, 8
	v_readlane_b32 s8, v250, 9
	v_readlane_b32 s9, v250, 10
	v_readlane_b32 s12, v250, 13
	v_readlane_b32 s13, v250, 14
	v_readlane_b32 s17, v250, 38
	v_readlane_b32 s18, v250, 39
	v_readlane_b32 s19, v250, 40
	v_readlane_b32 s20, v250, 41
	v_readlane_b32 s21, v250, 42
	v_readlane_b32 s22, v250, 43
	v_readlane_b32 s23, v250, 44
	v_readlane_b32 s26, v250, 47
	v_readlane_b32 s27, v250, 48
	v_readlane_b32 s30, v250, 51
	v_readlane_b32 s31, v250, 52
	s_and_b32 s32, s36, 0x1c0
	v_lshrrev_b32_e32 v12, 6, v147
	v_and_b32_e32 v22, 15, v147
	v_lshlrev_b32_e32 v13, 4, v12
	v_or_b32_e32 v13, v13, v22
	v_or_b32_e32 v13, s32, v13
	v_lshlrev_b32_e32 v14, 7, v13
	v_mov_b32_e32 v15, v145
	v_bfe_u32 v16, v147, 4, 2
	v_lshlrev_b32_e32 v17, 4, v16
	v_add_u32_e32 v14, v14, v17
	v_lshl_add_u64 v[18:19], s[94:95], 0, v[14:15]
	global_load_dwordx4 v[180:183], v[18:19], off
	global_load_dwordx4 v[184:187], v[18:19], off offset:64
	v_add_co_u32_e32 v20, vcc, 0x10000, v18
	s_nop 0
	v_addc_co_u32_e32 v21, vcc, 0, v19, vcc
	global_load_dwordx4 v[188:191], v[20:21], off
	global_load_dwordx4 v[192:195], v[20:21], off offset:64
	v_lshl_add_u64 v[18:19], s[50:51], 0, v[14:15]
	global_load_dwordx4 v[232:235], v[18:19], off
	global_load_dwordx4 v[236:239], v[18:19], off offset:64
	v_add_co_u32_e32 v20, vcc, 0x10000, v18
	s_nop 0
	v_addc_co_u32_e32 v21, vcc, 0, v19, vcc
	global_load_dwordx4 v[240:243], v[20:21], off
	global_load_dwordx4 v[244:247], v[20:21], off offset:64
	v_mul_u32_u24_e32 v229, 0x90, v22
	v_add_u32_e32 v229, v229, v17
	v_lshlrev_b32_e32 v230, 8, v22
	v_add_u32_e32 v230, v230, v17
	v_lshl_add_u32 v230, v12, 6, v230
	v_lshlrev_b32_e32 v231, 4, v12
	v_lshl_add_u32 v231, v16, 2, v231
	v_or_b32_e32 v231, s32, v231
	v_lshlrev_b32_e32 v231, 2, v231
	v_mov_b32_e32 v205, 0x3c088889
	v_lshl_add_u32 v204, v12, 2, v16
	v_xor_b32_e32 v204, v204, v22
	v_lshlrev_b32_e32 v204, 4, v204
	v_lshl_add_u32 v204, v22, 8, v204
	v_xor_b32_e32 v82, 0x10, v82
	v_xor_b32_e32 v83, 0x20, v83
	v_xor_b32_e32 v84, 0x30, v84
	v_xor_b32_e32 v85, 0x40, v85
	v_xor_b32_e32 v86, 0x50, v86
	v_xor_b32_e32 v87, 0x60, v87
	v_xor_b32_e32 v88, 0x70, v88
	v_xor_b32_e32 v89, 0x80, v89
	v_xor_b32_e32 v90, 0x90, v90
	v_xor_b32_e32 v91, 0xa0, v91
	v_xor_b32_e32 v92, 0xb0, v92
	v_xor_b32_e32 v93, 0xc0, v93
	v_xor_b32_e32 v94, 0xd0, v94
	v_xor_b32_e32 v95, 0xe0, v95
	v_xor_b32_e32 v96, 0xf0, v96
	global_load_dwordx4 v[122:125], v231, s[44:45]
	global_load_dwordx4 v[126:129], v231, s[46:47]
	global_load_dwordx4 v[130:133], v231, s[48:49]
	global_load_dwordx4 v[134:137], v231, s[52:53]
	global_load_dwordx4 v[138:141], v231, s[54:55]
	global_load_dwordx4 v[150:153], v231, s[56:57]
	s_waitcnt vmcnt(0)
	v_mul_f32_e32 v122, 0xbfb8aa3b, v122
	v_mul_f32_e32 v123, 0xbfb8aa3b, v123
	v_mul_f32_e32 v124, 0xbfb8aa3b, v124
	v_mul_f32_e32 v125, 0xbfb8aa3b, v125
	v_mul_f32_e32 v126, 0xbfb8aa3b, v126
	v_mul_f32_e32 v127, 0xbfb8aa3b, v127
	v_mul_f32_e32 v128, 0xbfb8aa3b, v128
	v_mul_f32_e32 v129, 0xbfb8aa3b, v129
	v_mul_f32_e32 v134, 0xbfb8aa3b, v134
	v_mul_f32_e32 v135, 0xbfb8aa3b, v135
	v_mul_f32_e32 v136, 0xbfb8aa3b, v136
	v_mul_f32_e32 v137, 0xbfb8aa3b, v137
	v_mul_f32_e32 v138, 0xbfb8aa3b, v138
	v_mul_f32_e32 v139, 0xbfb8aa3b, v139
	v_mul_f32_e32 v140, 0xbfb8aa3b, v140
	v_mul_f32_e32 v141, 0xbfb8aa3b, v141
	s_branch .LBB0_375

; __device__ __forceinline__ float bf2f(unsigned h) { return __uint_as_float(h << 16); }
; template <bool FINAL>
; __device__ void phase_lru(const Params& p, int l, unsigned char* smem) {
;     ...
;     {
;       const int ch = nb * 64 + e_;
;       const float cw0 = p.conv_w[(l * 4 + 0) * 512 + ch], cw1 = p.conv_w[(l * 4 + 1) * 512 + ch],
;                   cw2 = p.conv_w[(l * 4 + 2) * 512 + ch], cw3 = p.conv_w[(l * 4 + 3) * 512 + ch];
;       const float cb = p.conv_b[l * 512 + ch];
;       float xv[19];
; #pragma unroll
;       for (int k = 0; k < 19; ++k) xv[k] = bf2f(xs[(qd * 16 + k) * 64 + e_]);
; #pragma unroll
;       for (int tt = 0; tt < 16; ++tt) {
;         const int t = qd * 16 + tt;
;         const float u = cb + xv[tt] * cw0 + xv[tt + 1] * cw1 + xv[tt + 2] * cw2 + xv[tt + 3] * cw3;
;         u32[t * 64 + e_] = u;
;         ub[t * 72 + e_] = (u16)f2bf(u);
;       }
;     }
.LBB0_385:
	s_and_b32 s60, s36, 0x1c0
	v_or_b32_e32 v18, s60, v59
	v_or_b32_e32 v12, s63, v18
	v_readlane_b32 s4, v250, 37
	v_ashrrev_i32_e32 v13, 31, v12
	v_readlane_b32 s6, v250, 39
	v_readlane_b32 s7, v250, 40
	v_readlane_b32 s8, v250, 41
	v_readlane_b32 s9, v250, 42
	v_lshl_add_u64 v[14:15], v[12:13], 2, s[6:7]
	v_add_co_u32_e32 v16, vcc, 0x1000, v14
	global_load_dword v13, v[14:15], off
	global_load_dword v12, v[14:15], off offset:2048
	v_addc_co_u32_e32 v17, vcc, 0, v15, vcc
	global_load_dword v15, v[16:17], off
	global_load_dword v14, v[16:17], off offset:2048
	v_or_b32_e32 v16, s64, v18
	v_ashrrev_i32_e32 v17, 31, v16
	v_lshl_add_u64 v[16:17], v[16:17], 2, s[8:9]
	global_load_dword v16, v[16:17], off
	ds_read_u16 v17, v101
	ds_read_u16 v18, v101 offset:128
	ds_read_u16 v19, v101 offset:256
	ds_read_u16 v20, v101 offset:384
	ds_read_u16 v21, v101 offset:512
	ds_read_u16 v22, v101 offset:640
	ds_read_u16 v23, v101 offset:768
	ds_read_u16 v24, v101 offset:896
	s_waitcnt lgkmcnt(7)
	v_lshlrev_b32_e32 v17, 16, v17
	s_waitcnt lgkmcnt(6)
	v_lshlrev_b32_e32 v18, 16, v18
	s_waitcnt lgkmcnt(5)
	v_lshlrev_b32_e32 v19, 16, v19
	s_waitcnt lgkmcnt(4)
	v_lshlrev_b32_e32 v20, 16, v20
	v_add_u32_e32 v50, v62, v66
	ds_read_u16 v25, v101 offset:1024
	ds_read_u16 v26, v101 offset:1152
	ds_read_u16 v27, v101 offset:1280
	ds_read_u16 v28, v101 offset:1408
	ds_read_u16 v29, v101 offset:1536
	ds_read_u16 v30, v101 offset:1664
	ds_read_u16 v31, v101 offset:1792
	ds_read_u16 v32, v101 offset:1920
	ds_read_u16 v33, v101 offset:2048
	ds_read_u16 v34, v101 offset:2176
	ds_read_u16 v35, v101 offset:2304
	s_waitcnt lgkmcnt(14)
	v_lshlrev_b32_e32 v21, 16, v21
	s_waitcnt lgkmcnt(13)
	v_lshlrev_b32_e32 v22, 16, v22
	s_waitcnt lgkmcnt(12)
	v_lshlrev_b32_e32 v23, 16, v23
	s_waitcnt lgkmcnt(11)
	v_lshlrev_b32_e32 v24, 16, v24
	s_waitcnt lgkmcnt(10)
	v_lshlrev_b32_e32 v25, 16, v25
	s_waitcnt lgkmcnt(9)
	v_lshlrev_b32_e32 v26, 16, v26
	s_waitcnt lgkmcnt(8)
	v_lshlrev_b32_e32 v27, 16, v27
	s_waitcnt lgkmcnt(7)
	v_lshlrev_b32_e32 v28, 16, v28
	s_waitcnt lgkmcnt(6)
	v_lshlrev_b32_e32 v29, 16, v29
	s_waitcnt lgkmcnt(5)
	v_lshlrev_b32_e32 v30, 16, v30
	s_waitcnt lgkmcnt(4)
	v_lshlrev_b32_e32 v31, 16, v31
	s_waitcnt lgkmcnt(3)
	v_lshlrev_b32_e32 v32, 16, v32
	s_waitcnt lgkmcnt(2)
	v_lshlrev_b32_e32 v33, 16, v33
	s_ashr_i32 s42, s72, 3
	s_ashr_i32 s43, s42, 31
	s_waitcnt lgkmcnt(1)
	v_lshlrev_b32_e32 v34, 16, v34
	s_lshl_b64 s[42:43], s[42:43], 10
	v_add_u32_e32 v144, s60, v45
	s_waitcnt lgkmcnt(0)
	v_lshlrev_b32_e32 v35, 16, v35
	v_lshlrev_b32_e32 v54, 1, v44
	v_mov_b32_e32 v55, v145
	v_readlane_b32 s5, v250, 38
	s_mov_b64 s[4:5], 0x10000
	v_or_b32_e32 v56, s60, v63
	v_lshlrev_b32_e32 v104, 2, v56
	s_mov_b32 s6, 0xbe800000
	s_mov_b64 s[8:9], 0x10800
	v_readlane_b32 s10, v250, 43
	v_readlane_b32 s11, v250, 44
	v_readlane_b32 s12, v250, 45
	v_readlane_b32 s13, v250, 46
	v_readlane_b32 s14, v250, 47
	v_readlane_b32 s15, v250, 48
	v_readlane_b32 s16, v250, 49
	v_readlane_b32 s17, v250, 50
	v_readlane_b32 s18, v250, 51
	v_readlane_b32 s19, v250, 52
	s_waitcnt vmcnt(0)
	v_fma_f32 v17, v13, v17, v16
	v_fmac_f32_e32 v17, v12, v18
	v_fmac_f32_e32 v17, v15, v19
	v_fmac_f32_e32 v17, v14, v20
	ds_write_b32 v50, v17 offset:8704
	v_cvt_pk_bf16_f32 v17, v17, s0
	ds_write_b16 v102, v17 offset:25088
	v_fma_f32 v17, v13, v18, v16
	v_fmac_f32_e32 v17, v12, v19
	v_fmac_f32_e32 v17, v15, v20
	v_fmac_f32_e32 v17, v14, v21
	v_add_u32_e32 v18, v62, v67
	ds_write_b32 v18, v17 offset:8704
	v_cvt_pk_bf16_f32 v17, v17, s0
	ds_write_b16 v103, v17 offset:25088
	v_fma_f32 v17, v13, v19, v16
	v_fmac_f32_e32 v17, v12, v20
	v_fmac_f32_e32 v17, v15, v21
	v_fmac_f32_e32 v17, v14, v22
	v_add_u32_e32 v18, v62, v68
	ds_write_b32 v18, v17 offset:8704
	v_cvt_pk_bf16_f32 v17, v17, s0
	ds_write_b16 v103, v17 offset:25232
	v_fma_f32 v17, v13, v20, v16
	v_fmac_f32_e32 v17, v12, v21
	v_fmac_f32_e32 v17, v15, v22
	v_fmac_f32_e32 v17, v14, v23
	v_add_u32_e32 v18, v62, v69
	ds_write_b32 v18, v17 offset:8704
	v_cvt_pk_bf16_f32 v17, v17, s0
	ds_write_b16 v103, v17 offset:25376
	v_fma_f32 v17, v13, v21, v16
	v_fmac_f32_e32 v17, v12, v22
	v_fmac_f32_e32 v17, v15, v23
	v_fmac_f32_e32 v17, v14, v24
	v_add_u32_e32 v18, v62, v70
	ds_write_b32 v18, v17 offset:8704
	v_cvt_pk_bf16_f32 v17, v17, s0
	ds_write_b16 v103, v17 offset:25520
	v_fma_f32 v17, v13, v22, v16
	v_fmac_f32_e32 v17, v12, v23
	v_fmac_f32_e32 v17, v15, v24
	v_fmac_f32_e32 v17, v14, v25
	v_add_u32_e32 v18, v62, v71
	ds_write_b32 v18, v17 offset:8704
	v_cvt_pk_bf16_f32 v17, v17, s0
	ds_write_b16 v103, v17 offset:25664
	v_fma_f32 v17, v13, v23, v16
	v_fmac_f32_e32 v17, v12, v24
	v_fmac_f32_e32 v17, v15, v25
	v_fmac_f32_e32 v17, v14, v26
	v_add_u32_e32 v18, v62, v72
	ds_write_b32 v18, v17 offset:8704
	v_cvt_pk_bf16_f32 v17, v17, s0
	ds_write_b16 v103, v17 offset:25808
	v_fma_f32 v17, v13, v24, v16
	v_fmac_f32_e32 v17, v12, v25
	v_fmac_f32_e32 v17, v15, v26
	v_fmac_f32_e32 v17, v14, v27
	v_add_u32_e32 v18, v62, v73
	ds_write_b32 v18, v17 offset:8704
	v_cvt_pk_bf16_f32 v17, v17, s0
	ds_write_b16 v103, v17 offset:25952
	v_fma_f32 v17, v13, v25, v16
	v_fmac_f32_e32 v17, v12, v26
	v_fmac_f32_e32 v17, v15, v27
	v_fmac_f32_e32 v17, v14, v28
	v_add_u32_e32 v18, v62, v74
	ds_write_b32 v18, v17 offset:8704
	v_cvt_pk_bf16_f32 v17, v17, s0
	ds_write_b16 v103, v17 offset:26096
	v_fma_f32 v17, v13, v26, v16
	v_fmac_f32_e32 v17, v12, v27
	v_fmac_f32_e32 v17, v15, v28
	v_fmac_f32_e32 v17, v14, v29
	v_add_u32_e32 v18, v62, v75
	ds_write_b32 v18, v17 offset:8704
	v_cvt_pk_bf16_f32 v17, v17, s0
	ds_write_b16 v103, v17 offset:26240
	v_fma_f32 v17, v13, v27, v16
	v_fmac_f32_e32 v17, v12, v28
; template <bool FINAL>
; __device__ void phase_lru(const Params& p, int l, unsigned char* smem) {
;     ...
;       for (int tt = 0; tt < 16; ++tt) {
;         const int t = qd * 16 + tt;
;         const float u = cb + xv[tt] * cw0 + xv[tt + 1] * cw1 + xv[tt + 2] * cw2 + xv[tt + 3] * cw3;
;         u32[t * 64 + e_] = u;
;         ub[t * 72 + e_] = (u16)f2bf(u);
;       }
;     }
;     __syncthreads();
;     if (FINAL) {
;       *(uint4*)(xs + (tid >> 3) * 64 + (tid & 7) * 8) = gz0;
;       *(uint4*)(xs + ((tid >> 3) + 32) * 64 + (tid & 7) * 8) = gz1;
;     }
;     float hsum[16];
; #pragma unroll
;     for (int tt = 0; tt < 16; ++tt) hsum[tt] = 0.f;
; #pragma unroll
;     for (int d = 0; d < 2; ++d) {
;       {
;         bf16x8 uf[2];
;         uf[0] = *(const bf16x8*)(ub + (16 * w + l15) * 72 + g * 8);
;         uf[1] = *(const bf16x8*)(ub + (16 * w + l15) * 72 + 32 + g * 8);
;         const int t = 16 * w + l15;
; #pragma unroll
;         for (int et = 0; et < 4; ++et) {
;           f32x4 ar = {0.f, 0.f, 0.f, 0.f}, ai = {0.f, 0.f, 0.f, 0.f};
;           const u16* wr = p.WLRU + ((((size_t)(l * 2 + d) * 2 + 0) * 8 + nb) * 64 + et * 16 + l15) * 64 + g * 8;
;           const u16* wi = p.WLRU + ((((size_t)(l * 2 + d) * 2 + 1) * 8 + nb) * 64 + et * 16 + l15) * 64 + g * 8;
; #pragma unroll
;           for (int ks = 0; ks < 2; ++ks) {
;             ar = mfma16(*(const bf16x8*)(wr + ks * 32), uf[ks], ar);
;             ai = mfma16(*(const bf16x8*)(wi + ks * 32), uf[ks], ai);
;           }
;           const int e0 = et * 16 + 4 * g, ch0 = nb * 64 + e0;
;           const float4 ba4 = *(const float4*)(p.ba + (l * 2 + d) * 512 + ch0);
;           const float4 bx4 = *(const float4*)(p.bx + (l * 2 + d) * 512 + ch0);
;           const float4 sp4 = *(const float4*)(p.SP8 + (l * 2 + d) * 512 + ch0);
;           const float4 uu = *(const float4*)(u32 + t * 64 + e0);
;           const float* bap = (const float*)&ba4; const float* bxp = (const float*)&bx4;
;           const float* spp = (const float*)&sp4; const float* uup = (const float*)&uu;
;           f32x4 av, bv;
; #pragma unroll
;           for (int j = 0; j < 4; ++j) {
;             float r = sigmoidf_(ar[j] + bap[j]);
;             float ig = sigmoidf_(ai[j] + bxp[j]);
;             float la = spp[j] * r;
;             float av_ = __expf(la);
;             float t2 = 2.0f * la;
	v_fmac_f32_e32 v17, v15, v29
	v_fmac_f32_e32 v17, v14, v30
	v_add_u32_e32 v18, v62, v76
	ds_write_b32 v18, v17 offset:8704
	v_cvt_pk_bf16_f32 v17, v17, s0
	ds_write_b16 v103, v17 offset:26384
	v_fma_f32 v17, v13, v28, v16
	v_fmac_f32_e32 v17, v12, v29
	v_fmac_f32_e32 v17, v15, v30
	v_fmac_f32_e32 v17, v14, v31
	v_add_u32_e32 v18, v62, v77
	ds_write_b32 v18, v17 offset:8704
	v_cvt_pk_bf16_f32 v17, v17, s0
	ds_write_b16 v103, v17 offset:26528
	v_fma_f32 v17, v13, v29, v16
	v_fmac_f32_e32 v17, v12, v30
	v_fmac_f32_e32 v17, v15, v31
	v_fmac_f32_e32 v17, v14, v32
	v_add_u32_e32 v18, v62, v78
	ds_write_b32 v18, v17 offset:8704
	v_cvt_pk_bf16_f32 v17, v17, s0
	ds_write_b16 v103, v17 offset:26672
	v_fma_f32 v17, v13, v30, v16
	v_fmac_f32_e32 v17, v12, v31
	v_fmac_f32_e32 v17, v15, v32
	v_fmac_f32_e32 v17, v14, v33
	v_add_u32_e32 v18, v62, v79
	ds_write_b32 v18, v17 offset:8704
	v_cvt_pk_bf16_f32 v17, v17, s0
	ds_write_b16 v103, v17 offset:26816
	v_fma_f32 v17, v13, v31, v16
	v_fmac_f32_e32 v16, v13, v32
	v_fmac_f32_e32 v17, v12, v32
	v_fmac_f32_e32 v16, v12, v33
	v_or_b32_e32 v20, s60, v60
	v_fmac_f32_e32 v17, v15, v33
	v_fmac_f32_e32 v16, v15, v34
	v_lshl_add_u64 v[50:51], v[144:145], 0, s[42:43]
	v_lshlrev_b32_e32 v144, 7, v20
	v_fmac_f32_e32 v17, v14, v34
	v_add_u32_e32 v18, v62, v80
	v_fmac_f32_e32 v16, v14, v35
	v_add_u32_e32 v12, v62, v81
	v_lshl_add_u64 v[20:21], s[94:95], 0, v[144:145]
	ds_write_b32 v18, v17 offset:8704
	v_cvt_pk_bf16_f32 v17, v17, s0
	ds_write_b32 v12, v16 offset:8704
	v_cvt_pk_bf16_f32 v12, v16, s0
	v_lshl_add_u64 v[28:29], v[20:21], 0, v[54:55]
	ds_write_b16 v103, v17 offset:26960
	ds_write_b16 v103, v12 offset:27104
	s_waitcnt lgkmcnt(0)
	s_barrier
	s_mov_b32 s5, 0x3e4ccccd
	ds_read_b128 v[12:15], v229 offset:25088
	ds_read_b128 v[16:19], v229 offset:25152
	ds_read_b128 v[28:31], v230 offset:8704
	s_waitcnt lgkmcnt(1)
	v_mfma_f32_16x16x32_bf16 v[20:23], v[180:183], v[12:15], 0
	v_mfma_f32_16x16x32_bf16 v[24:27], v[188:191], v[12:15], 0
	v_mfma_f32_16x16x32_bf16 v[20:23], v[184:187], v[16:19], v[20:23]
	v_mfma_f32_16x16x32_bf16 v[24:27], v[192:195], v[16:19], v[24:27]
	s_nop 7
	s_nop 3
	s_waitcnt lgkmcnt(0)
	v_fmamk_f32 v20, v20, 0xbfb8aa3b, v122
	v_fmamk_f32 v21, v21, 0xbfb8aa3b, v123
	v_fmamk_f32 v24, v24, 0xbfb8aa3b, v126
	v_fmamk_f32 v25, v25, 0xbfb8aa3b, v127
	v_exp_f32_e32 v20, v20
	v_exp_f32_e32 v21, v21
	v_exp_f32_e32 v24, v24
	v_exp_f32_e32 v25, v25
	v_add_f32_e32 v20, 1.0, v20
	v_add_f32_e32 v21, 1.0, v21
	v_add_f32_e32 v24, 1.0, v24
	v_add_f32_e32 v25, 1.0, v25
	v_rcp_f32_e32 v20, v20
	v_rcp_f32_e32 v21, v21
	v_rcp_f32_e32 v24, v24
	v_rcp_f32_e32 v25, v25
	v_pk_mul_f32 v[12:13], v[20:21], v[130:131]
	s_nop 0
	v_pk_add_f32 v[14:15], v[12:13], v[12:13]
	v_mul_f32_e32 v20, 0x3fb8aa3b, v12
	v_mul_f32_e32 v21, 0x3fb8aa3b, v13
	v_exp_f32_e32 v20, v20
	v_exp_f32_e32 v21, v21
	v_fmaak_f32 v16, v14, v205, 0x3d2aaaab
	v_fmaak_f32 v19, v15, v205, 0x3d2aaaab
	v_fmaak_f32 v16, v16, v14, 0x3e2aaaab
	v_fmaak_f32 v19, v19, v15, 0x3e2aaaab
	v_fma_f32 v16, v16, v14, 0.5
	v_fma_f32 v19, v19, v15, 0.5
	v_fma_f32 v16, v16, v14, 1.0
	v_fma_f32 v19, v19, v15, 1.0
	v_mul_f32_e64 v17, v16, -v14
	v_mul_f32_e64 v12, v19, -v15
	v_fma_f32 v16, -v20, v20, 1.0
	v_cmp_lt_f32_e32 vcc, s6, v14
	v_fma_f32 v13, -v21, v21, 1.0
	s_nop 0
	v_cndmask_b32_e32 v16, v16, v17, vcc
	v_cmp_lt_f32_e32 vcc, s6, v15
	v_sqrt_f32_e32 v16, v16
	s_nop 1
	v_cndmask_b32_e32 v17, v13, v12, vcc
	v_sqrt_f32_e32 v17, v17
	s_nop 0
	v_pk_mul_f32 v[24:25], v[24:25], v[16:17]
	s_nop 0
	v_pk_mul_f32 v[24:25], v[28:29], v[24:25]
	v_fmamk_f32 v22, v22, 0xbfb8aa3b, v124
	v_fmamk_f32 v23, v23, 0xbfb8aa3b, v125
	v_fmamk_f32 v26, v26, 0xbfb8aa3b, v128
	v_fmamk_f32 v27, v27, 0xbfb8aa3b, v129
	v_exp_f32_e32 v22, v22
	v_exp_f32_e32 v23, v23
	v_exp_f32_e32 v26, v26
	v_exp_f32_e32 v27, v27
	v_add_f32_e32 v22, 1.0, v22
	v_add_f32_e32 v23, 1.0, v23
	v_add_f32_e32 v26, 1.0, v26
	v_add_f32_e32 v27, 1.0, v27
	v_rcp_f32_e32 v22, v22
	v_rcp_f32_e32 v23, v23
	v_rcp_f32_e32 v26, v26
	v_rcp_f32_e32 v27, v27
	v_pk_mul_f32 v[12:13], v[22:23], v[132:133]
	s_nop 0
	v_pk_add_f32 v[14:15], v[12:13], v[12:13]
	v_mul_f32_e32 v22, 0x3fb8aa3b, v12
	v_mul_f32_e32 v23, 0x3fb8aa3b, v13
	v_exp_f32_e32 v22, v22
	v_exp_f32_e32 v23, v23
	v_fmaak_f32 v16, v14, v205, 0x3d2aaaab
	v_fmaak_f32 v19, v15, v205, 0x3d2aaaab
	v_fmaak_f32 v16, v16, v14, 0x3e2aaaab
	v_fmaak_f32 v19, v19, v15, 0x3e2aaaab
	v_fma_f32 v16, v16, v14, 0.5
	v_fma_f32 v19, v19, v15, 0.5
	v_fma_f32 v16, v16, v14, 1.0
	v_fma_f32 v19, v19, v15, 1.0
	v_mul_f32_e64 v17, v16, -v14
	v_mul_f32_e64 v12, v19, -v15
	v_fma_f32 v16, -v22, v22, 1.0
	v_cmp_lt_f32_e32 vcc, s6, v14
	v_fma_f32 v13, -v23, v23, 1.0
	s_nop 0
	v_cndmask_b32_e32 v16, v16, v17, vcc
	v_cmp_lt_f32_e32 vcc, s6, v15
	v_sqrt_f32_e32 v16, v16
	s_nop 1
	v_cndmask_b32_e32 v17, v13, v12, vcc
	v_sqrt_f32_e32 v17, v17
	s_nop 0
	v_pk_mul_f32 v[26:27], v[26:27], v[16:17]
	s_nop 0
	v_pk_mul_f32 v[26:27], v[30:31], v[26:27]
	ds_write_b128 v204, v[20:23] offset:34304
	ds_write_b128 v204, v[24:27] offset:50688
	ds_read_b128 v[12:15], v229 offset:27392
	ds_read_b128 v[16:19], v229 offset:27456
	ds_read_b128 v[28:31], v230 offset:12800
	s_waitcnt lgkmcnt(1)
	v_mfma_f32_16x16x32_bf16 v[20:23], v[180:183], v[12:15], 0
	v_mfma_f32_16x16x32_bf16 v[24:27], v[188:191], v[12:15], 0
	v_mfma_f32_16x16x32_bf16 v[20:23], v[184:187], v[16:19], v[20:23]
	v_mfma_f32_16x16x32_bf16 v[24:27], v[192:195], v[16:19], v[24:27]
	s_nop 7
	s_nop 3
	s_waitcnt lgkmcnt(0)
; __device__ __forceinline__ float sigmoidf_(float x) { return __builtin_amdgcn_rcpf(1.0f + __expf(-x)); }
; template <bool FINAL>
; __device__ void phase_lru(const Params& p, int l, unsigned char* smem) {
;     ...
;           const int e0 = et * 16 + 4 * g, ch0 = nb * 64 + e0;
;           const float4 ba4 = *(const float4*)(p.ba + (l * 2 + d) * 512 + ch0);
;           const float4 bx4 = *(const float4*)(p.bx + (l * 2 + d) * 512 + ch0);
;           const float4 sp4 = *(const float4*)(p.SP8 + (l * 2 + d) * 512 + ch0);
;           const float4 uu = *(const float4*)(u32 + t * 64 + e0);
;           const float* bap = (const float*)&ba4; const float* bxp = (const float*)&bx4;
;           const float* spp = (const float*)&sp4; const float* uup = (const float*)&uu;
;           f32x4 av, bv;
; #pragma unroll
;           for (int j = 0; j < 4; ++j) {
;             float r = sigmoidf_(ar[j] + bap[j]);
;             float ig = sigmoidf_(ai[j] + bxp[j]);
;             float la = spp[j] * r;
;             float av_ = __expf(la);
;             float t2 = 2.0f * la;
;             float ser = -t2 * (1.f + t2 * 0.5f * (1.f + t2 * (1.f / 3.f) * (1.f + t2 * 0.25f * (1.f + t2 * 0.2f))));
;             float om = (t2 > -0.25f) ? ser : (1.0f - av_ * av_);
;             av[j] = av_;
;             bv[j] = __builtin_amdgcn_sqrtf(om) * ig * uup[j];
;           }
;           *(f32x4*)(sa + t * 64 + e0) = av;
;           *(f32x4*)(sb + t * 64 + e0) = bv;
;         }
	v_fmamk_f32 v20, v20, 0xbfb8aa3b, v122
	v_fmamk_f32 v21, v21, 0xbfb8aa3b, v123
	v_fmamk_f32 v24, v24, 0xbfb8aa3b, v126
	v_fmamk_f32 v25, v25, 0xbfb8aa3b, v127
	v_exp_f32_e32 v20, v20
	v_exp_f32_e32 v21, v21
	v_exp_f32_e32 v24, v24
	v_exp_f32_e32 v25, v25
	v_add_f32_e32 v20, 1.0, v20
	v_add_f32_e32 v21, 1.0, v21
	v_add_f32_e32 v24, 1.0, v24
	v_add_f32_e32 v25, 1.0, v25
	v_rcp_f32_e32 v20, v20
	v_rcp_f32_e32 v21, v21
	v_rcp_f32_e32 v24, v24
	v_rcp_f32_e32 v25, v25
	v_pk_mul_f32 v[12:13], v[20:21], v[130:131]
	s_nop 0
	v_pk_add_f32 v[14:15], v[12:13], v[12:13]
	v_mul_f32_e32 v20, 0x3fb8aa3b, v12
	v_mul_f32_e32 v21, 0x3fb8aa3b, v13
	v_exp_f32_e32 v20, v20
	v_exp_f32_e32 v21, v21
	v_fmaak_f32 v16, v14, v205, 0x3d2aaaab
	v_fmaak_f32 v19, v15, v205, 0x3d2aaaab
	v_fmaak_f32 v16, v16, v14, 0x3e2aaaab
	v_fmaak_f32 v19, v19, v15, 0x3e2aaaab
	v_fma_f32 v16, v16, v14, 0.5
	v_fma_f32 v19, v19, v15, 0.5
	v_fma_f32 v16, v16, v14, 1.0
	v_fma_f32 v19, v19, v15, 1.0
	v_mul_f32_e64 v17, v16, -v14
	v_mul_f32_e64 v12, v19, -v15
	v_fma_f32 v16, -v20, v20, 1.0
	v_cmp_lt_f32_e32 vcc, s6, v14
	v_fma_f32 v13, -v21, v21, 1.0
	s_nop 0
	v_cndmask_b32_e32 v16, v16, v17, vcc
	v_cmp_lt_f32_e32 vcc, s6, v15
	v_sqrt_f32_e32 v16, v16
	s_nop 1
	v_cndmask_b32_e32 v17, v13, v12, vcc
	v_sqrt_f32_e32 v17, v17
	s_nop 0
	v_pk_mul_f32 v[24:25], v[24:25], v[16:17]
	s_nop 0
	v_pk_mul_f32 v[24:25], v[28:29], v[24:25]
	v_fmamk_f32 v22, v22, 0xbfb8aa3b, v124
	v_fmamk_f32 v23, v23, 0xbfb8aa3b, v125
	v_fmamk_f32 v26, v26, 0xbfb8aa3b, v128
	v_fmamk_f32 v27, v27, 0xbfb8aa3b, v129
	v_exp_f32_e32 v22, v22
	v_exp_f32_e32 v23, v23
	v_exp_f32_e32 v26, v26
	v_exp_f32_e32 v27, v27
	v_add_f32_e32 v22, 1.0, v22
	v_add_f32_e32 v23, 1.0, v23
	v_add_f32_e32 v26, 1.0, v26
	v_add_f32_e32 v27, 1.0, v27
	v_rcp_f32_e32 v22, v22
	v_rcp_f32_e32 v23, v23
	v_rcp_f32_e32 v26, v26
	v_rcp_f32_e32 v27, v27
	v_pk_mul_f32 v[12:13], v[22:23], v[132:133]
	s_nop 0
	v_pk_add_f32 v[14:15], v[12:13], v[12:13]
	v_mul_f32_e32 v22, 0x3fb8aa3b, v12
	v_mul_f32_e32 v23, 0x3fb8aa3b, v13
	v_exp_f32_e32 v22, v22
	v_exp_f32_e32 v23, v23
	v_fmaak_f32 v16, v14, v205, 0x3d2aaaab
	v_fmaak_f32 v19, v15, v205, 0x3d2aaaab
	v_fmaak_f32 v16, v16, v14, 0x3e2aaaab
	v_fmaak_f32 v19, v19, v15, 0x3e2aaaab
	v_fma_f32 v16, v16, v14, 0.5
	v_fma_f32 v19, v19, v15, 0.5
	v_fma_f32 v16, v16, v14, 1.0
	v_fma_f32 v19, v19, v15, 1.0
	v_mul_f32_e64 v17, v16, -v14
	v_mul_f32_e64 v12, v19, -v15
	v_fma_f32 v16, -v22, v22, 1.0
	v_cmp_lt_f32_e32 vcc, s6, v14
	v_fma_f32 v13, -v23, v23, 1.0
	s_nop 0
	v_cndmask_b32_e32 v16, v16, v17, vcc
	v_cmp_lt_f32_e32 vcc, s6, v15
	v_sqrt_f32_e32 v16, v16
	s_nop 1
	v_cndmask_b32_e32 v17, v13, v12, vcc
	v_sqrt_f32_e32 v17, v17
	s_nop 0
	v_pk_mul_f32 v[26:27], v[26:27], v[16:17]
	s_nop 0
	v_pk_mul_f32 v[26:27], v[30:31], v[26:27]
	ds_write_b128 v204, v[20:23] offset:38400
	ds_write_b128 v204, v[24:27] offset:54784
	ds_read_b128 v[12:15], v229 offset:29696
	ds_read_b128 v[16:19], v229 offset:29760
	ds_read_b128 v[28:31], v230 offset:16896
	s_waitcnt lgkmcnt(1)
	v_mfma_f32_16x16x32_bf16 v[20:23], v[180:183], v[12:15], 0
	v_mfma_f32_16x16x32_bf16 v[24:27], v[188:191], v[12:15], 0
	v_mfma_f32_16x16x32_bf16 v[20:23], v[184:187], v[16:19], v[20:23]
	v_mfma_f32_16x16x32_bf16 v[24:27], v[192:195], v[16:19], v[24:27]
	s_nop 7
	s_nop 3
	s_waitcnt lgkmcnt(0)
	v_fmamk_f32 v20, v20, 0xbfb8aa3b, v122
	v_fmamk_f32 v21, v21, 0xbfb8aa3b, v123
	v_fmamk_f32 v24, v24, 0xbfb8aa3b, v126
	v_fmamk_f32 v25, v25, 0xbfb8aa3b, v127
	v_exp_f32_e32 v20, v20
	v_exp_f32_e32 v21, v21
	v_exp_f32_e32 v24, v24
	v_exp_f32_e32 v25, v25
	v_add_f32_e32 v20, 1.0, v20
	v_add_f32_e32 v21, 1.0, v21
	v_add_f32_e32 v24, 1.0, v24
	v_add_f32_e32 v25, 1.0, v25
	v_rcp_f32_e32 v20, v20
	v_rcp_f32_e32 v21, v21
	v_rcp_f32_e32 v24, v24
	v_rcp_f32_e32 v25, v25
	v_pk_mul_f32 v[12:13], v[20:21], v[130:131]
	s_nop 0
	v_pk_add_f32 v[14:15], v[12:13], v[12:13]
	v_mul_f32_e32 v20, 0x3fb8aa3b, v12
	v_mul_f32_e32 v21, 0x3fb8aa3b, v13
	v_exp_f32_e32 v20, v20
	v_exp_f32_e32 v21, v21
	v_fmaak_f32 v16, v14, v205, 0x3d2aaaab
	v_fmaak_f32 v19, v15, v205, 0x3d2aaaab
	v_fmaak_f32 v16, v16, v14, 0x3e2aaaab
	v_fmaak_f32 v19, v19, v15, 0x3e2aaaab
	v_fma_f32 v16, v16, v14, 0.5
	v_fma_f32 v19, v19, v15, 0.5
	v_fma_f32 v16, v16, v14, 1.0
	v_fma_f32 v19, v19, v15, 1.0
	v_mul_f32_e64 v17, v16, -v14
	v_mul_f32_e64 v12, v19, -v15
	v_fma_f32 v16, -v20, v20, 1.0
	v_cmp_lt_f32_e32 vcc, s6, v14
	v_fma_f32 v13, -v21, v21, 1.0
	s_nop 0
	v_cndmask_b32_e32 v16, v16, v17, vcc
	v_cmp_lt_f32_e32 vcc, s6, v15
	v_sqrt_f32_e32 v16, v16
	s_nop 1
	v_cndmask_b32_e32 v17, v13, v12, vcc
	v_sqrt_f32_e32 v17, v17
	s_nop 0
	v_pk_mul_f32 v[24:25], v[24:25], v[16:17]
	s_nop 0
	v_pk_mul_f32 v[24:25], v[28:29], v[24:25]
	v_fmamk_f32 v22, v22, 0xbfb8aa3b, v124
	v_fmamk_f32 v23, v23, 0xbfb8aa3b, v125
	v_fmamk_f32 v26, v26, 0xbfb8aa3b, v128
	v_fmamk_f32 v27, v27, 0xbfb8aa3b, v129
	v_exp_f32_e32 v22, v22
	v_exp_f32_e32 v23, v23
	v_exp_f32_e32 v26, v26
	v_exp_f32_e32 v27, v27
	v_add_f32_e32 v22, 1.0, v22
	v_add_f32_e32 v23, 1.0, v23
	v_add_f32_e32 v26, 1.0, v26
	v_add_f32_e32 v27, 1.0, v27
	v_rcp_f32_e32 v22, v22
	v_rcp_f32_e32 v23, v23
	v_rcp_f32_e32 v26, v26
	v_rcp_f32_e32 v27, v27
	v_pk_mul_f32 v[12:13], v[22:23], v[132:133]
	s_nop 0
	v_pk_add_f32 v[14:15], v[12:13], v[12:13]
	v_mul_f32_e32 v22, 0x3fb8aa3b, v12
	v_mul_f32_e32 v23, 0x3fb8aa3b, v13
	v_exp_f32_e32 v22, v22
	v_exp_f32_e32 v23, v23
	v_fmaak_f32 v16, v14, v205, 0x3d2aaaab
	v_fmaak_f32 v19, v15, v205, 0x3d2aaaab
	v_fmaak_f32 v16, v16, v14, 0x3e2aaaab
	v_fmaak_f32 v19, v19, v15, 0x3e2aaaab
	v_fma_f32 v16, v16, v14, 0.5
	v_fma_f32 v19, v19, v15, 0.5
	v_fma_f32 v16, v16, v14, 1.0
	v_fma_f32 v19, v19, v15, 1.0
	v_mul_f32_e64 v17, v16, -v14
	v_mul_f32_e64 v12, v19, -v15
	v_fma_f32 v16, -v22, v22, 1.0
	v_cmp_lt_f32_e32 vcc, s6, v14
	v_fma_f32 v13, -v23, v23, 1.0
	s_nop 0
	v_cndmask_b32_e32 v16, v16, v17, vcc
	v_cmp_lt_f32_e32 vcc, s6, v15
	v_sqrt_f32_e32 v16, v16
	s_nop 1
	v_cndmask_b32_e32 v17, v13, v12, vcc
	v_sqrt_f32_e32 v17, v17
	s_nop 0
	v_pk_mul_f32 v[26:27], v[26:27], v[16:17]
	s_nop 0
	v_pk_mul_f32 v[26:27], v[30:31], v[26:27]
	ds_write_b128 v204, v[20:23] offset:42496
	ds_write_b128 v204, v[24:27] offset:58880
	ds_read_b128 v[12:15], v229 offset:32000
	ds_read_b128 v[16:19], v229 offset:32064
	ds_read_b128 v[28:31], v230 offset:20992
	s_waitcnt lgkmcnt(1)
; template <bool FINAL>
; __device__ void phase_lru(const Params& p, int l, unsigned char* smem) {
;     ...
;           const int e0 = et * 16 + 4 * g, ch0 = nb * 64 + e0;
;           const float4 ba4 = *(const float4*)(p.ba + (l * 2 + d) * 512 + ch0);
;           const float4 bx4 = *(const float4*)(p.bx + (l * 2 + d) * 512 + ch0);
;           const float4 sp4 = *(const float4*)(p.SP8 + (l * 2 + d) * 512 + ch0);
;           const float4 uu = *(const float4*)(u32 + t * 64 + e0);
;           const float* bap = (const float*)&ba4; const float* bxp = (const float*)&bx4;
;           const float* spp = (const float*)&sp4; const float* uup = (const float*)&uu;
;           f32x4 av, bv;
; #pragma unroll
;           for (int j = 0; j < 4; ++j) {
;             float r = sigmoidf_(ar[j] + bap[j]);
;             float ig = sigmoidf_(ai[j] + bxp[j]);
;             float la = spp[j] * r;
;             float av_ = __expf(la);
;             float t2 = 2.0f * la;
;             float ser = -t2 * (1.f + t2 * 0.5f * (1.f + t2 * (1.f / 3.f) * (1.f + t2 * 0.25f * (1.f + t2 * 0.2f))));
;             float om = (t2 > -0.25f) ? ser : (1.0f - av_ * av_);
;             av[j] = av_;
;             bv[j] = __builtin_amdgcn_sqrtf(om) * ig * uup[j];
;           }
;           *(f32x4*)(sa + t * 64 + e0) = av;
;           *(f32x4*)(sb + t * 64 + e0) = bv;
;         }
;       }
;       __syncthreads();
;       {
;         float A = 1.f, B = 0.f;
;         if (d == 0) {
; #pragma unroll
;           for (int tt = 0; tt < 16; ++tt) { int t = qd * 16 + tt; float a = sa[t * 64 + e_], b = sb[t * 64 + e_]; B = a * B + b; A *= a; }
;         } else {
; #pragma unroll
;     ...
;         }
;         part[(0 * 4 + qd) * 64 + e_] = A;
;         part[(1 * 4 + qd) * 64 + e_] = B;
;       }
;       __syncthreads();
;       if (!FINAL) {
;         if (qd == 0) {
;           float A = 1.f, B = 0.f;
;           if (d == 0) {
; #pragma unroll
;             for (int q = 0; q < 4; ++q) { float aq = part[q * 64 + e_], bq = part[(4 + q) * 64 + e_]; B = aq * B + bq; A *= aq; }
;           } else {
; #pragma unroll
;             for (int q = 3; q >= 0; --q) { float aq = part[q * 64 + e_], bq = part[(4 + q) * 64 + e_]; B = aq * B + bq; A *= aq; }
;           }
;           const size_t cidx = ((size_t)ci * 2 + d) * 512 + nb * 64 + e_;
;           p.CA[cidx] = A; p.CB[cidx] = B;
;         }
	v_mfma_f32_16x16x32_bf16 v[20:23], v[180:183], v[12:15], 0
	v_mfma_f32_16x16x32_bf16 v[24:27], v[188:191], v[12:15], 0
	v_mfma_f32_16x16x32_bf16 v[20:23], v[184:187], v[16:19], v[20:23]
	v_mfma_f32_16x16x32_bf16 v[24:27], v[192:195], v[16:19], v[24:27]
	s_nop 7
	s_nop 3
	s_waitcnt lgkmcnt(0)
	v_fmamk_f32 v20, v20, 0xbfb8aa3b, v122
	v_fmamk_f32 v21, v21, 0xbfb8aa3b, v123
	v_fmamk_f32 v24, v24, 0xbfb8aa3b, v126
	v_fmamk_f32 v25, v25, 0xbfb8aa3b, v127
	v_exp_f32_e32 v20, v20
	v_exp_f32_e32 v21, v21
	v_exp_f32_e32 v24, v24
	v_exp_f32_e32 v25, v25
	v_add_f32_e32 v20, 1.0, v20
	v_add_f32_e32 v21, 1.0, v21
	v_add_f32_e32 v24, 1.0, v24
	v_add_f32_e32 v25, 1.0, v25
	v_rcp_f32_e32 v20, v20
	v_rcp_f32_e32 v21, v21
	v_rcp_f32_e32 v24, v24
	v_rcp_f32_e32 v25, v25
	v_pk_mul_f32 v[12:13], v[20:21], v[130:131]
	s_nop 0
	v_pk_add_f32 v[14:15], v[12:13], v[12:13]
	v_mul_f32_e32 v20, 0x3fb8aa3b, v12
	v_mul_f32_e32 v21, 0x3fb8aa3b, v13
	v_exp_f32_e32 v20, v20
	v_exp_f32_e32 v21, v21
	v_fmaak_f32 v16, v14, v205, 0x3d2aaaab
	v_fmaak_f32 v19, v15, v205, 0x3d2aaaab
	v_fmaak_f32 v16, v16, v14, 0x3e2aaaab
	v_fmaak_f32 v19, v19, v15, 0x3e2aaaab
	v_fma_f32 v16, v16, v14, 0.5
	v_fma_f32 v19, v19, v15, 0.5
	v_fma_f32 v16, v16, v14, 1.0
	v_fma_f32 v19, v19, v15, 1.0
	v_mul_f32_e64 v17, v16, -v14
	v_mul_f32_e64 v12, v19, -v15
	v_fma_f32 v16, -v20, v20, 1.0
	v_cmp_lt_f32_e32 vcc, s6, v14
	v_fma_f32 v13, -v21, v21, 1.0
	s_nop 0
	v_cndmask_b32_e32 v16, v16, v17, vcc
	v_cmp_lt_f32_e32 vcc, s6, v15
	v_sqrt_f32_e32 v16, v16
	s_nop 1
	v_cndmask_b32_e32 v17, v13, v12, vcc
	v_sqrt_f32_e32 v17, v17
	s_nop 0
	v_pk_mul_f32 v[24:25], v[24:25], v[16:17]
	s_nop 0
	v_pk_mul_f32 v[24:25], v[28:29], v[24:25]
	v_fmamk_f32 v22, v22, 0xbfb8aa3b, v124
	v_fmamk_f32 v23, v23, 0xbfb8aa3b, v125
	v_fmamk_f32 v26, v26, 0xbfb8aa3b, v128
	v_fmamk_f32 v27, v27, 0xbfb8aa3b, v129
	v_exp_f32_e32 v22, v22
	v_exp_f32_e32 v23, v23
	v_exp_f32_e32 v26, v26
	v_exp_f32_e32 v27, v27
	v_add_f32_e32 v22, 1.0, v22
	v_add_f32_e32 v23, 1.0, v23
	v_add_f32_e32 v26, 1.0, v26
	v_add_f32_e32 v27, 1.0, v27
	v_rcp_f32_e32 v22, v22
	v_rcp_f32_e32 v23, v23
	v_rcp_f32_e32 v26, v26
	v_rcp_f32_e32 v27, v27
	v_pk_mul_f32 v[12:13], v[22:23], v[132:133]
	s_nop 0
	v_pk_add_f32 v[14:15], v[12:13], v[12:13]
	v_mul_f32_e32 v22, 0x3fb8aa3b, v12
	v_mul_f32_e32 v23, 0x3fb8aa3b, v13
	v_exp_f32_e32 v22, v22
	v_exp_f32_e32 v23, v23
	v_fmaak_f32 v16, v14, v205, 0x3d2aaaab
	v_fmaak_f32 v19, v15, v205, 0x3d2aaaab
	v_fmaak_f32 v16, v16, v14, 0x3e2aaaab
	v_fmaak_f32 v19, v19, v15, 0x3e2aaaab
	v_fma_f32 v16, v16, v14, 0.5
	v_fma_f32 v19, v19, v15, 0.5
	v_fma_f32 v16, v16, v14, 1.0
	v_fma_f32 v19, v19, v15, 1.0
	v_mul_f32_e64 v17, v16, -v14
	v_mul_f32_e64 v12, v19, -v15
	v_fma_f32 v16, -v22, v22, 1.0
	v_cmp_lt_f32_e32 vcc, s6, v14
	v_fma_f32 v13, -v23, v23, 1.0
	s_nop 0
	v_cndmask_b32_e32 v16, v16, v17, vcc
	v_cmp_lt_f32_e32 vcc, s6, v15
	v_sqrt_f32_e32 v16, v16
	s_nop 1
	v_cndmask_b32_e32 v17, v13, v12, vcc
	v_sqrt_f32_e32 v17, v17
	s_nop 0
	v_pk_mul_f32 v[26:27], v[26:27], v[16:17]
	s_nop 0
	v_pk_mul_f32 v[26:27], v[30:31], v[26:27]
	ds_write_b128 v204, v[20:23] offset:46592
	ds_write_b128 v204, v[24:27] offset:62976
	s_waitcnt lgkmcnt(0)
	s_barrier
	ds_read2st64_b32 v[12:13], v49 offset0:134 offset1:198
	ds_read2st64_b32 v[14:15], v82 offset0:134 offset1:198
	ds_read2st64_b32 v[16:17], v83 offset0:134 offset1:198
	s_waitcnt lgkmcnt(2)
	v_fmac_f32_e32 v13, 0, v12
	s_waitcnt lgkmcnt(1)
	v_mul_f32_e32 v18, v12, v14
	s_waitcnt lgkmcnt(0)
	v_mul_f32_e32 v20, v18, v16
	ds_read2st64_b32 v[18:19], v84 offset0:134 offset1:198
	v_fmac_f32_e32 v15, v14, v13
	v_fmac_f32_e32 v17, v16, v15
	v_lshlrev_b64 v[12:13], 2, v[50:51]
	v_lshl_add_u64 v[50:51], s[86:87], 0, v[12:13]
	s_waitcnt lgkmcnt(0)
	v_mul_f32_e32 v22, v20, v18
	ds_read2st64_b32 v[20:21], v85 offset0:134 offset1:198
	v_fmac_f32_e32 v19, v18, v17
	s_waitcnt lgkmcnt(0)
	v_mul_f32_e32 v24, v22, v20
	ds_read2st64_b32 v[22:23], v86 offset0:134 offset1:198
	v_fmac_f32_e32 v21, v20, v19
	s_waitcnt lgkmcnt(0)
	v_mul_f32_e32 v26, v24, v22
	ds_read2st64_b32 v[24:25], v87 offset0:134 offset1:198
	v_fmac_f32_e32 v23, v22, v21
	s_waitcnt lgkmcnt(0)
	v_mul_f32_e32 v28, v26, v24
	ds_read2st64_b32 v[26:27], v88 offset0:134 offset1:198
	v_fmac_f32_e32 v25, v24, v23
	s_waitcnt lgkmcnt(0)
	v_mul_f32_e32 v30, v28, v26
	ds_read2st64_b32 v[28:29], v89 offset0:134 offset1:198
	v_fmac_f32_e32 v27, v26, v25
	s_waitcnt lgkmcnt(0)
	v_mul_f32_e32 v32, v30, v28
	ds_read2st64_b32 v[30:31], v90 offset0:134 offset1:198
	v_fmac_f32_e32 v29, v28, v27
	s_waitcnt lgkmcnt(0)
	v_mul_f32_e32 v34, v32, v30
	ds_read2st64_b32 v[32:33], v91 offset0:134 offset1:198
	v_fmac_f32_e32 v31, v30, v29
	s_waitcnt lgkmcnt(0)
	v_mul_f32_e32 v52, v34, v32
	ds_read2st64_b32 v[34:35], v92 offset0:134 offset1:198
	v_fmac_f32_e32 v33, v32, v31
	s_waitcnt lgkmcnt(0)
	v_mul_f32_e32 v104, v52, v34
	ds_read2st64_b32 v[52:53], v93 offset0:134 offset1:198
	v_fmac_f32_e32 v35, v34, v33
	s_waitcnt lgkmcnt(0)
	v_mul_f32_e32 v106, v104, v52
	ds_read2st64_b32 v[104:105], v94 offset0:134 offset1:198
	v_fmac_f32_e32 v53, v52, v35
	s_waitcnt lgkmcnt(0)
	v_mul_f32_e32 v108, v106, v104
	ds_read2st64_b32 v[106:107], v95 offset0:134 offset1:198
	v_fmac_f32_e32 v105, v104, v53
	v_lshl_add_u64 v[52:53], s[88:89], 0, v[12:13]
	s_waitcnt lgkmcnt(0)
	v_mul_f32_e32 v110, v108, v106
	ds_read2st64_b32 v[108:109], v96 offset0:134 offset1:198
	v_fmac_f32_e32 v107, v106, v105
	s_waitcnt lgkmcnt(0)
	v_mul_f32_e32 v110, v110, v108
	v_fmac_f32_e32 v109, v108, v107
	ds_write_b32 v64, v110
	ds_write_b32 v65, v109 offset:1024
	s_waitcnt lgkmcnt(0)
	s_barrier
	s_and_saveexec_b64 s[42:43], s[40:41]
	s_cbranch_execz .LBB0_387
	ds_read2st64_b32 v[12:13], v64 offset1:1
	ds_read2st64_b32 v[14:15], v64 offset0:2 offset1:3
	s_waitcnt lgkmcnt(1)
	v_mul_f32_e32 v16, v12, v13
	s_waitcnt lgkmcnt(0)
	v_mul_f32_e32 v16, v16, v14
	v_mul_f32_e32 v18, v16, v15
	ds_read2st64_b32 v[16:17], v64 offset0:4 offset1:5
	s_waitcnt lgkmcnt(0)
	v_fma_f32 v12, 0, v12, v16
	v_fmac_f32_e32 v17, v13, v12
	ds_read2st64_b32 v[12:13], v64 offset0:6 offset1:7
	s_waitcnt lgkmcnt(0)
	v_fma_f32 v12, v14, v17, v12
	v_fmac_f32_e32 v13, v15, v12
	global_store_dword v[50:51], v18, off
	global_store_dword v[52:53], v13, off
; __device__ __forceinline__ float sigmoidf_(float x) { return __builtin_amdgcn_rcpf(1.0f + __expf(-x)); }
; template <bool FINAL>
; __device__ void phase_lru(const Params& p, int l, unsigned char* smem) {
;     ...
;     for (int d = 0; d < 2; ++d) {
;       {
;         bf16x8 uf[2];
;         uf[0] = *(const bf16x8*)(ub + (16 * w + l15) * 72 + g * 8);
;         uf[1] = *(const bf16x8*)(ub + (16 * w + l15) * 72 + 32 + g * 8);
;         const int t = 16 * w + l15;
; #pragma unroll
;         for (int et = 0; et < 4; ++et) {
;           f32x4 ar = {0.f, 0.f, 0.f, 0.f}, ai = {0.f, 0.f, 0.f, 0.f};
;           const u16* wr = p.WLRU + ((((size_t)(l * 2 + d) * 2 + 0) * 8 + nb) * 64 + et * 16 + l15) * 64 + g * 8;
;           const u16* wi = p.WLRU + ((((size_t)(l * 2 + d) * 2 + 1) * 8 + nb) * 64 + et * 16 + l15) * 64 + g * 8;
; #pragma unroll
;           for (int ks = 0; ks < 2; ++ks) {
;             ar = mfma16(*(const bf16x8*)(wr + ks * 32), uf[ks], ar);
;             ai = mfma16(*(const bf16x8*)(wi + ks * 32), uf[ks], ai);
;           }
;           const int e0 = et * 16 + 4 * g, ch0 = nb * 64 + e0;
;           const float4 ba4 = *(const float4*)(p.ba + (l * 2 + d) * 512 + ch0);
;           const float4 bx4 = *(const float4*)(p.bx + (l * 2 + d) * 512 + ch0);
;           const float4 sp4 = *(const float4*)(p.SP8 + (l * 2 + d) * 512 + ch0);
;           const float4 uu = *(const float4*)(u32 + t * 64 + e0);
;           const float* bap = (const float*)&ba4; const float* bxp = (const float*)&bx4;
;           const float* spp = (const float*)&sp4; const float* uup = (const float*)&uu;
;           f32x4 av, bv;
; #pragma unroll
;           for (int j = 0; j < 4; ++j) {
;             float r = sigmoidf_(ar[j] + bap[j]);
;             float ig = sigmoidf_(ai[j] + bxp[j]);
;             float la = spp[j] * r;
;             float av_ = __expf(la);
;             float t2 = 2.0f * la;
;             float ser = -t2 * (1.f + t2 * 0.5f * (1.f + t2 * (1.f / 3.f) * (1.f + t2 * 0.25f * (1.f + t2 * 0.2f))));
;             float om = (t2 > -0.25f) ? ser : (1.0f - av_ * av_);
;             av[j] = av_;
;             bv[j] = __builtin_amdgcn_sqrtf(om) * ig * uup[j];
;           }
;           *(f32x4*)(sa + t * 64 + e0) = av;
;           *(f32x4*)(sb + t * 64 + e0) = bv;
;         }
.LBB0_387:
	s_or_b64 exec, exec, s[42:43]
	v_lshl_add_u64 v[20:21], s[50:51], 0, v[144:145]
	v_lshl_add_u64 v[28:29], v[20:21], 0, v[54:55]
	s_barrier
	s_mov_b32 s5, 0x3e4ccccd
	ds_read_b128 v[12:15], v229 offset:25088
	ds_read_b128 v[16:19], v229 offset:25152
	ds_read_b128 v[28:31], v230 offset:8704
	s_waitcnt lgkmcnt(1)
	v_mfma_f32_16x16x32_bf16 v[20:23], v[232:235], v[12:15], 0
	v_mfma_f32_16x16x32_bf16 v[24:27], v[240:243], v[12:15], 0
	v_mfma_f32_16x16x32_bf16 v[20:23], v[236:239], v[16:19], v[20:23]
	v_mfma_f32_16x16x32_bf16 v[24:27], v[244:247], v[16:19], v[24:27]
	s_nop 7
	s_nop 3
	s_waitcnt lgkmcnt(0)
	v_fmamk_f32 v20, v20, 0xbfb8aa3b, v134
	v_fmamk_f32 v21, v21, 0xbfb8aa3b, v135
	v_fmamk_f32 v24, v24, 0xbfb8aa3b, v138
	v_fmamk_f32 v25, v25, 0xbfb8aa3b, v139
	v_exp_f32_e32 v20, v20
	v_exp_f32_e32 v21, v21
	v_exp_f32_e32 v24, v24
	v_exp_f32_e32 v25, v25
	v_add_f32_e32 v20, 1.0, v20
	v_add_f32_e32 v21, 1.0, v21
	v_add_f32_e32 v24, 1.0, v24
	v_add_f32_e32 v25, 1.0, v25
	v_rcp_f32_e32 v20, v20
	v_rcp_f32_e32 v21, v21
	v_rcp_f32_e32 v24, v24
	v_rcp_f32_e32 v25, v25
	v_pk_mul_f32 v[12:13], v[20:21], v[150:151]
	s_nop 0
	v_pk_add_f32 v[14:15], v[12:13], v[12:13]
	v_mul_f32_e32 v20, 0x3fb8aa3b, v12
	v_mul_f32_e32 v21, 0x3fb8aa3b, v13
	v_exp_f32_e32 v20, v20
	v_exp_f32_e32 v21, v21
	v_fmaak_f32 v16, v14, v205, 0x3d2aaaab
	v_fmaak_f32 v19, v15, v205, 0x3d2aaaab
	v_fmaak_f32 v16, v16, v14, 0x3e2aaaab
	v_fmaak_f32 v19, v19, v15, 0x3e2aaaab
	v_fma_f32 v16, v16, v14, 0.5
	v_fma_f32 v19, v19, v15, 0.5
	v_fma_f32 v16, v16, v14, 1.0
	v_fma_f32 v19, v19, v15, 1.0
	v_mul_f32_e64 v17, v16, -v14
	v_mul_f32_e64 v12, v19, -v15
	v_fma_f32 v16, -v20, v20, 1.0
	v_cmp_lt_f32_e32 vcc, s6, v14
	v_fma_f32 v13, -v21, v21, 1.0
	s_nop 0
	v_cndmask_b32_e32 v16, v16, v17, vcc
	v_cmp_lt_f32_e32 vcc, s6, v15
	v_sqrt_f32_e32 v16, v16
	s_nop 1
	v_cndmask_b32_e32 v17, v13, v12, vcc
	v_sqrt_f32_e32 v17, v17
	s_nop 0
	v_pk_mul_f32 v[24:25], v[24:25], v[16:17]
	s_nop 0
	v_pk_mul_f32 v[24:25], v[28:29], v[24:25]
	v_fmamk_f32 v22, v22, 0xbfb8aa3b, v136
	v_fmamk_f32 v23, v23, 0xbfb8aa3b, v137
	v_fmamk_f32 v26, v26, 0xbfb8aa3b, v140
	v_fmamk_f32 v27, v27, 0xbfb8aa3b, v141
	v_exp_f32_e32 v22, v22
	v_exp_f32_e32 v23, v23
	v_exp_f32_e32 v26, v26
	v_exp_f32_e32 v27, v27
	v_add_f32_e32 v22, 1.0, v22
	v_add_f32_e32 v23, 1.0, v23
	v_add_f32_e32 v26, 1.0, v26
	v_add_f32_e32 v27, 1.0, v27
	v_rcp_f32_e32 v22, v22
	v_rcp_f32_e32 v23, v23
	v_rcp_f32_e32 v26, v26
	v_rcp_f32_e32 v27, v27
	v_pk_mul_f32 v[12:13], v[22:23], v[152:153]
	s_nop 0
	v_pk_add_f32 v[14:15], v[12:13], v[12:13]
	v_mul_f32_e32 v22, 0x3fb8aa3b, v12
	v_mul_f32_e32 v23, 0x3fb8aa3b, v13
	v_exp_f32_e32 v22, v22
	v_exp_f32_e32 v23, v23
	v_fmaak_f32 v16, v14, v205, 0x3d2aaaab
	v_fmaak_f32 v19, v15, v205, 0x3d2aaaab
	v_fmaak_f32 v16, v16, v14, 0x3e2aaaab
	v_fmaak_f32 v19, v19, v15, 0x3e2aaaab
	v_fma_f32 v16, v16, v14, 0.5
	v_fma_f32 v19, v19, v15, 0.5
	v_fma_f32 v16, v16, v14, 1.0
	v_fma_f32 v19, v19, v15, 1.0
	v_mul_f32_e64 v17, v16, -v14
	v_mul_f32_e64 v12, v19, -v15
	v_fma_f32 v16, -v22, v22, 1.0
	v_cmp_lt_f32_e32 vcc, s6, v14
	v_fma_f32 v13, -v23, v23, 1.0
	s_nop 0
	v_cndmask_b32_e32 v16, v16, v17, vcc
	v_cmp_lt_f32_e32 vcc, s6, v15
	v_sqrt_f32_e32 v16, v16
	s_nop 1
	v_cndmask_b32_e32 v17, v13, v12, vcc
	v_sqrt_f32_e32 v17, v17
	s_nop 0
	v_pk_mul_f32 v[26:27], v[26:27], v[16:17]
	s_nop 0
	v_pk_mul_f32 v[26:27], v[30:31], v[26:27]
	ds_write_b128 v204, v[20:23] offset:34304
	ds_write_b128 v204, v[24:27] offset:50688
	ds_read_b128 v[12:15], v229 offset:27392
	ds_read_b128 v[16:19], v229 offset:27456
	ds_read_b128 v[28:31], v230 offset:12800
	s_waitcnt lgkmcnt(1)
	v_mfma_f32_16x16x32_bf16 v[20:23], v[232:235], v[12:15], 0
	v_mfma_f32_16x16x32_bf16 v[24:27], v[240:243], v[12:15], 0
	v_mfma_f32_16x16x32_bf16 v[20:23], v[236:239], v[16:19], v[20:23]
	v_mfma_f32_16x16x32_bf16 v[24:27], v[244:247], v[16:19], v[24:27]
	s_nop 7
	s_nop 3
	s_waitcnt lgkmcnt(0)
	v_fmamk_f32 v20, v20, 0xbfb8aa3b, v134
	v_fmamk_f32 v21, v21, 0xbfb8aa3b, v135
	v_fmamk_f32 v24, v24, 0xbfb8aa3b, v138
	v_fmamk_f32 v25, v25, 0xbfb8aa3b, v139
	v_exp_f32_e32 v20, v20
	v_exp_f32_e32 v21, v21
	v_exp_f32_e32 v24, v24
	v_exp_f32_e32 v25, v25
	v_add_f32_e32 v20, 1.0, v20
	v_add_f32_e32 v21, 1.0, v21
	v_add_f32_e32 v24, 1.0, v24
	v_add_f32_e32 v25, 1.0, v25
	v_rcp_f32_e32 v20, v20
	v_rcp_f32_e32 v21, v21
	v_rcp_f32_e32 v24, v24
	v_rcp_f32_e32 v25, v25
	v_pk_mul_f32 v[12:13], v[20:21], v[150:151]
	s_nop 0
	v_pk_add_f32 v[14:15], v[12:13], v[12:13]
	v_mul_f32_e32 v20, 0x3fb8aa3b, v12
	v_mul_f32_e32 v21, 0x3fb8aa3b, v13
	v_exp_f32_e32 v20, v20
	v_exp_f32_e32 v21, v21
	v_fmaak_f32 v16, v14, v205, 0x3d2aaaab
	v_fmaak_f32 v19, v15, v205, 0x3d2aaaab
	v_fmaak_f32 v16, v16, v14, 0x3e2aaaab
	v_fmaak_f32 v19, v19, v15, 0x3e2aaaab
	v_fma_f32 v16, v16, v14, 0.5
	v_fma_f32 v19, v19, v15, 0.5
	v_fma_f32 v16, v16, v14, 1.0
	v_fma_f32 v19, v19, v15, 1.0
	v_mul_f32_e64 v17, v16, -v14
	v_mul_f32_e64 v12, v19, -v15
	v_fma_f32 v16, -v20, v20, 1.0
	v_cmp_lt_f32_e32 vcc, s6, v14
	v_fma_f32 v13, -v21, v21, 1.0
	s_nop 0
	v_cndmask_b32_e32 v16, v16, v17, vcc
	v_cmp_lt_f32_e32 vcc, s6, v15
	v_sqrt_f32_e32 v16, v16
	s_nop 1
	v_cndmask_b32_e32 v17, v13, v12, vcc
	v_sqrt_f32_e32 v17, v17
	s_nop 0
	v_pk_mul_f32 v[24:25], v[24:25], v[16:17]
	s_nop 0
	v_pk_mul_f32 v[24:25], v[28:29], v[24:25]
	v_fmamk_f32 v22, v22, 0xbfb8aa3b, v136
	v_fmamk_f32 v23, v23, 0xbfb8aa3b, v137
	v_fmamk_f32 v26, v26, 0xbfb8aa3b, v140
	v_fmamk_f32 v27, v27, 0xbfb8aa3b, v141
	v_exp_f32_e32 v22, v22
	v_exp_f32_e32 v23, v23
	v_exp_f32_e32 v26, v26
	v_exp_f32_e32 v27, v27
	v_add_f32_e32 v22, 1.0, v22
	v_add_f32_e32 v23, 1.0, v23
	v_add_f32_e32 v26, 1.0, v26
	v_add_f32_e32 v27, 1.0, v27
	v_rcp_f32_e32 v22, v22
	v_rcp_f32_e32 v23, v23
	v_rcp_f32_e32 v26, v26
	v_rcp_f32_e32 v27, v27
	v_pk_mul_f32 v[12:13], v[22:23], v[152:153]
	s_nop 0
	v_pk_add_f32 v[14:15], v[12:13], v[12:13]
	v_mul_f32_e32 v22, 0x3fb8aa3b, v12
	v_mul_f32_e32 v23, 0x3fb8aa3b, v13
	v_exp_f32_e32 v22, v22
	v_exp_f32_e32 v23, v23
	v_fmaak_f32 v16, v14, v205, 0x3d2aaaab
	v_fmaak_f32 v19, v15, v205, 0x3d2aaaab
	v_fmaak_f32 v16, v16, v14, 0x3e2aaaab
	v_fmaak_f32 v19, v19, v15, 0x3e2aaaab
	v_fma_f32 v16, v16, v14, 0.5
	v_fma_f32 v19, v19, v15, 0.5
	v_fma_f32 v16, v16, v14, 1.0
	v_fma_f32 v19, v19, v15, 1.0
	v_mul_f32_e64 v17, v16, -v14
	v_mul_f32_e64 v12, v19, -v15
	v_fma_f32 v16, -v22, v22, 1.0
	v_cmp_lt_f32_e32 vcc, s6, v14
	v_fma_f32 v13, -v23, v23, 1.0
	s_nop 0
	v_cndmask_b32_e32 v16, v16, v17, vcc
	v_cmp_lt_f32_e32 vcc, s6, v15
	v_sqrt_f32_e32 v16, v16
	s_nop 1
	v_cndmask_b32_e32 v17, v13, v12, vcc
	v_sqrt_f32_e32 v17, v17
	s_nop 0
	v_pk_mul_f32 v[26:27], v[26:27], v[16:17]
	s_nop 0
	v_pk_mul_f32 v[26:27], v[30:31], v[26:27]
	ds_write_b128 v204, v[20:23] offset:38400
	ds_write_b128 v204, v[24:27] offset:54784
	ds_read_b128 v[12:15], v229 offset:29696
	ds_read_b128 v[16:19], v229 offset:29760
	ds_read_b128 v[28:31], v230 offset:16896
	s_waitcnt lgkmcnt(1)
; __device__ __forceinline__ float sigmoidf_(float x) { return __builtin_amdgcn_rcpf(1.0f + __expf(-x)); }
; template <bool FINAL>
; __device__ void phase_lru(const Params& p, int l, unsigned char* smem) {
;     ...
;           const int e0 = et * 16 + 4 * g, ch0 = nb * 64 + e0;
;           const float4 ba4 = *(const float4*)(p.ba + (l * 2 + d) * 512 + ch0);
;           const float4 bx4 = *(const float4*)(p.bx + (l * 2 + d) * 512 + ch0);
;           const float4 sp4 = *(const float4*)(p.SP8 + (l * 2 + d) * 512 + ch0);
;           const float4 uu = *(const float4*)(u32 + t * 64 + e0);
;           const float* bap = (const float*)&ba4; const float* bxp = (const float*)&bx4;
;           const float* spp = (const float*)&sp4; const float* uup = (const float*)&uu;
;           f32x4 av, bv;
; #pragma unroll
;           for (int j = 0; j < 4; ++j) {
;             float r = sigmoidf_(ar[j] + bap[j]);
;             float ig = sigmoidf_(ai[j] + bxp[j]);
;             float la = spp[j] * r;
;             float av_ = __expf(la);
;             float t2 = 2.0f * la;
;             float ser = -t2 * (1.f + t2 * 0.5f * (1.f + t2 * (1.f / 3.f) * (1.f + t2 * 0.25f * (1.f + t2 * 0.2f))));
;             float om = (t2 > -0.25f) ? ser : (1.0f - av_ * av_);
;             av[j] = av_;
;             bv[j] = __builtin_amdgcn_sqrtf(om) * ig * uup[j];
;           }
;           *(f32x4*)(sa + t * 64 + e0) = av;
;           *(f32x4*)(sb + t * 64 + e0) = bv;
;         }
;       }
;       __syncthreads();
;       {
;         float A = 1.f, B = 0.f;
;         if (d == 0) {
; #pragma unroll
;           for (int tt = 0; tt < 16; ++tt) { int t = qd * 16 + tt; float a = sa[t * 64 + e_], b = sb[t * 64 + e_]; B = a * B + b; A *= a; }
;         } else {
; #pragma unroll
;     ...
;         }
;         part[(0 * 4 + qd) * 64 + e_] = A;
;         part[(1 * 4 + qd) * 64 + e_] = B;
;       }
;       __syncthreads();
	v_mfma_f32_16x16x32_bf16 v[20:23], v[232:235], v[12:15], 0
	v_mfma_f32_16x16x32_bf16 v[24:27], v[240:243], v[12:15], 0
	v_mfma_f32_16x16x32_bf16 v[20:23], v[236:239], v[16:19], v[20:23]
	v_mfma_f32_16x16x32_bf16 v[24:27], v[244:247], v[16:19], v[24:27]
	s_nop 7
	s_nop 3
	s_waitcnt lgkmcnt(0)
	v_fmamk_f32 v20, v20, 0xbfb8aa3b, v134
	v_fmamk_f32 v21, v21, 0xbfb8aa3b, v135
	v_fmamk_f32 v24, v24, 0xbfb8aa3b, v138
	v_fmamk_f32 v25, v25, 0xbfb8aa3b, v139
	v_exp_f32_e32 v20, v20
	v_exp_f32_e32 v21, v21
	v_exp_f32_e32 v24, v24
	v_exp_f32_e32 v25, v25
	v_add_f32_e32 v20, 1.0, v20
	v_add_f32_e32 v21, 1.0, v21
	v_add_f32_e32 v24, 1.0, v24
	v_add_f32_e32 v25, 1.0, v25
	v_rcp_f32_e32 v20, v20
	v_rcp_f32_e32 v21, v21
	v_rcp_f32_e32 v24, v24
	v_rcp_f32_e32 v25, v25
	v_pk_mul_f32 v[12:13], v[20:21], v[150:151]
	s_nop 0
	v_pk_add_f32 v[14:15], v[12:13], v[12:13]
	v_mul_f32_e32 v20, 0x3fb8aa3b, v12
	v_mul_f32_e32 v21, 0x3fb8aa3b, v13
	v_exp_f32_e32 v20, v20
	v_exp_f32_e32 v21, v21
	v_fmaak_f32 v16, v14, v205, 0x3d2aaaab
	v_fmaak_f32 v19, v15, v205, 0x3d2aaaab
	v_fmaak_f32 v16, v16, v14, 0x3e2aaaab
	v_fmaak_f32 v19, v19, v15, 0x3e2aaaab
	v_fma_f32 v16, v16, v14, 0.5
	v_fma_f32 v19, v19, v15, 0.5
	v_fma_f32 v16, v16, v14, 1.0
	v_fma_f32 v19, v19, v15, 1.0
	v_mul_f32_e64 v17, v16, -v14
	v_mul_f32_e64 v12, v19, -v15
	v_fma_f32 v16, -v20, v20, 1.0
	v_cmp_lt_f32_e32 vcc, s6, v14
	v_fma_f32 v13, -v21, v21, 1.0
	s_nop 0
	v_cndmask_b32_e32 v16, v16, v17, vcc
	v_cmp_lt_f32_e32 vcc, s6, v15
	v_sqrt_f32_e32 v16, v16
	s_nop 1
	v_cndmask_b32_e32 v17, v13, v12, vcc
	v_sqrt_f32_e32 v17, v17
	s_nop 0
	v_pk_mul_f32 v[24:25], v[24:25], v[16:17]
	s_nop 0
	v_pk_mul_f32 v[24:25], v[28:29], v[24:25]
	v_fmamk_f32 v22, v22, 0xbfb8aa3b, v136
	v_fmamk_f32 v23, v23, 0xbfb8aa3b, v137
	v_fmamk_f32 v26, v26, 0xbfb8aa3b, v140
	v_fmamk_f32 v27, v27, 0xbfb8aa3b, v141
	v_exp_f32_e32 v22, v22
	v_exp_f32_e32 v23, v23
	v_exp_f32_e32 v26, v26
	v_exp_f32_e32 v27, v27
	v_add_f32_e32 v22, 1.0, v22
	v_add_f32_e32 v23, 1.0, v23
	v_add_f32_e32 v26, 1.0, v26
	v_add_f32_e32 v27, 1.0, v27
	v_rcp_f32_e32 v22, v22
	v_rcp_f32_e32 v23, v23
	v_rcp_f32_e32 v26, v26
	v_rcp_f32_e32 v27, v27
	v_pk_mul_f32 v[12:13], v[22:23], v[152:153]
	s_nop 0
	v_pk_add_f32 v[14:15], v[12:13], v[12:13]
	v_mul_f32_e32 v22, 0x3fb8aa3b, v12
	v_mul_f32_e32 v23, 0x3fb8aa3b, v13
	v_exp_f32_e32 v22, v22
	v_exp_f32_e32 v23, v23
	v_fmaak_f32 v16, v14, v205, 0x3d2aaaab
	v_fmaak_f32 v19, v15, v205, 0x3d2aaaab
	v_fmaak_f32 v16, v16, v14, 0x3e2aaaab
	v_fmaak_f32 v19, v19, v15, 0x3e2aaaab
	v_fma_f32 v16, v16, v14, 0.5
	v_fma_f32 v19, v19, v15, 0.5
	v_fma_f32 v16, v16, v14, 1.0
	v_fma_f32 v19, v19, v15, 1.0
	v_mul_f32_e64 v17, v16, -v14
	v_mul_f32_e64 v12, v19, -v15
	v_fma_f32 v16, -v22, v22, 1.0
	v_cmp_lt_f32_e32 vcc, s6, v14
	v_fma_f32 v13, -v23, v23, 1.0
	s_nop 0
	v_cndmask_b32_e32 v16, v16, v17, vcc
	v_cmp_lt_f32_e32 vcc, s6, v15
	v_sqrt_f32_e32 v16, v16
	s_nop 1
	v_cndmask_b32_e32 v17, v13, v12, vcc
	v_sqrt_f32_e32 v17, v17
	s_nop 0
	v_pk_mul_f32 v[26:27], v[26:27], v[16:17]
	s_nop 0
	v_pk_mul_f32 v[26:27], v[30:31], v[26:27]
	ds_write_b128 v204, v[20:23] offset:42496
	ds_write_b128 v204, v[24:27] offset:58880
	ds_read_b128 v[12:15], v229 offset:32000
	ds_read_b128 v[16:19], v229 offset:32064
	ds_read_b128 v[28:31], v230 offset:20992
	s_waitcnt lgkmcnt(1)
	v_mfma_f32_16x16x32_bf16 v[20:23], v[232:235], v[12:15], 0
	v_mfma_f32_16x16x32_bf16 v[24:27], v[240:243], v[12:15], 0
	v_mfma_f32_16x16x32_bf16 v[20:23], v[236:239], v[16:19], v[20:23]
	v_mfma_f32_16x16x32_bf16 v[24:27], v[244:247], v[16:19], v[24:27]
	s_nop 7
	s_nop 3
	s_waitcnt lgkmcnt(0)
	v_fmamk_f32 v20, v20, 0xbfb8aa3b, v134
	v_fmamk_f32 v21, v21, 0xbfb8aa3b, v135
	v_fmamk_f32 v24, v24, 0xbfb8aa3b, v138
	v_fmamk_f32 v25, v25, 0xbfb8aa3b, v139
	v_exp_f32_e32 v20, v20
	v_exp_f32_e32 v21, v21
	v_exp_f32_e32 v24, v24
	v_exp_f32_e32 v25, v25
	v_add_f32_e32 v20, 1.0, v20
	v_add_f32_e32 v21, 1.0, v21
	v_add_f32_e32 v24, 1.0, v24
	v_add_f32_e32 v25, 1.0, v25
	v_rcp_f32_e32 v20, v20
	v_rcp_f32_e32 v21, v21
	v_rcp_f32_e32 v24, v24
	v_rcp_f32_e32 v25, v25
	v_pk_mul_f32 v[12:13], v[20:21], v[150:151]
	s_nop 0
	v_pk_add_f32 v[14:15], v[12:13], v[12:13]
	v_mul_f32_e32 v20, 0x3fb8aa3b, v12
	v_mul_f32_e32 v21, 0x3fb8aa3b, v13
	v_exp_f32_e32 v20, v20
	v_exp_f32_e32 v21, v21
	v_fmaak_f32 v16, v14, v205, 0x3d2aaaab
	v_fmaak_f32 v19, v15, v205, 0x3d2aaaab
	v_fmaak_f32 v16, v16, v14, 0x3e2aaaab
	v_fmaak_f32 v19, v19, v15, 0x3e2aaaab
	v_fma_f32 v16, v16, v14, 0.5
	v_fma_f32 v19, v19, v15, 0.5
	v_fma_f32 v16, v16, v14, 1.0
	v_fma_f32 v19, v19, v15, 1.0
	v_mul_f32_e64 v17, v16, -v14
	v_mul_f32_e64 v12, v19, -v15
	v_fma_f32 v16, -v20, v20, 1.0
	v_cmp_lt_f32_e32 vcc, s6, v14
	v_fma_f32 v13, -v21, v21, 1.0
	s_nop 0
	v_cndmask_b32_e32 v16, v16, v17, vcc
	v_cmp_lt_f32_e32 vcc, s6, v15
	v_sqrt_f32_e32 v16, v16
	s_nop 1
	v_cndmask_b32_e32 v17, v13, v12, vcc
	v_sqrt_f32_e32 v17, v17
	s_nop 0
	v_pk_mul_f32 v[24:25], v[24:25], v[16:17]
	s_nop 0
	v_pk_mul_f32 v[24:25], v[28:29], v[24:25]
	v_fmamk_f32 v22, v22, 0xbfb8aa3b, v136
	v_fmamk_f32 v23, v23, 0xbfb8aa3b, v137
	v_fmamk_f32 v26, v26, 0xbfb8aa3b, v140
	v_fmamk_f32 v27, v27, 0xbfb8aa3b, v141
	v_exp_f32_e32 v22, v22
	v_exp_f32_e32 v23, v23
	v_exp_f32_e32 v26, v26
	v_exp_f32_e32 v27, v27
	v_add_f32_e32 v22, 1.0, v22
	v_add_f32_e32 v23, 1.0, v23
	v_add_f32_e32 v26, 1.0, v26
	v_add_f32_e32 v27, 1.0, v27
	v_rcp_f32_e32 v22, v22
	v_rcp_f32_e32 v23, v23
	v_rcp_f32_e32 v26, v26
	v_rcp_f32_e32 v27, v27
	v_pk_mul_f32 v[12:13], v[22:23], v[152:153]
	s_nop 0
	v_pk_add_f32 v[14:15], v[12:13], v[12:13]
	v_mul_f32_e32 v22, 0x3fb8aa3b, v12
	v_mul_f32_e32 v23, 0x3fb8aa3b, v13
	v_exp_f32_e32 v22, v22
	v_exp_f32_e32 v23, v23
	v_fmaak_f32 v16, v14, v205, 0x3d2aaaab
	v_fmaak_f32 v19, v15, v205, 0x3d2aaaab
	v_fmaak_f32 v16, v16, v14, 0x3e2aaaab
	v_fmaak_f32 v19, v19, v15, 0x3e2aaaab
	v_fma_f32 v16, v16, v14, 0.5
	v_fma_f32 v19, v19, v15, 0.5
	v_fma_f32 v16, v16, v14, 1.0
	v_fma_f32 v19, v19, v15, 1.0
	v_mul_f32_e64 v17, v16, -v14
	v_mul_f32_e64 v12, v19, -v15
	v_fma_f32 v16, -v22, v22, 1.0
	v_cmp_lt_f32_e32 vcc, s6, v14
	v_fma_f32 v13, -v23, v23, 1.0
	s_nop 0
	v_cndmask_b32_e32 v16, v16, v17, vcc
	v_cmp_lt_f32_e32 vcc, s6, v15
	v_sqrt_f32_e32 v16, v16
	s_nop 1
	v_cndmask_b32_e32 v17, v13, v12, vcc
	v_sqrt_f32_e32 v17, v17
	s_nop 0
	v_pk_mul_f32 v[26:27], v[26:27], v[16:17]
	s_nop 0
	v_pk_mul_f32 v[26:27], v[30:31], v[26:27]
	ds_write_b128 v204, v[20:23] offset:46592
	ds_write_b128 v204, v[24:27] offset:62976
	s_waitcnt lgkmcnt(0)
	s_barrier
; template <bool FINAL>
; __device__ void phase_lru(const Params& p, int l, unsigned char* smem) {
;     ...
;       {
;         float A = 1.f, B = 0.f;
;         if (d == 0) {
; #pragma unroll
;           for (int tt = 0; tt < 16; ++tt) { int t = qd * 16 + tt; float a = sa[t * 64 + e_], b = sb[t * 64 + e_]; B = a * B + b; A *= a; }
;         } else {
; #pragma unroll
;     ...
;         }
;         part[(0 * 4 + qd) * 64 + e_] = A;
;         part[(1 * 4 + qd) * 64 + e_] = B;
;       }
;       __syncthreads();
;       if (!FINAL) {
;         if (qd == 0) {
;           float A = 1.f, B = 0.f;
;           if (d == 0) {
; #pragma unroll
;             for (int q = 0; q < 4; ++q) { float aq = part[q * 64 + e_], bq = part[(4 + q) * 64 + e_]; B = aq * B + bq; A *= aq; }
;           } else {
; #pragma unroll
;             for (int q = 3; q >= 0; --q) { float aq = part[q * 64 + e_], bq = part[(4 + q) * 64 + e_]; B = aq * B + bq; A *= aq; }
;           }
;           const size_t cidx = ((size_t)ci * 2 + d) * 512 + nb * 64 + e_;
;           p.CA[cidx] = A; p.CB[cidx] = B;
;         }
	ds_read2st64_b32 v[12:13], v96 offset0:134 offset1:198
	ds_read2st64_b32 v[14:15], v95 offset0:134 offset1:198
	ds_read2st64_b32 v[16:17], v94 offset0:134 offset1:198
	ds_read2st64_b32 v[104:105], v83 offset0:134 offset1:198
	ds_read2st64_b32 v[106:107], v82 offset0:134 offset1:198
	s_waitcnt lgkmcnt(4)
	v_fmac_f32_e32 v13, 0, v12
	s_waitcnt lgkmcnt(3)
	v_mul_f32_e32 v18, v12, v14
	s_waitcnt lgkmcnt(2)
	v_mul_f32_e32 v20, v18, v16
	ds_read2st64_b32 v[18:19], v93 offset0:134 offset1:198
	v_fmac_f32_e32 v15, v14, v13
	v_fmac_f32_e32 v17, v16, v15
	ds_read2st64_b32 v[108:109], v49 offset0:134 offset1:198
	s_waitcnt lgkmcnt(1)
	v_mul_f32_e32 v22, v20, v18
	ds_read2st64_b32 v[20:21], v92 offset0:134 offset1:198
	v_fmac_f32_e32 v19, v18, v17
	s_waitcnt lgkmcnt(0)
	v_mul_f32_e32 v24, v22, v20
	ds_read2st64_b32 v[22:23], v91 offset0:134 offset1:198
	v_fmac_f32_e32 v21, v20, v19
	s_waitcnt lgkmcnt(0)
	v_mul_f32_e32 v26, v24, v22
	ds_read2st64_b32 v[24:25], v90 offset0:134 offset1:198
	v_fmac_f32_e32 v23, v22, v21
	s_waitcnt lgkmcnt(0)
	v_mul_f32_e32 v28, v26, v24
	ds_read2st64_b32 v[26:27], v89 offset0:134 offset1:198
	v_fmac_f32_e32 v25, v24, v23
	s_waitcnt lgkmcnt(0)
	v_mul_f32_e32 v30, v28, v26
	ds_read2st64_b32 v[28:29], v88 offset0:134 offset1:198
	v_fmac_f32_e32 v27, v26, v25
	s_waitcnt lgkmcnt(0)
	v_mul_f32_e32 v32, v30, v28
	ds_read2st64_b32 v[30:31], v87 offset0:134 offset1:198
	v_fmac_f32_e32 v29, v28, v27
	s_waitcnt lgkmcnt(0)
	v_mul_f32_e32 v34, v32, v30
	ds_read2st64_b32 v[32:33], v86 offset0:134 offset1:198
	v_fmac_f32_e32 v31, v30, v29
	s_waitcnt lgkmcnt(0)
	v_mul_f32_e32 v54, v34, v32
	ds_read2st64_b32 v[34:35], v85 offset0:134 offset1:198
	v_fmac_f32_e32 v33, v32, v31
	s_waitcnt lgkmcnt(0)
	v_mul_f32_e32 v56, v54, v34
	ds_read2st64_b32 v[54:55], v84 offset0:134 offset1:198
	v_fmac_f32_e32 v35, v34, v33
	s_waitcnt lgkmcnt(0)
	v_mul_f32_e32 v56, v56, v54
	v_mul_f32_e32 v56, v56, v104
	v_fmac_f32_e32 v55, v54, v35
	v_mul_f32_e32 v56, v56, v106
	v_fmac_f32_e32 v105, v104, v55
	v_mul_f32_e32 v56, v56, v108
	v_fmac_f32_e32 v107, v106, v105
	v_fmac_f32_e32 v109, v108, v107
	ds_write_b32 v64, v56
	ds_write_b32 v65, v109 offset:1024
	s_waitcnt lgkmcnt(0)
	s_barrier
	s_and_saveexec_b64 s[42:43], s[40:41]
	s_cbranch_execz .LBB0_374
	ds_read2st64_b32 v[12:13], v64 offset0:2 offset1:3
	ds_read2st64_b32 v[14:15], v64 offset1:1
	ds_read_b32 v17, v97
	s_waitcnt lgkmcnt(2)
	v_mul_f32_e32 v16, v13, v12
	s_waitcnt lgkmcnt(1)
	v_mul_f32_e32 v16, v16, v15
	s_waitcnt lgkmcnt(0)
	v_fmac_f32_e32 v17, 0, v13
	ds_read_b32 v13, v98
	v_mul_f32_e32 v16, v16, v14
	s_waitcnt lgkmcnt(0)
	v_fmac_f32_e32 v13, v12, v17
	ds_read_b32 v12, v99
	s_waitcnt lgkmcnt(0)
	v_fmac_f32_e32 v12, v15, v13
	ds_read_b32 v13, v100
	s_waitcnt lgkmcnt(0)
	v_fmac_f32_e32 v13, v14, v12
	global_store_dword v[50:51], v16, off offset:2048
	global_store_dword v[52:53], v13, off offset:2048
	s_branch .LBB0_374
